# GLA pass A/B: accurate-logf range handling (denormal pre-scale, inf test) on a value in [1,2] replaced by s_nop / moves - bit-identical, fewer VALU ops
# speedup vs baseline: 1.0046x; 1.0029x over previous
.LBB0_1113:
	v_add_u32_e32 v127, s37, v103
	v_add_u32_e32 v32, 0x1ff, v127
	v_add_u32_e32 v146, s37, v104
	v_cndmask_b32_e32 v32, v32, v146, vcc
	v_ashrrev_i32_e32 v33, 31, v32
	v_lshl_add_u64 v[52:53], v[32:33], 0, s[30:31]
	v_add_u32_e32 v32, 0x1fe, v127
	v_add_u32_e32 v33, 1, v146
	v_cndmask_b32_e32 v32, v32, v33, vcc
	v_ashrrev_i32_e32 v33, 31, v32
	v_lshl_add_u64 v[128:129], v[32:33], 0, s[30:31]
	v_add_u32_e32 v32, 0x1fd, v127
	v_add_u32_e32 v33, 2, v146
	v_add_u32_e32 v34, 0x1fc, v127
	v_add_u32_e32 v35, 3, v146
	v_cndmask_b32_e32 v32, v32, v33, vcc
	v_cndmask_b32_e32 v34, v34, v35, vcc
	v_ashrrev_i32_e32 v33, 31, v32
	v_ashrrev_i32_e32 v35, 31, v34
	v_mad_u64_u32 v[50:51], s[0:1], v52, s62, v[48:49]
	v_lshl_add_u64 v[32:33], v[32:33], 0, s[30:31]
	v_lshl_add_u64 v[34:35], v[34:35], 0, s[30:31]
	v_mad_i32_i24 v51, v53, s62, v51
	v_mad_u64_u32 v[54:55], s[0:1], v128, s62, v[48:49]
	v_mad_u64_u32 v[56:57], s[0:1], v32, s62, v[48:49]
	v_mad_u64_u32 v[58:59], s[0:1], v34, s62, v[48:49]
	v_mad_i32_i24 v55, v129, s62, v55
	v_mad_i32_i24 v57, v33, s62, v57
	v_mad_i32_i24 v59, v35, s62, v59
	global_load_ushort v108, v[50:51], off offset:1024
	global_load_ushort v111, v[50:51], off offset:2048
	global_load_ushort v106, v[54:55], off offset:1024
	global_load_ushort v112, v[54:55], off offset:2048
	global_load_ushort v110, v[56:57], off offset:1024
	global_load_ushort v105, v[56:57], off offset:2048
	global_load_ushort v109, v[58:59], off offset:1024
	global_load_ushort v107, v[58:59], off offset:2048
	v_add_u32_e32 v50, 0x1fb, v127
	v_add_u32_e32 v51, 4, v146
	v_cndmask_b32_e32 v50, v50, v51, vcc
	v_add_u32_e32 v54, 0x1fa, v127
	v_add_u32_e32 v55, 5, v146
	v_add_u32_e32 v56, 0x1f9, v127
	v_add_u32_e32 v57, 6, v146
	v_add_u32_e32 v58, 0x1f8, v127
	v_add_u32_e32 v59, 7, v146
	v_ashrrev_i32_e32 v51, 31, v50
	v_cndmask_b32_e32 v54, v54, v55, vcc
	v_cndmask_b32_e32 v56, v56, v57, vcc
	v_cndmask_b32_e32 v58, v58, v59, vcc
	v_lshl_add_u64 v[74:75], v[50:51], 0, s[30:31]
	v_ashrrev_i32_e32 v55, 31, v54
	v_ashrrev_i32_e32 v57, 31, v56
	v_ashrrev_i32_e32 v59, 31, v58
	v_mad_u64_u32 v[50:51], s[0:1], v74, s62, v[48:49]
	v_lshl_add_u64 v[72:73], v[54:55], 0, s[30:31]
	v_lshl_add_u64 v[68:69], v[56:57], 0, s[30:31]
	v_lshl_add_u64 v[70:71], v[58:59], 0, s[30:31]
	v_mad_i32_i24 v51, v75, s62, v51
	v_mad_u64_u32 v[54:55], s[0:1], v72, s62, v[48:49]
	v_mad_u64_u32 v[56:57], s[0:1], v68, s62, v[48:49]
	v_mad_u64_u32 v[58:59], s[0:1], v70, s62, v[48:49]
	v_mad_i32_i24 v55, v73, s62, v55
	v_mad_i32_i24 v57, v69, s62, v57
	v_mad_i32_i24 v59, v71, s62, v59
	global_load_ushort v116, v[50:51], off offset:1024
	global_load_ushort v119, v[50:51], off offset:2048
	global_load_ushort v114, v[54:55], off offset:1024
	global_load_ushort v120, v[54:55], off offset:2048
	global_load_ushort v118, v[56:57], off offset:1024
	global_load_ushort v113, v[56:57], off offset:2048
	global_load_ushort v117, v[58:59], off offset:1024
	global_load_ushort v115, v[58:59], off offset:2048
	v_add_u32_e32 v50, 0x1f7, v127
	v_add_u32_e32 v51, 8, v146
	v_cndmask_b32_e32 v50, v50, v51, vcc
	v_ashrrev_i32_e32 v51, 31, v50
	v_lshl_add_u64 v[64:65], v[50:51], 0, s[30:31]
	v_add_u32_e32 v50, 0x1f6, v127
	v_add_u32_e32 v51, 9, v146
	v_cndmask_b32_e32 v50, v50, v51, vcc
	v_ashrrev_i32_e32 v51, 31, v50
	v_lshl_add_u64 v[62:63], v[50:51], 0, s[30:31]
	v_add_u32_e32 v50, 0x1f5, v127
	v_add_u32_e32 v51, 10, v146
	v_cndmask_b32_e32 v50, v50, v51, vcc
	v_ashrrev_i32_e32 v51, 31, v50
	v_lshl_add_u64 v[60:61], v[50:51], 0, s[30:31]
	v_add_u32_e32 v50, 0x1f4, v127
	v_add_u32_e32 v51, 11, v146
	v_cndmask_b32_e32 v66, v50, v51, vcc
	v_mov_b64_e32 v[50:51], s[38:39]
	v_mad_u64_u32 v[54:55], s[0:1], v64, s62, v[48:49]
	v_mad_u64_u32 v[56:57], s[0:1], v62, s62, v[48:49]
	v_mad_u64_u32 v[58:59], s[0:1], v60, s62, v[48:49]
	v_mad_u64_u32 v[132:133], s[0:1], v52, s62, v[50:51]
	v_mad_i32_i24 v133, v53, s62, v133
	v_add_co_u32_e64 v52, s[0:1], s44, v132
	v_ashrrev_i32_e32 v67, 31, v66
	s_nop 0
	v_addc_co_u32_e64 v53, s[0:1], 0, v133, s[0:1]
	global_load_dwordx4 v[138:141], v[52:53], off offset:1536
	v_lshl_add_u64 v[66:67], v[66:67], 0, s[30:31]
	v_mad_u64_u32 v[52:53], s[0:1], v66, s62, v[48:49]
	v_mad_i32_i24 v55, v65, s62, v55
	v_mad_i32_i24 v53, v67, s62, v53
	v_mad_i32_i24 v57, v63, s62, v57
	v_mad_i32_i24 v59, v61, s62, v59
	global_load_ushort v124, v[54:55], off offset:1024
	global_load_ushort v130, v[54:55], off offset:2048
	global_load_ushort v123, v[56:57], off offset:1024
	global_load_ushort v131, v[56:57], off offset:2048
	global_load_ushort v126, v[58:59], off offset:1024
	global_load_ushort v121, v[58:59], off offset:2048
	global_load_ushort v125, v[52:53], off offset:1024
	global_load_ushort v122, v[52:53], off offset:2048
	v_lshl_add_u64 v[52:53], v[132:133], 0, s[34:35]
	global_load_dwordx4 v[142:145], v[52:53], off offset:16
	v_add_u32_e32 v54, 0x1f3, v127
	v_add_u32_e32 v55, 12, v146
	v_cndmask_b32_e32 v52, v54, v55, vcc
	v_ashrrev_i32_e32 v53, 31, v52
	v_lshl_add_u64 v[58:59], v[52:53], 0, s[30:31]
	v_add_u32_e32 v52, 0x1f2, v127
	v_add_u32_e32 v53, 13, v146
	v_cndmask_b32_e32 v52, v52, v53, vcc
	v_ashrrev_i32_e32 v53, 31, v52
	v_lshl_add_u64 v[56:57], v[52:53], 0, s[30:31]
	v_add_u32_e32 v52, 0x1f1, v127
	v_add_u32_e32 v53, 14, v146
	v_cndmask_b32_e32 v52, v52, v53, vcc
	v_ashrrev_i32_e32 v53, 31, v52
	v_lshl_add_u64 v[54:55], v[52:53], 0, s[30:31]
	v_mad_u64_u32 v[134:135], s[0:1], v58, s62, v[48:49]
	v_mad_u64_u32 v[136:137], s[0:1], v56, s62, v[48:49]
	v_mad_u64_u32 v[150:151], s[0:1], v54, s62, v[48:49]
	v_mad_u64_u32 v[152:153], s[0:1], v128, s62, v[50:51]
	v_mad_i32_i24 v153, v129, s62, v153
	v_add_co_u32_e64 v128, s[0:1], s44, v152
	v_add_u32_e32 v53, 15, v146
	s_nop 0
	v_addc_co_u32_e64 v129, s[0:1], 0, v153, s[0:1]
	global_load_dwordx4 v[146:149], v[128:129], off offset:1536
	v_add_u32_e32 v52, 0x1f0, v127
	v_cndmask_b32_e32 v52, v52, v53, vcc
	v_ashrrev_i32_e32 v53, 31, v52
	v_lshl_add_u64 v[52:53], v[52:53], 0, s[30:31]
	v_mad_i32_i24 v135, v59, s62, v135
	v_mad_i32_i24 v151, v55, s62, v151
	v_mad_u64_u32 v[154:155], s[0:1], v52, s62, v[48:49]
	v_mad_i32_i24 v137, v57, s62, v137
	v_mad_i32_i24 v155, v53, s62, v155
	global_load_ushort v132, v[134:135], off offset:1024
	s_nop 0
	global_load_ushort v135, v[134:135], off offset:2048
	s_nop 0
	global_load_ushort v129, v[136:137], off offset:1024
	s_nop 0
	global_load_ushort v136, v[136:137], off offset:2048
	s_nop 0
	global_load_ushort v134, v[150:151], off offset:1024
	global_load_ushort v127, v[150:151], off offset:2048
	global_load_ushort v133, v[154:155], off offset:1024
	global_load_ushort v128, v[154:155], off offset:2048
	v_lshl_add_u64 v[150:151], v[152:153], 0, s[34:35]
	global_load_dwordx4 v[150:153], v[150:151], off offset:16
	v_mad_u64_u32 v[154:155], s[0:1], v32, s62, v[50:51]
	v_mad_i32_i24 v155, v33, s62, v155
	v_lshl_add_u64 v[32:33], v[154:155], 0, s[34:35]
	v_add_co_u32_e64 v154, s[0:1], s44, v154
	s_waitcnt vmcnt(0)
	v_lshlrev_b32_e32 v137, 16, v138
	v_addc_co_u32_e64 v155, s[0:1], 0, v155, s[0:1]
	global_load_dwordx4 v[154:157], v[154:155], off offset:1536
	s_nop 0
	global_load_dwordx4 v[158:161], v[32:33], off offset:16
	v_and_b32_e32 v138, 0xffff0000, v138
	s_waitcnt lgkmcnt(0)
	v_mul_f32_e32 v138, v88, v138
	v_fmac_f32_e32 v138, v87, v137
	v_lshlrev_b32_e32 v137, 16, v139
	v_fmac_f32_e32 v138, v89, v137
	v_and_b32_e32 v137, 0xffff0000, v139
	v_fmac_f32_e32 v138, v90, v137
	v_lshlrev_b32_e32 v137, 16, v140
	v_fmac_f32_e32 v138, v91, v137
	v_and_b32_e32 v137, 0xffff0000, v140
	v_fmac_f32_e32 v138, v92, v137
	v_lshlrev_b32_e32 v137, 16, v141
	v_mad_u64_u32 v[32:33], s[0:1], v34, s62, v[50:51]
	v_fmac_f32_e32 v138, v93, v137
	v_and_b32_e32 v137, 0xffff0000, v141
	v_mad_i32_i24 v33, v35, s62, v33
	v_fmac_f32_e32 v138, v94, v137
	v_and_b32_e32 v139, 0xffff0000, v142
	v_lshl_add_u64 v[34:35], v[32:33], 0, s[34:35]
	v_add_f32_e32 v137, v86, v138
	v_lshlrev_b32_e32 v138, 16, v142
	v_mul_f32_e32 v139, v96, v139
	v_add_co_u32_e64 v32, s[0:1], s44, v32
	v_fmac_f32_e32 v139, v95, v138
	v_lshlrev_b32_e32 v138, 16, v143
	v_addc_co_u32_e64 v33, s[0:1], 0, v33, s[0:1]
	v_fmac_f32_e32 v139, v97, v138
	v_and_b32_e32 v138, 0xffff0000, v143
	global_load_dwordx4 v[140:143], v[32:33], off offset:1536
	s_nop 0
	global_load_dwordx4 v[32:35], v[34:35], off offset:16
	v_fmac_f32_e32 v139, v98, v138
	v_lshlrev_b32_e32 v138, 16, v144
	v_fmac_f32_e32 v139, v99, v138
	v_and_b32_e32 v138, 0xffff0000, v144
	v_fmac_f32_e32 v139, v100, v138
	v_lshlrev_b32_e32 v138, 16, v145
	v_fmac_f32_e32 v139, v101, v138
	v_and_b32_e32 v138, 0xffff0000, v145
	v_and_b32_e32 v145, 0xffff0000, v146
	v_lshlrev_b32_e32 v144, 16, v146
	v_mul_f32_e32 v145, v88, v145
	v_fmac_f32_e32 v145, v87, v144
	v_lshlrev_b32_e32 v144, 16, v147
	v_fmac_f32_e32 v139, v102, v138
	v_fmac_f32_e32 v145, v89, v144
	v_and_b32_e32 v144, 0xffff0000, v147
	v_add_f32_e32 v137, v137, v139
	v_fmac_f32_e32 v145, v90, v144
	v_lshlrev_b32_e32 v144, 16, v148
	v_mul_f32_e64 v138, |v137|, s70
	v_fmac_f32_e32 v145, v91, v144
	v_and_b32_e32 v144, 0xffff0000, v148
	v_exp_f32_e32 v138, v138
	v_fmac_f32_e32 v145, v92, v144
	v_lshlrev_b32_e32 v144, 16, v149
	v_fmac_f32_e32 v145, v93, v144
	v_and_b32_e32 v144, 0xffff0000, v149
	v_fmac_f32_e32 v145, v94, v144
	v_and_b32_e32 v146, 0xffff0000, v150
	v_add_f32_e32 v144, v86, v145
	v_lshlrev_b32_e32 v145, 16, v150
	v_mul_f32_e32 v146, v96, v146
	v_add_f32_e32 v138, 1.0, v138
	v_fmac_f32_e32 v146, v95, v145
	v_lshlrev_b32_e32 v145, 16, v151
	s_nop 0
	v_fmac_f32_e32 v146, v97, v145
	v_and_b32_e32 v145, 0xffff0000, v151
	s_nop 0
	v_fmac_f32_e32 v146, v98, v145
	v_lshlrev_b32_e32 v145, 16, v152
	s_nop 0
	v_fmac_f32_e32 v146, v99, v145
	v_and_b32_e32 v145, 0xffff0000, v152
	v_log_f32_e32 v138, v138
	v_fmac_f32_e32 v146, v100, v145
	v_lshlrev_b32_e32 v145, 16, v153
	v_fmac_f32_e32 v146, v101, v145
	v_and_b32_e32 v145, 0xffff0000, v153
	v_fmac_f32_e32 v146, v102, v145
	v_add_f32_e32 v144, v144, v146
	v_mul_f32_e32 v139, 0x3f317217, v138
	v_mul_f32_e64 v145, |v144|, s70
	v_fma_f32 v139, v138, s72, -v139
	v_exp_f32_e32 v145, v145
	v_fmac_f32_e32 v139, 0x3377d1cf, v138
	v_fmac_f32_e32 v139, 0x3f317217, v138
	s_nop 0
	s_waitcnt vmcnt(3)
	v_and_b32_e32 v146, 0xffff0000, v154
	v_mul_f32_e32 v146, v88, v146
	v_mov_b32_e32 v138, v139
	s_nop 0
	s_nop 0
	v_add_f32_e32 v139, 1.0, v145
	s_nop 0
	s_waitcnt vmcnt(2)
	v_and_b32_e32 v147, 0xffff0000, v158
	v_mul_f32_e32 v147, v96, v147
	s_nop 0
	s_nop 0
	v_lshlrev_b32_e32 v145, 16, v154
	v_fmac_f32_e32 v146, v87, v145
	v_lshlrev_b32_e32 v145, 16, v155
	v_fmac_f32_e32 v146, v89, v145
	v_and_b32_e32 v145, 0xffff0000, v155
	v_fmac_f32_e32 v146, v90, v145
	v_lshlrev_b32_e32 v145, 16, v156
	v_fmac_f32_e32 v146, v91, v145
	v_and_b32_e32 v145, 0xffff0000, v156
	v_fmac_f32_e32 v146, v92, v145
	v_lshlrev_b32_e32 v145, 16, v157
	v_fmac_f32_e32 v146, v93, v145
	v_and_b32_e32 v145, 0xffff0000, v157
	v_fmac_f32_e32 v146, v94, v145
	v_add_f32_e32 v145, v86, v146
	v_lshlrev_b32_e32 v146, 16, v158
	v_fmac_f32_e32 v147, v95, v146
	v_lshlrev_b32_e32 v146, 16, v159
	v_fmac_f32_e32 v147, v97, v146
	v_and_b32_e32 v146, 0xffff0000, v159
	v_fmac_f32_e32 v147, v98, v146
	v_lshlrev_b32_e32 v146, 16, v160
	v_fmac_f32_e32 v147, v99, v146
	v_and_b32_e32 v146, 0xffff0000, v160
	v_fmac_f32_e32 v147, v100, v146
	v_lshlrev_b32_e32 v146, 16, v161
	v_fmac_f32_e32 v147, v101, v146
	v_and_b32_e32 v146, 0xffff0000, v161
	v_log_f32_e32 v139, v139
	v_fmac_f32_e32 v147, v102, v146
	v_add_f32_e32 v145, v145, v147
	v_mul_f32_e64 v146, |v145|, s70
	v_min_f32_e32 v137, 0, v137
	v_exp_f32_e32 v146, v146
	v_sub_f32_e32 v137, v137, v138
	v_min_f32_e32 v138, 0, v144
	v_mul_f32_e32 v144, 0x3f317217, v139
	v_fma_f32 v144, v139, s72, -v144
	v_fmac_f32_e32 v144, 0x3377d1cf, v139
	v_fmac_f32_e32 v144, 0x3f317217, v139
	s_nop 0
	v_add_f32_e32 v146, 1.0, v146
	s_waitcnt vmcnt(1)
	v_lshlrev_b32_e32 v152, 16, v140
	v_mov_b32_e32 v139, v144
	s_nop 0
	s_nop 0
	v_mad_u64_u32 v[148:149], s[24:25], v74, s62, v[50:51]
	s_nop 0
	s_nop 0
	s_nop 0
	v_log_f32_e32 v150, v146
	v_mad_i32_i24 v149, v75, s62, v149
	v_add_co_u32_e64 v74, s[24:25], s44, v148
	s_nop 0
	v_mul_f32_e32 v144, 0x3f317217, v150
	v_and_b32_e32 v140, 0xffff0000, v140
	v_addc_co_u32_e64 v75, s[24:25], 0, v149, s[24:25]
	v_sub_f32_e32 v138, v138, v139
	v_min_f32_e32 v139, 0, v145
	v_fma_f32 v151, v150, s72, -v144
	v_mul_f32_e32 v140, v88, v140
	global_load_dwordx4 v[144:147], v[74:75], off offset:1536
	v_fmac_f32_e32 v140, v87, v152
	v_lshlrev_b32_e32 v74, 16, v141
	v_fmac_f32_e32 v140, v89, v74
	v_and_b32_e32 v74, 0xffff0000, v141
	v_fmac_f32_e32 v140, v90, v74
	v_lshlrev_b32_e32 v74, 16, v142
	v_fmac_f32_e32 v140, v91, v74
	v_and_b32_e32 v74, 0xffff0000, v142
	v_fmac_f32_e32 v140, v92, v74
	v_lshlrev_b32_e32 v74, 16, v143
	v_fmac_f32_e32 v140, v93, v74
	v_and_b32_e32 v74, 0xffff0000, v143
	v_fmac_f32_e32 v140, v94, v74
	v_lshl_add_u64 v[74:75], v[148:149], 0, s[34:35]
	v_add_f32_e32 v152, v86, v140
	global_load_dwordx4 v[140:143], v[74:75], off offset:16
	s_waitcnt vmcnt(2)
	v_lshlrev_b32_e32 v153, 16, v32
	v_and_b32_e32 v32, 0xffff0000, v32
	v_mul_f32_e32 v32, v96, v32
	v_fmac_f32_e32 v32, v95, v153
	v_lshlrev_b32_e32 v74, 16, v33
	v_fmac_f32_e32 v32, v97, v74
	v_and_b32_e32 v33, 0xffff0000, v33
	v_fmac_f32_e32 v32, v98, v33
	v_lshlrev_b32_e32 v33, 16, v34
	v_fmac_f32_e32 v32, v99, v33
	v_and_b32_e32 v33, 0xffff0000, v34
	v_fmac_f32_e32 v32, v100, v33
	v_lshlrev_b32_e32 v33, 16, v35
	v_fmac_f32_e32 v32, v101, v33
	v_and_b32_e32 v33, 0xffff0000, v35
	v_fmac_f32_e32 v32, v102, v33
	v_add_f32_e32 v74, v152, v32
	v_mul_f32_e64 v32, |v74|, s70
	v_exp_f32_e32 v32, v32
	v_fmac_f32_e32 v151, 0x3377d1cf, v150
	v_fmac_f32_e32 v151, 0x3f317217, v150
	s_nop 0
	v_add_f32_e32 v32, 1.0, v32
	s_nop 0
	v_mov_b32_e32 v33, v151
	s_nop 0
	v_mov_b32_e32 v75, v33
	v_mul_f32_e32 v137, 0x3d800000, v137
	s_nop 0
	s_nop 0
	v_log_f32_e32 v152, v32
	v_mad_u64_u32 v[32:33], s[24:25], v72, s62, v[50:51]
	v_mad_i32_i24 v33, v73, s62, v33
	v_add_co_u32_e64 v34, s[24:25], s44, v32
	s_nop 0
	s_nop 0
	v_addc_co_u32_e64 v35, s[24:25], 0, v33, s[24:25]
	global_load_dwordx4 v[148:151], v[34:35], off offset:1536
	v_mul_f32_e32 v35, 0x3f317217, v152
	v_fma_f32 v35, v152, s72, -v35
	v_fmac_f32_e32 v35, 0x3377d1cf, v152
	v_fmac_f32_e32 v35, 0x3f317217, v152
	s_nop 0
	v_lshl_add_u64 v[32:33], v[32:33], 0, s[34:35]
	v_min_f32_e32 v34, 0, v74
	s_nop 0
	global_load_dwordx4 v[152:155], v[32:33], off offset:16
	v_mad_u64_u32 v[32:33], s[0:1], v68, s62, v[50:51]
	s_nop 0
	v_mad_i32_i24 v33, v69, s62, v33
	v_sub_f32_e32 v73, v34, v35
	v_lshl_add_u64 v[34:35], v[32:33], 0, s[34:35]
	v_add_co_u32_e64 v32, s[0:1], s44, v32
	v_sub_f32_e32 v72, v139, v75
	s_nop 0
	v_addc_co_u32_e64 v33, s[0:1], 0, v33, s[0:1]
	global_load_dwordx4 v[156:159], v[32:33], off offset:1536
	global_load_dwordx4 v[160:163], v[34:35], off offset:16
	v_mad_u64_u32 v[32:33], s[0:1], v70, s62, v[50:51]
	s_waitcnt vmcnt(5)
	v_and_b32_e32 v69, 0xffff0000, v144
	v_lshlrev_b32_e32 v68, 16, v144
	v_mul_f32_e32 v69, v88, v69
	v_fmac_f32_e32 v69, v87, v68
	v_lshlrev_b32_e32 v68, 16, v145
	v_fmac_f32_e32 v69, v89, v68
	v_and_b32_e32 v68, 0xffff0000, v145
	v_fmac_f32_e32 v69, v90, v68
	v_lshlrev_b32_e32 v68, 16, v146
	v_fmac_f32_e32 v69, v91, v68
	v_and_b32_e32 v68, 0xffff0000, v146
	v_fmac_f32_e32 v69, v92, v68
	v_lshlrev_b32_e32 v68, 16, v147
	v_fmac_f32_e32 v69, v93, v68
	v_and_b32_e32 v68, 0xffff0000, v147
	v_fmac_f32_e32 v69, v94, v68
	s_waitcnt vmcnt(4)
	v_and_b32_e32 v70, 0xffff0000, v140
	v_add_f32_e32 v68, v86, v69
	v_lshlrev_b32_e32 v69, 16, v140
	v_mul_f32_e32 v70, v96, v70
	v_fmac_f32_e32 v70, v95, v69
	v_lshlrev_b32_e32 v69, 16, v141
	v_fmac_f32_e32 v70, v97, v69
	v_and_b32_e32 v69, 0xffff0000, v141
	v_mad_i32_i24 v33, v71, s62, v33
	v_fmac_f32_e32 v70, v98, v69
	v_lshlrev_b32_e32 v69, 16, v142
	v_lshl_add_u64 v[34:35], v[32:33], 0, s[34:35]
	v_fmac_f32_e32 v70, v99, v69
	v_and_b32_e32 v69, 0xffff0000, v142
	v_add_co_u32_e64 v32, s[0:1], s44, v32
	v_fmac_f32_e32 v70, v100, v69
	v_lshlrev_b32_e32 v69, 16, v143
	v_addc_co_u32_e64 v33, s[0:1], 0, v33, s[0:1]
	v_fmac_f32_e32 v70, v101, v69
	v_and_b32_e32 v69, 0xffff0000, v143
	global_load_dwordx4 v[140:143], v[32:33], off offset:1536
	s_nop 0
	global_load_dwordx4 v[32:35], v[34:35], off offset:16
	v_fmac_f32_e32 v70, v102, v69
	v_add_f32_e32 v68, v68, v70
	v_mul_f32_e64 v69, |v68|, s70
	v_exp_f32_e32 v69, v69
	v_min_f32_e32 v68, 0, v68
	v_add_f32_e32 v69, 1.0, v69
	s_nop 0
	s_waitcnt vmcnt(5)
	v_and_b32_e32 v74, 0xffff0000, v148
	v_lshlrev_b32_e32 v71, 16, v148
	v_mul_f32_e32 v74, v88, v74
	v_fmac_f32_e32 v74, v87, v71
	v_lshlrev_b32_e32 v71, 16, v149
	v_fmac_f32_e32 v74, v89, v71
	v_and_b32_e32 v71, 0xffff0000, v149
	v_fmac_f32_e32 v74, v90, v71
	v_lshlrev_b32_e32 v71, 16, v150
	v_fmac_f32_e32 v74, v91, v71
	v_and_b32_e32 v71, 0xffff0000, v150
	v_fmac_f32_e32 v74, v92, v71
	v_lshlrev_b32_e32 v71, 16, v151
	v_fmac_f32_e32 v74, v93, v71
	v_and_b32_e32 v71, 0xffff0000, v151
	v_fmac_f32_e32 v74, v94, v71
	s_waitcnt vmcnt(4)
	v_and_b32_e32 v75, 0xffff0000, v152
	v_add_f32_e32 v71, v86, v74
	v_lshlrev_b32_e32 v74, 16, v152
	v_mul_f32_e32 v75, v96, v75
	v_fmac_f32_e32 v75, v95, v74
	v_lshlrev_b32_e32 v74, 16, v153
	v_fmac_f32_e32 v75, v97, v74
	v_and_b32_e32 v74, 0xffff0000, v153
	v_fmac_f32_e32 v75, v98, v74
	v_lshlrev_b32_e32 v74, 16, v154
	v_fmac_f32_e32 v75, v99, v74
	v_and_b32_e32 v74, 0xffff0000, v154
	s_nop 0
	v_fmac_f32_e32 v75, v100, v74
	v_lshlrev_b32_e32 v74, 16, v155
	s_nop 0
	v_fmac_f32_e32 v75, v101, v74
	v_and_b32_e32 v74, 0xffff0000, v155
	v_log_f32_e32 v69, v69
	v_fmac_f32_e32 v75, v102, v74
	v_add_f32_e32 v71, v71, v75
	v_mul_f32_e64 v74, |v71|, s70
	v_exp_f32_e32 v74, v74
	v_mul_f32_e32 v70, 0x3f317217, v69
	v_fma_f32 v70, v69, s72, -v70
	v_fmac_f32_e32 v70, 0x3377d1cf, v69
	v_fmac_f32_e32 v70, 0x3f317217, v69
	s_nop 0
	v_add_f32_e32 v74, 1.0, v74
	s_waitcnt vmcnt(2)
	v_and_b32_e32 v139, 0xffff0000, v160
	v_mov_b32_e32 v69, v70
	s_nop 0
	s_nop 0
	s_nop 0
	v_sub_f32_e32 v68, v68, v69
	s_nop 0
	s_nop 0
	v_and_b32_e32 v75, 0xffff0000, v156
	v_min_f32_e32 v69, 0, v71
	v_lshlrev_b32_e32 v71, 16, v156
	v_mul_f32_e32 v75, v88, v75
	v_fmac_f32_e32 v75, v87, v71
	v_lshlrev_b32_e32 v71, 16, v157
	v_fmac_f32_e32 v75, v89, v71
	v_and_b32_e32 v71, 0xffff0000, v157
	v_fmac_f32_e32 v75, v90, v71
	v_lshlrev_b32_e32 v71, 16, v158
	v_fmac_f32_e32 v75, v91, v71
	v_and_b32_e32 v71, 0xffff0000, v158
	v_fmac_f32_e32 v75, v92, v71
	v_lshlrev_b32_e32 v71, 16, v159
	v_fmac_f32_e32 v75, v93, v71
	v_and_b32_e32 v71, 0xffff0000, v159
	v_fmac_f32_e32 v75, v94, v71
	v_add_f32_e32 v71, v86, v75
	v_lshlrev_b32_e32 v75, 16, v160
	v_mul_f32_e32 v139, v96, v139
	v_fmac_f32_e32 v139, v95, v75
	v_lshlrev_b32_e32 v75, 16, v161
	v_fmac_f32_e32 v139, v97, v75
	v_and_b32_e32 v75, 0xffff0000, v161
	v_fmac_f32_e32 v139, v98, v75
	v_lshlrev_b32_e32 v75, 16, v162
	v_fmac_f32_e32 v139, v99, v75
	v_and_b32_e32 v75, 0xffff0000, v162
	v_fmac_f32_e32 v139, v100, v75
	v_lshlrev_b32_e32 v75, 16, v163
	v_fmac_f32_e32 v139, v101, v75
	v_and_b32_e32 v75, 0xffff0000, v163
	v_log_f32_e32 v74, v74
	v_fmac_f32_e32 v139, v102, v75
	v_add_f32_e32 v71, v71, v139
	v_mul_f32_e64 v75, |v71|, s70
	v_exp_f32_e32 v75, v75
	v_mul_f32_e32 v70, 0x3f317217, v74
	v_fma_f32 v70, v74, s72, -v70
	v_fmac_f32_e32 v70, 0x3377d1cf, v74
	v_fmac_f32_e32 v70, 0x3f317217, v74
	s_nop 0
	v_add_f32_e32 v75, 1.0, v75
	s_waitcnt vmcnt(1)
	v_lshlrev_b32_e32 v148, 16, v140
	s_nop 0
	s_nop 0
	s_nop 0
	s_nop 0
	v_sub_f32_e32 v69, v69, v70
	s_nop 0
	s_nop 0
	v_log_f32_e32 v75, v75
	v_min_f32_e32 v74, 0, v71
	s_waitcnt vmcnt(0)
	v_lshlrev_b32_e32 v149, 16, v32
	v_and_b32_e32 v32, 0xffff0000, v32
	v_mul_f32_e32 v70, 0x3f317217, v75
	v_fma_f32 v139, v75, s72, -v70
	v_and_b32_e32 v70, 0xffff0000, v140
	v_mul_f32_e32 v140, v88, v70
	v_mad_u64_u32 v[70:71], s[24:25], v64, s62, v[50:51]
	v_mad_i32_i24 v71, v65, s62, v71
	v_add_co_u32_e64 v64, s[24:25], s44, v70
	v_fmac_f32_e32 v140, v87, v148
	s_nop 0
	v_addc_co_u32_e64 v65, s[24:25], 0, v71, s[24:25]
	global_load_dwordx4 v[144:147], v[64:65], off offset:1536
	v_lshlrev_b32_e32 v64, 16, v141
	v_fmac_f32_e32 v140, v89, v64
	v_and_b32_e32 v64, 0xffff0000, v141
	v_fmac_f32_e32 v140, v90, v64
	v_lshlrev_b32_e32 v64, 16, v142
	v_fmac_f32_e32 v140, v91, v64
	v_and_b32_e32 v64, 0xffff0000, v142
	v_fmac_f32_e32 v140, v92, v64
	v_lshlrev_b32_e32 v64, 16, v143
	v_fmac_f32_e32 v140, v93, v64
	v_and_b32_e32 v64, 0xffff0000, v143
	v_fmac_f32_e32 v140, v94, v64
	v_lshl_add_u64 v[64:65], v[70:71], 0, s[34:35]
	v_add_f32_e32 v148, v86, v140
	global_load_dwordx4 v[140:143], v[64:65], off offset:16
	v_mul_f32_e32 v32, v96, v32
	v_fmac_f32_e32 v32, v95, v149
	v_lshlrev_b32_e32 v64, 16, v33
	v_fmac_f32_e32 v32, v97, v64
	v_and_b32_e32 v33, 0xffff0000, v33
	v_fmac_f32_e32 v32, v98, v33
	v_lshlrev_b32_e32 v33, 16, v34
	v_fmac_f32_e32 v32, v99, v33
	v_and_b32_e32 v33, 0xffff0000, v34
	v_fmac_f32_e32 v32, v100, v33
	v_lshlrev_b32_e32 v33, 16, v35
	v_fmac_f32_e32 v32, v101, v33
	v_and_b32_e32 v33, 0xffff0000, v35
	v_fmac_f32_e32 v32, v102, v33
	v_add_f32_e32 v64, v148, v32
	v_mul_f32_e64 v32, |v64|, s70
	v_exp_f32_e32 v32, v32
	v_fmac_f32_e32 v139, 0x3377d1cf, v75
	v_fmac_f32_e32 v139, 0x3f317217, v75
	s_nop 0
	v_add_f32_e32 v32, 1.0, v32
	s_nop 0
	v_mov_b32_e32 v33, v139
	s_nop 0
	v_mov_b32_e32 v65, v33
	s_nop 0
	s_nop 0
	s_nop 0
	v_log_f32_e32 v70, v32
	v_mad_u64_u32 v[32:33], s[24:25], v62, s62, v[50:51]
	v_mad_i32_i24 v33, v63, s62, v33
	v_add_co_u32_e64 v34, s[24:25], s44, v32
	s_nop 0
	s_nop 0
	v_addc_co_u32_e64 v35, s[24:25], 0, v33, s[24:25]
	global_load_dwordx4 v[148:151], v[34:35], off offset:1536
	v_lshl_add_u64 v[32:33], v[32:33], 0, s[34:35]
	global_load_dwordx4 v[152:155], v[32:33], off offset:16
	v_mul_f32_e32 v35, 0x3f317217, v70
	v_fma_f32 v35, v70, s72, -v35
	v_fmac_f32_e32 v35, 0x3377d1cf, v70
	v_fmac_f32_e32 v35, 0x3f317217, v70
	s_nop 0
	v_mad_u64_u32 v[32:33], s[0:1], v60, s62, v[50:51]
	s_nop 0
	s_nop 0
	v_min_f32_e32 v34, 0, v64
	s_nop 0
	v_mad_i32_i24 v33, v61, s62, v33
	v_sub_f32_e32 v63, v34, v35
	v_lshl_add_u64 v[34:35], v[32:33], 0, s[34:35]
	v_add_co_u32_e64 v32, s[0:1], s44, v32
	v_sub_f32_e32 v62, v74, v65
	s_nop 0
	v_addc_co_u32_e64 v33, s[0:1], 0, v33, s[0:1]
	global_load_dwordx4 v[156:159], v[32:33], off offset:1536
	global_load_dwordx4 v[160:163], v[34:35], off offset:16
	v_mad_u64_u32 v[32:33], s[0:1], v66, s62, v[50:51]
	v_mad_i32_i24 v33, v67, s62, v33
	v_lshl_add_u64 v[34:35], v[32:33], 0, s[34:35]
	v_add_co_u32_e64 v32, s[0:1], s44, v32
	s_waitcnt vmcnt(5)
	v_and_b32_e32 v61, 0xffff0000, v144
	v_lshlrev_b32_e32 v60, 16, v144
	v_mul_f32_e32 v61, v88, v61
	v_fmac_f32_e32 v61, v87, v60
	v_lshlrev_b32_e32 v60, 16, v145
	v_fmac_f32_e32 v61, v89, v60
	v_and_b32_e32 v60, 0xffff0000, v145
	v_fmac_f32_e32 v61, v90, v60
	v_lshlrev_b32_e32 v60, 16, v146
	v_fmac_f32_e32 v61, v91, v60
	v_and_b32_e32 v60, 0xffff0000, v146
	v_fmac_f32_e32 v61, v92, v60
	v_lshlrev_b32_e32 v60, 16, v147
	v_fmac_f32_e32 v61, v93, v60
	v_and_b32_e32 v60, 0xffff0000, v147
	v_fmac_f32_e32 v61, v94, v60
	s_waitcnt vmcnt(4)
	v_and_b32_e32 v64, 0xffff0000, v140
	v_add_f32_e32 v60, v86, v61
	v_lshlrev_b32_e32 v61, 16, v140
	v_mul_f32_e32 v64, v96, v64
	v_fmac_f32_e32 v64, v95, v61
	v_lshlrev_b32_e32 v61, 16, v141
	v_fmac_f32_e32 v64, v97, v61
	v_and_b32_e32 v61, 0xffff0000, v141
	v_fmac_f32_e32 v64, v98, v61
	v_lshlrev_b32_e32 v61, 16, v142
	v_fmac_f32_e32 v64, v99, v61
	v_and_b32_e32 v61, 0xffff0000, v142
	v_fmac_f32_e32 v64, v100, v61
	v_lshlrev_b32_e32 v61, 16, v143
	v_fmac_f32_e32 v64, v101, v61
	v_and_b32_e32 v61, 0xffff0000, v143
	v_fmac_f32_e32 v64, v102, v61
	v_add_f32_e32 v60, v60, v64
	v_mul_f32_e64 v61, |v60|, s70
	v_exp_f32_e32 v61, v61
	v_addc_co_u32_e64 v33, s[0:1], 0, v33, s[0:1]
	v_min_f32_e32 v60, 0, v60
	v_add_f32_e32 v61, 1.0, v61
	s_nop 0
	s_waitcnt vmcnt(3)
	v_and_b32_e32 v74, 0xffff0000, v148
	s_nop 0
	s_nop 0
	global_load_dwordx4 v[64:67], v[32:33], off offset:1536
	s_nop 0
	global_load_dwordx4 v[32:35], v[34:35], off offset:16
	v_lshlrev_b32_e32 v71, 16, v148
	v_mul_f32_e32 v74, v88, v74
	v_fmac_f32_e32 v74, v87, v71
	v_lshlrev_b32_e32 v71, 16, v149
	v_fmac_f32_e32 v74, v89, v71
	v_and_b32_e32 v71, 0xffff0000, v149
	v_fmac_f32_e32 v74, v90, v71
	v_lshlrev_b32_e32 v71, 16, v150
	v_fmac_f32_e32 v74, v91, v71
	v_and_b32_e32 v71, 0xffff0000, v150
	v_fmac_f32_e32 v74, v92, v71
	v_lshlrev_b32_e32 v71, 16, v151
	v_fmac_f32_e32 v74, v93, v71
	v_and_b32_e32 v71, 0xffff0000, v151
	v_fmac_f32_e32 v74, v94, v71
	s_waitcnt vmcnt(4)
	v_and_b32_e32 v75, 0xffff0000, v152
	v_add_f32_e32 v71, v86, v74
	v_lshlrev_b32_e32 v74, 16, v152
	v_mul_f32_e32 v75, v96, v75
	v_fmac_f32_e32 v75, v95, v74
	v_lshlrev_b32_e32 v74, 16, v153
	v_fmac_f32_e32 v75, v97, v74
	v_and_b32_e32 v74, 0xffff0000, v153
	v_fmac_f32_e32 v75, v98, v74
	v_lshlrev_b32_e32 v74, 16, v154
	v_fmac_f32_e32 v75, v99, v74
	v_and_b32_e32 v74, 0xffff0000, v154
	v_fmac_f32_e32 v75, v100, v74
	v_lshlrev_b32_e32 v74, 16, v155
	v_fmac_f32_e32 v75, v101, v74
	v_and_b32_e32 v74, 0xffff0000, v155
	v_log_f32_e32 v61, v61
	v_fmac_f32_e32 v75, v102, v74
	v_add_f32_e32 v71, v71, v75
	v_mul_f32_e64 v74, |v71|, s70
	v_exp_f32_e32 v74, v74
	v_mul_f32_e32 v70, 0x3f317217, v61
	v_fma_f32 v70, v61, s72, -v70
	v_fmac_f32_e32 v70, 0x3377d1cf, v61
	v_fmac_f32_e32 v70, 0x3f317217, v61
	s_nop 0
	v_add_f32_e32 v74, 1.0, v74
	s_waitcnt vmcnt(2)
	v_and_b32_e32 v139, 0xffff0000, v160
	v_mov_b32_e32 v61, v70
	s_nop 0
	s_nop 0
	s_nop 0
	v_sub_f32_e32 v60, v60, v61
	s_nop 0
	s_nop 0
	v_and_b32_e32 v75, 0xffff0000, v156
	v_min_f32_e32 v61, 0, v71
	v_lshlrev_b32_e32 v71, 16, v156
	v_mul_f32_e32 v75, v88, v75
	v_fmac_f32_e32 v75, v87, v71
	v_lshlrev_b32_e32 v71, 16, v157
	v_fmac_f32_e32 v75, v89, v71
	v_and_b32_e32 v71, 0xffff0000, v157
	v_fmac_f32_e32 v75, v90, v71
	v_lshlrev_b32_e32 v71, 16, v158
	v_fmac_f32_e32 v75, v91, v71
	v_and_b32_e32 v71, 0xffff0000, v158
	v_fmac_f32_e32 v75, v92, v71
	v_lshlrev_b32_e32 v71, 16, v159
	v_fmac_f32_e32 v75, v93, v71
	v_and_b32_e32 v71, 0xffff0000, v159
	v_fmac_f32_e32 v75, v94, v71
	v_add_f32_e32 v71, v86, v75
	v_lshlrev_b32_e32 v75, 16, v160
	v_mul_f32_e32 v139, v96, v139
	v_fmac_f32_e32 v139, v95, v75
	v_lshlrev_b32_e32 v75, 16, v161
	v_fmac_f32_e32 v139, v97, v75
	v_and_b32_e32 v75, 0xffff0000, v161
	v_fmac_f32_e32 v139, v98, v75
	v_lshlrev_b32_e32 v75, 16, v162
	v_fmac_f32_e32 v139, v99, v75
	v_and_b32_e32 v75, 0xffff0000, v162
	v_fmac_f32_e32 v139, v100, v75
	v_lshlrev_b32_e32 v75, 16, v163
	v_fmac_f32_e32 v139, v101, v75
	v_and_b32_e32 v75, 0xffff0000, v163
	v_log_f32_e32 v74, v74
	v_fmac_f32_e32 v139, v102, v75
	v_add_f32_e32 v71, v71, v139
	v_mul_f32_e64 v75, |v71|, s70
	v_exp_f32_e32 v75, v75
	v_mul_f32_e32 v70, 0x3f317217, v74
	v_fma_f32 v70, v74, s72, -v70
	v_fmac_f32_e32 v70, 0x3377d1cf, v74
	v_fmac_f32_e32 v70, 0x3f317217, v74
	s_nop 0
	v_add_f32_e32 v75, 1.0, v75
	s_waitcnt vmcnt(1)
	v_lshlrev_b32_e32 v144, 16, v64
	s_nop 0
	s_nop 0
	s_nop 0
	s_nop 0
	v_sub_f32_e32 v74, v61, v70
	s_nop 0
	s_nop 0
	v_log_f32_e32 v75, v75
	v_min_f32_e32 v61, 0, v71
	v_and_b32_e32 v64, 0xffff0000, v64
	v_mul_f32_e32 v64, v88, v64
	v_mul_f32_e32 v70, 0x3f317217, v75
	v_fma_f32 v139, v75, s72, -v70
	v_mad_u64_u32 v[70:71], s[24:25], v58, s62, v[50:51]
	v_mad_i32_i24 v71, v59, s62, v71
	v_add_co_u32_e64 v58, s[24:25], s44, v70
	v_fmac_f32_e32 v64, v87, v144
	s_nop 0
	v_addc_co_u32_e64 v59, s[24:25], 0, v71, s[24:25]
	global_load_dwordx4 v[140:143], v[58:59], off offset:1536
	v_lshlrev_b32_e32 v58, 16, v65
	v_fmac_f32_e32 v64, v89, v58
	v_and_b32_e32 v58, 0xffff0000, v65
	v_fmac_f32_e32 v64, v90, v58
	v_lshlrev_b32_e32 v58, 16, v66
	v_fmac_f32_e32 v64, v91, v58
	v_and_b32_e32 v58, 0xffff0000, v66
	v_fmac_f32_e32 v64, v92, v58
	v_lshlrev_b32_e32 v58, 16, v67
	v_fmac_f32_e32 v64, v93, v58
	v_and_b32_e32 v58, 0xffff0000, v67
	v_fmac_f32_e32 v64, v94, v58
	v_lshl_add_u64 v[58:59], v[70:71], 0, s[34:35]
	v_add_f32_e32 v144, v86, v64
	global_load_dwordx4 v[64:67], v[58:59], off offset:16
	s_waitcnt vmcnt(2)
	v_lshlrev_b32_e32 v145, 16, v32
	v_and_b32_e32 v32, 0xffff0000, v32
	v_mul_f32_e32 v32, v96, v32
	v_fmac_f32_e32 v32, v95, v145
	v_lshlrev_b32_e32 v58, 16, v33
	v_fmac_f32_e32 v32, v97, v58
	v_and_b32_e32 v33, 0xffff0000, v33
	v_fmac_f32_e32 v32, v98, v33
	v_lshlrev_b32_e32 v33, 16, v34
	v_fmac_f32_e32 v32, v99, v33
	v_and_b32_e32 v33, 0xffff0000, v34
	v_fmac_f32_e32 v32, v100, v33
	v_lshlrev_b32_e32 v33, 16, v35
	v_fmac_f32_e32 v32, v101, v33
	v_and_b32_e32 v33, 0xffff0000, v35
	v_fmac_f32_e32 v32, v102, v33
	v_add_f32_e32 v70, v144, v32
	v_mul_f32_e64 v32, |v70|, s70
	v_exp_f32_e32 v32, v32
	v_fmac_f32_e32 v139, 0x3377d1cf, v75
	v_fmac_f32_e32 v139, 0x3f317217, v75
	s_nop 0
	v_add_f32_e32 v32, 1.0, v32
	s_nop 0
	v_mov_b32_e32 v33, v139
	s_nop 0
	v_mov_b32_e32 v71, v33
	v_mad_u64_u32 v[58:59], s[24:25], v56, s62, v[50:51]
	s_nop 0
	s_nop 0
	v_log_f32_e32 v75, v32
	v_mad_i32_i24 v59, v57, s62, v59
	v_add_co_u32_e64 v32, s[24:25], s44, v58
	v_mul_f32_e32 v57, 0x3f317217, v75
	s_nop 0
	v_addc_co_u32_e64 v33, s[24:25], 0, v59, s[24:25]
	global_load_dwordx4 v[32:35], v[32:33], off offset:1536
	v_fma_f32 v57, v75, s72, -v57
	v_fmac_f32_e32 v57, 0x3377d1cf, v75
	v_fmac_f32_e32 v57, 0x3f317217, v75
	s_nop 0
	v_sub_f32_e32 v139, v61, v71
	s_nop 0
	s_nop 0
	v_min_f32_e32 v56, 0, v70
	s_nop 0
	v_sub_f32_e32 v75, v56, v57
	v_lshl_add_u64 v[56:57], v[58:59], 0, s[34:35]
	global_load_dwordx4 v[56:59], v[56:57], off offset:16
	v_mad_u64_u32 v[70:71], s[0:1], v54, s62, v[50:51]
	v_mad_i32_i24 v71, v55, s62, v71
	v_lshl_add_u64 v[54:55], v[70:71], 0, s[34:35]
	v_add_co_u32_e64 v70, s[0:1], s44, v70
	s_waitcnt vmcnt(2)
	v_and_b32_e32 v61, 0xffff0000, v64
	v_addc_co_u32_e64 v71, s[0:1], 0, v71, s[0:1]
	v_mad_u64_u32 v[50:51], s[0:1], v52, s62, v[50:51]
	v_mad_i32_i24 v51, v53, s62, v51
	v_and_b32_e32 v53, 0xffff0000, v140
	v_lshlrev_b32_e32 v52, 16, v140
	v_mul_f32_e32 v53, v88, v53
	v_fmac_f32_e32 v53, v87, v52
	v_lshlrev_b32_e32 v52, 16, v141
	v_fmac_f32_e32 v53, v89, v52
	v_and_b32_e32 v52, 0xffff0000, v141
	v_fmac_f32_e32 v53, v90, v52
	v_lshlrev_b32_e32 v52, 16, v142
	v_fmac_f32_e32 v53, v91, v52
	v_and_b32_e32 v52, 0xffff0000, v142
	v_fmac_f32_e32 v53, v92, v52
	v_lshlrev_b32_e32 v52, 16, v143
	v_fmac_f32_e32 v53, v93, v52
	v_and_b32_e32 v52, 0xffff0000, v143
	v_fmac_f32_e32 v53, v94, v52
	global_load_dwordx4 v[144:147], v[70:71], off offset:1536
	global_load_dwordx4 v[148:151], v[54:55], off offset:16
	v_add_f32_e32 v52, v86, v53
	v_lshlrev_b32_e32 v53, 16, v64
	v_mul_f32_e32 v61, v96, v61
	v_fmac_f32_e32 v61, v95, v53
	v_lshlrev_b32_e32 v53, 16, v65
	v_fmac_f32_e32 v61, v97, v53
	v_and_b32_e32 v53, 0xffff0000, v65
	v_fmac_f32_e32 v61, v98, v53
	v_lshlrev_b32_e32 v53, 16, v66
	v_fmac_f32_e32 v61, v99, v53
	v_and_b32_e32 v53, 0xffff0000, v66
	v_fmac_f32_e32 v61, v100, v53
	v_lshlrev_b32_e32 v53, 16, v67
	v_fmac_f32_e32 v61, v101, v53
	v_and_b32_e32 v53, 0xffff0000, v67
	v_fmac_f32_e32 v61, v102, v53
	v_add_f32_e32 v61, v52, v61
	v_mul_f32_e64 v52, |v61|, s70
	v_exp_f32_e32 v52, v52
	v_lshl_add_u64 v[54:55], v[50:51], 0, s[34:35]
	v_add_co_u32_e64 v50, s[0:1], s44, v50
	v_add_f32_e32 v52, 1.0, v52
	s_nop 0
	v_addc_co_u32_e64 v51, s[0:1], 0, v51, s[0:1]
	s_nop 0
	s_nop 1
	s_nop 0
	s_nop 0
	v_log_f32_e32 v70, v52
	global_load_dwordx4 v[50:53], v[50:51], off offset:1536
	s_nop 0
	global_load_dwordx4 v[64:67], v[54:55], off offset:16
	v_min_f32_e32 v54, 0, v61
	s_waitcnt vmcnt(5)
	v_lshlrev_b32_e32 v61, 16, v32
	v_and_b32_e32 v32, 0xffff0000, v32
	v_mul_f32_e32 v32, v88, v32
	v_fmac_f32_e32 v32, v87, v61
	v_lshlrev_b32_e32 v61, 16, v33
	v_fmac_f32_e32 v32, v89, v61
	v_and_b32_e32 v33, 0xffff0000, v33
	v_fmac_f32_e32 v32, v90, v33
	v_lshlrev_b32_e32 v33, 16, v34
	v_fmac_f32_e32 v32, v91, v33
	v_and_b32_e32 v33, 0xffff0000, v34
	v_fmac_f32_e32 v32, v92, v33
	v_lshlrev_b32_e32 v33, 16, v35
	v_fmac_f32_e32 v32, v93, v33
	v_and_b32_e32 v33, 0xffff0000, v35
	s_waitcnt vmcnt(4)
	v_and_b32_e32 v34, 0xffff0000, v56
	v_fmac_f32_e32 v32, v94, v33
	v_lshlrev_b32_e32 v33, 16, v56
	v_mul_f32_e32 v34, v96, v34
	v_fmac_f32_e32 v34, v95, v33
	v_lshlrev_b32_e32 v33, 16, v57
	v_fmac_f32_e32 v34, v97, v33
	v_and_b32_e32 v33, 0xffff0000, v57
	v_fmac_f32_e32 v34, v98, v33
	v_lshlrev_b32_e32 v33, 16, v58
	v_fmac_f32_e32 v34, v99, v33
	v_and_b32_e32 v33, 0xffff0000, v58
	v_fmac_f32_e32 v34, v100, v33
	v_lshlrev_b32_e32 v33, 16, v59
	v_fmac_f32_e32 v34, v101, v33
	v_and_b32_e32 v33, 0xffff0000, v59
	v_add_f32_e32 v32, v86, v32
	v_fmac_f32_e32 v34, v102, v33
	v_add_f32_e32 v32, v32, v34
	v_mul_f32_e64 v33, |v32|, s70
	v_exp_f32_e32 v33, v33
	v_mul_f32_e32 v55, 0x3f317217, v70
	v_fma_f32 v55, v70, s72, -v55
	v_fmac_f32_e32 v55, 0x3377d1cf, v70
	v_add_f32_e32 v33, 1.0, v33
	v_fmac_f32_e32 v55, 0x3f317217, v70
	s_nop 0
	s_nop 0
	s_nop 0
	v_mov_b32_e32 v34, v55
	s_nop 0
	s_nop 0
	s_nop 0
	s_waitcnt vmcnt(3)
	v_and_b32_e32 v55, 0xffff0000, v144
	v_sub_f32_e32 v34, v54, v34
	v_lshlrev_b32_e32 v54, 16, v144
	v_mul_f32_e32 v55, v88, v55
	v_fmac_f32_e32 v55, v87, v54
	v_lshlrev_b32_e32 v54, 16, v145
	v_fmac_f32_e32 v55, v89, v54
	v_and_b32_e32 v54, 0xffff0000, v145
	v_fmac_f32_e32 v55, v90, v54
	v_lshlrev_b32_e32 v54, 16, v146
	v_fmac_f32_e32 v55, v91, v54
	v_and_b32_e32 v54, 0xffff0000, v146
	v_fmac_f32_e32 v55, v92, v54
	v_lshlrev_b32_e32 v54, 16, v147
	v_fmac_f32_e32 v55, v93, v54
	v_and_b32_e32 v54, 0xffff0000, v147
	v_log_f32_e32 v33, v33
	v_fmac_f32_e32 v55, v94, v54
	s_waitcnt vmcnt(2)
	v_and_b32_e32 v56, 0xffff0000, v148
	v_add_f32_e32 v54, v86, v55
	v_lshlrev_b32_e32 v55, 16, v148
	v_mul_f32_e32 v56, v96, v56
	v_fmac_f32_e32 v56, v95, v55
	v_lshlrev_b32_e32 v55, 16, v149
	v_fmac_f32_e32 v56, v97, v55
	v_and_b32_e32 v55, 0xffff0000, v149
	v_mul_f32_e32 v35, 0x3f317217, v33
	v_fmac_f32_e32 v56, v98, v55
	v_lshlrev_b32_e32 v55, 16, v150
	v_fma_f32 v35, v33, s72, -v35
	v_fmac_f32_e32 v56, v99, v55
	v_and_b32_e32 v55, 0xffff0000, v150
	v_fmac_f32_e32 v35, 0x3377d1cf, v33
	v_fmac_f32_e32 v56, v100, v55
	v_lshlrev_b32_e32 v55, 16, v151
	v_fmac_f32_e32 v35, 0x3f317217, v33
	v_fmac_f32_e32 v56, v101, v55
	v_and_b32_e32 v55, 0xffff0000, v151
	s_nop 0
	v_fmac_f32_e32 v56, v102, v55
	v_min_f32_e32 v32, 0, v32
	v_mov_b32_e32 v33, v35
	s_nop 0
	v_add_f32_e32 v54, v54, v56
	s_nop 0
	v_mul_f32_e64 v55, |v54|, s70
	v_sub_f32_e32 v32, v32, v33
	v_min_f32_e32 v33, 0, v54
	s_waitcnt vmcnt(1)
	v_lshlrev_b32_e32 v54, 16, v50
	v_and_b32_e32 v50, 0xffff0000, v50
	v_mul_f32_e32 v50, v88, v50
	v_fmac_f32_e32 v50, v87, v54
	v_lshlrev_b32_e32 v54, 16, v51
	v_fmac_f32_e32 v50, v89, v54
	v_and_b32_e32 v51, 0xffff0000, v51
	v_fmac_f32_e32 v50, v90, v51
	v_lshlrev_b32_e32 v51, 16, v52
	v_fmac_f32_e32 v50, v91, v51
	v_and_b32_e32 v51, 0xffff0000, v52
	v_fmac_f32_e32 v50, v92, v51
	v_lshlrev_b32_e32 v51, 16, v53
	v_fmac_f32_e32 v50, v93, v51
	v_and_b32_e32 v51, 0xffff0000, v53
	s_waitcnt vmcnt(0)
	v_and_b32_e32 v52, 0xffff0000, v64
	v_fmac_f32_e32 v50, v94, v51
	v_lshlrev_b32_e32 v51, 16, v64
	v_mul_f32_e32 v52, v96, v52
	v_fmac_f32_e32 v52, v95, v51
	v_lshlrev_b32_e32 v51, 16, v65
	v_fmac_f32_e32 v52, v97, v51
	v_and_b32_e32 v51, 0xffff0000, v65
	v_fmac_f32_e32 v52, v98, v51
	v_lshlrev_b32_e32 v51, 16, v66
	v_exp_f32_e32 v55, v55
	v_fmac_f32_e32 v52, v99, v51
	v_and_b32_e32 v51, 0xffff0000, v66
	v_fmac_f32_e32 v52, v100, v51
	v_lshlrev_b32_e32 v51, 16, v67
	v_fmac_f32_e32 v52, v101, v51
	v_and_b32_e32 v51, 0xffff0000, v67
	v_add_f32_e32 v50, v86, v50
	v_fmac_f32_e32 v52, v102, v51
	v_add_f32_e32 v55, 1.0, v55
	v_add_f32_e32 v50, v50, v52
	s_nop 0
	v_mul_f32_e64 v51, |v50|, s70
	v_exp_f32_e32 v51, v51
	s_nop 0
	s_nop 0
	v_log_f32_e32 v55, v55
	v_add_f32_e32 v51, 1.0, v51
	s_nop 0
	s_nop 0
	v_fmamk_f32 v67, v138, 0x3d800000, v137
	v_mul_f32_e32 v35, 0x3f317217, v55
	s_nop 0
	v_fmamk_f32 v66, v72, 0x3d800000, v67
	v_fma_f32 v35, v55, s72, -v35
	s_nop 0
	v_fmamk_f32 v65, v73, 0x3d800000, v66
	v_fmac_f32_e32 v35, 0x3377d1cf, v55
	v_log_f32_e32 v51, v51
	v_fmamk_f32 v64, v68, 0x3d800000, v65
	v_fmac_f32_e32 v35, 0x3f317217, v55
	s_nop 0
	v_fmamk_f32 v61, v69, 0x3d800000, v64
	v_fmamk_f32 v59, v62, 0x3d800000, v61
	s_nop 0
	s_nop 0
	v_fmamk_f32 v58, v63, 0x3d800000, v59
	v_sub_f32_e32 v33, v33, v35
	v_min_f32_e32 v35, 0, v50
	v_mul_f32_e32 v50, 0x3f317217, v51
	v_fmamk_f32 v57, v60, 0x3d800000, v58
	v_fma_f32 v50, v51, s72, -v50
	v_fmamk_f32 v56, v74, 0x3d800000, v57
	v_fmac_f32_e32 v50, 0x3377d1cf, v51
	v_fmamk_f32 v55, v139, 0x3d800000, v56
	v_fmac_f32_e32 v50, 0x3f317217, v51
	s_nop 0
	v_fmamk_f32 v54, v75, 0x3d800000, v55
	v_fmamk_f32 v53, v34, 0x3d800000, v54
	s_nop 0
	s_nop 0
	s_nop 0
	v_fmamk_f32 v52, v32, 0x3d800000, v53
	v_sub_f32_e32 v35, v35, v50
	v_fmamk_f32 v51, v33, 0x3d800000, v52
	v_fmamk_f32 v50, v35, 0x3d800000, v51
	ds_write_b32 v77, v50
	s_waitcnt lgkmcnt(0)
	s_barrier
	ds_read2st64_b32 v[34:35], v78 offset1:2
	ds_read2st64_b32 v[32:33], v78 offset0:4 offset1:6
	s_waitcnt lgkmcnt(1)
	v_add_f32_e32 v60, 0, v34
	v_add_f32_e32 v34, v60, v35
	s_waitcnt lgkmcnt(0)
	v_add_f32_e32 v34, v34, v32
	v_add_f32_e32 v34, v34, v33
	s_and_saveexec_b64 s[0:1], s[6:7]
	s_cbranch_execz .LBB0_1112
	v_mul_f32_e32 v62, 0x3fb8aa3b, v34
	v_exp_f32_e32 v62, v62
	v_add_f32_e32 v40, v40, v34
	ds_write_b32 v81, v62
	s_branch .LBB0_1112

.LBB0_1182:
	v_add_u32_e32 v163, s95, v42
	v_add_u32_e32 v32, 0x1ff, v163
	v_add_u32_e32 v165, s95, v154
	v_cndmask_b32_e64 v32, v32, v165, s[44:45]
	v_ashrrev_i32_e32 v33, 31, v32
	v_lshl_add_u64 v[38:39], v[32:33], 0, s[62:63]
	v_add_u32_e32 v32, 0x1fe, v163
	v_add_u32_e32 v33, 1, v165
	v_cndmask_b32_e64 v32, v32, v33, s[44:45]
	v_ashrrev_i32_e32 v33, 31, v32
	v_lshl_add_u64 v[34:35], v[32:33], 0, s[62:63]
	v_add_u32_e32 v32, 0x1fd, v163
	v_add_u32_e32 v33, 2, v165
	v_cndmask_b32_e64 v32, v32, v33, s[44:45]
	v_ashrrev_i32_e32 v33, 31, v32
	v_mad_u64_u32 v[36:37], s[0:1], v38, s86, v[58:59]
	v_lshl_add_u64 v[32:33], v[32:33], 0, s[62:63]
	v_mad_i32_i24 v37, v39, s86, v37
	v_mad_u64_u32 v[62:63], s[0:1], v34, s86, v[58:59]
	v_mad_u64_u32 v[64:65], s[0:1], v32, s86, v[58:59]
	v_mad_i32_i24 v63, v35, s86, v63
	v_mad_i32_i24 v65, v33, s86, v65
	global_load_ushort v204, v[36:37], off
	global_load_ushort v188, v[36:37], off offset:1024
	global_load_ushort v197, v[36:37], off offset:2048
	global_load_ushort v201, v[62:63], off
	global_load_ushort v185, v[62:63], off offset:1024
	global_load_ushort v198, v[62:63], off offset:2048
	global_load_ushort v190, v[64:65], off offset:1024
	global_load_ushort v174, v[64:65], off offset:2048
	v_add_u32_e32 v36, 0x1fc, v163
	v_add_u32_e32 v37, 3, v165
	v_cndmask_b32_e64 v36, v36, v37, s[44:45]
	v_add_u32_e32 v62, 0x1fb, v163
	v_add_u32_e32 v63, 4, v165
	v_add_u32_e32 v66, 0x1fa, v163
	v_add_u32_e32 v67, 5, v165
	v_ashrrev_i32_e32 v37, 31, v36
	v_cndmask_b32_e64 v62, v62, v63, s[44:45]
	v_cndmask_b32_e64 v66, v66, v67, s[44:45]
	v_lshl_add_u64 v[84:85], v[36:37], 0, s[62:63]
	v_ashrrev_i32_e32 v63, 31, v62
	v_ashrrev_i32_e32 v67, 31, v66
	v_mad_u64_u32 v[36:37], s[0:1], v84, s86, v[58:59]
	v_lshl_add_u64 v[82:83], v[62:63], 0, s[62:63]
	v_lshl_add_u64 v[78:79], v[66:67], 0, s[62:63]
	v_mad_i32_i24 v37, v85, s86, v37
	v_mad_u64_u32 v[62:63], s[0:1], v82, s86, v[58:59]
	v_mad_u64_u32 v[66:67], s[0:1], v78, s86, v[58:59]
	v_mad_i32_i24 v63, v83, s86, v63
	v_mad_i32_i24 v67, v79, s86, v67
	global_load_ushort v206, v[64:65], off
	global_load_ushort v203, v[36:37], off
	global_load_ushort v200, v[36:37], off offset:1024
	global_load_ushort v193, v[36:37], off offset:2048
	global_load_ushort v192, v[62:63], off
	global_load_ushort v164, v[62:63], off offset:1024
	global_load_ushort v178, v[62:63], off offset:2048
	global_load_ushort v184, v[66:67], off offset:2048
	v_add_u32_e32 v36, 0x1f9, v163
	v_add_u32_e32 v37, 6, v165
	v_cndmask_b32_e64 v36, v36, v37, s[44:45]
	v_add_u32_e32 v62, 0x1f8, v163
	v_add_u32_e32 v63, 7, v165
	v_ashrrev_i32_e32 v37, 31, v36
	v_cndmask_b32_e64 v62, v62, v63, s[44:45]
	v_lshl_add_u64 v[76:77], v[36:37], 0, s[62:63]
	v_ashrrev_i32_e32 v63, 31, v62
	v_mad_u64_u32 v[36:37], s[0:1], v76, s86, v[58:59]
	v_lshl_add_u64 v[80:81], v[62:63], 0, s[62:63]
	v_mad_i32_i24 v37, v77, s86, v37
	v_mad_u64_u32 v[62:63], s[0:1], v80, s86, v[58:59]
	v_mad_i32_i24 v63, v81, s86, v63
	global_load_ushort v196, v[66:67], off
	global_load_ushort v176, v[66:67], off offset:1024
	global_load_ushort v191, v[36:37], off
	global_load_ushort v180, v[36:37], off offset:1024
	global_load_ushort v162, v[36:37], off offset:2048
	global_load_ushort v187, v[62:63], off
	global_load_ushort v179, v[62:63], off offset:1024
	global_load_ushort v167, v[62:63], off offset:2048
	v_add_u32_e32 v36, 0x1f7, v163
	v_add_u32_e32 v37, 8, v165
	v_cndmask_b32_e64 v36, v36, v37, s[44:45]
	v_add_u32_e32 v62, 0x1f6, v163
	v_add_u32_e32 v63, 9, v165
	v_add_u32_e32 v64, 0x1f5, v163
	v_add_u32_e32 v65, 10, v165
	v_ashrrev_i32_e32 v37, 31, v36
	v_cndmask_b32_e64 v62, v62, v63, s[44:45]
	v_cndmask_b32_e64 v64, v64, v65, s[44:45]
	v_lshl_add_u64 v[72:73], v[36:37], 0, s[62:63]
	v_ashrrev_i32_e32 v63, 31, v62
	v_ashrrev_i32_e32 v65, 31, v64
	v_mad_u64_u32 v[36:37], s[0:1], v72, s86, v[58:59]
	v_lshl_add_u64 v[70:71], v[62:63], 0, s[62:63]
	v_lshl_add_u64 v[68:69], v[64:65], 0, s[62:63]
	v_mad_i32_i24 v37, v73, s86, v37
	v_mad_u64_u32 v[62:63], s[0:1], v70, s86, v[58:59]
	v_mad_u64_u32 v[168:169], s[0:1], v68, s86, v[58:59]
	v_mad_i32_i24 v63, v71, s86, v63
	v_mad_i32_i24 v169, v69, s86, v169
	global_load_ushort v182, v[36:37], off
	global_load_ushort v159, v[36:37], off offset:1024
	global_load_ushort v166, v[36:37], off offset:2048
	global_load_ushort v177, v[62:63], off
	global_load_ushort v158, v[62:63], off offset:1024
	global_load_ushort v171, v[62:63], off offset:2048
	global_load_ushort v160, v[168:169], off offset:1024
	global_load_ushort v157, v[168:169], off offset:2048
	v_add_u32_e32 v36, 0x1f4, v163
	v_add_u32_e32 v37, 11, v165
	v_cndmask_b32_e64 v62, v36, v37, s[44:45]
	v_mov_b64_e32 v[36:37], s[72:73]
	v_mad_u64_u32 v[64:65], s[0:1], v38, s86, v[36:37]
	v_mad_i32_i24 v65, v39, s86, v65
	v_add_co_u32_e32 v38, vcc, s78, v64
	v_ashrrev_i32_e32 v63, 31, v62
	s_nop 0
	v_addc_co_u32_e32 v39, vcc, 0, v65, vcc
	global_load_dwordx4 v[208:211], v[38:39], off offset:1536
	v_lshl_add_u64 v[74:75], v[62:63], 0, s[62:63]
	v_add_u32_e32 v62, 0x1f3, v163
	v_add_u32_e32 v63, 12, v165
	v_add_u32_e32 v161, 0x1f2, v163
	v_add_u32_e32 v170, 13, v165
	v_lshl_add_u64 v[64:65], v[64:65], 0, s[70:71]
	v_cndmask_b32_e64 v62, v62, v63, s[44:45]
	global_load_dwordx4 v[212:215], v[64:65], off offset:16
	v_cndmask_b32_e64 v64, v161, v170, s[44:45]
	v_ashrrev_i32_e32 v63, 31, v62
	v_ashrrev_i32_e32 v65, 31, v64
	v_mad_u64_u32 v[38:39], s[0:1], v74, s86, v[58:59]
	v_lshl_add_u64 v[66:67], v[62:63], 0, s[62:63]
	v_lshl_add_u64 v[64:65], v[64:65], 0, s[62:63]
	v_mad_i32_i24 v39, v75, s86, v39
	v_mad_u64_u32 v[62:63], s[0:1], v66, s86, v[58:59]
	v_mad_u64_u32 v[220:221], s[0:1], v64, s86, v[58:59]
	v_mad_u64_u32 v[224:225], s[0:1], v34, s86, v[36:37]
	v_mad_i32_i24 v63, v67, s86, v63
	v_mad_i32_i24 v221, v65, s86, v221
	global_load_ushort v205, v[168:169], off
	global_load_ushort v202, v[38:39], off
	global_load_ushort v199, v[38:39], off offset:1024
	global_load_ushort v186, v[38:39], off offset:2048
	global_load_ushort v183, v[62:63], off
	global_load_ushort v161, v[62:63], off offset:1024
	global_load_ushort v168, v[62:63], off offset:2048
	global_load_ushort v172, v[220:221], off offset:2048
	v_add_u32_e32 v38, 0x1f1, v163
	v_add_u32_e32 v39, 14, v165
	v_mad_i32_i24 v225, v35, s86, v225
	v_add_co_u32_e32 v34, vcc, s78, v224
	v_cndmask_b32_e64 v38, v38, v39, s[44:45]
	s_nop 0
	v_addc_co_u32_e32 v35, vcc, 0, v225, vcc
	v_ashrrev_i32_e32 v39, 31, v38
	global_load_dwordx4 v[216:219], v[34:35], off offset:1536
	v_lshl_add_u64 v[62:63], v[38:39], 0, s[62:63]
	v_add_u32_e32 v38, 0x1f0, v163
	v_add_u32_e32 v39, 15, v165
	v_cndmask_b32_e64 v38, v38, v39, s[44:45]
	v_ashrrev_i32_e32 v39, 31, v38
	v_lshl_add_u64 v[38:39], v[38:39], 0, s[62:63]
	v_mad_u64_u32 v[34:35], s[0:1], v38, s86, v[58:59]
	v_mad_u64_u32 v[222:223], s[0:1], v62, s86, v[58:59]
	v_mad_i32_i24 v35, v39, s86, v35
	v_mad_i32_i24 v223, v63, s86, v223
	global_load_ushort v189, v[220:221], off
	global_load_ushort v163, v[220:221], off offset:1024
	global_load_ushort v181, v[222:223], off
	global_load_ushort v169, v[222:223], off offset:1024
	global_load_ushort v170, v[222:223], off offset:2048
	global_load_ushort v175, v[34:35], off
	global_load_ushort v165, v[34:35], off offset:1024
	global_load_ushort v173, v[34:35], off offset:2048
	v_lshl_add_u64 v[34:35], v[224:225], 0, s[70:71]
	global_load_dwordx4 v[220:223], v[34:35], off offset:16
	v_mad_u64_u32 v[34:35], s[0:1], v32, s86, v[36:37]
	v_mad_i32_i24 v35, v33, s86, v35
	v_lshl_add_u64 v[32:33], v[34:35], 0, s[70:71]
	v_add_co_u32_e32 v34, vcc, s78, v34
	s_waitcnt vmcnt(0)
	v_and_b32_e32 v207, 0xffff0000, v212
	v_addc_co_u32_e32 v35, vcc, 0, v35, vcc
	global_load_dwordx4 v[224:227], v[34:35], off offset:1536
	global_load_dwordx4 v[228:231], v[32:33], off offset:16
	v_mad_u64_u32 v[32:33], s[0:1], v84, s86, v[36:37]
	v_mad_i32_i24 v33, v85, s86, v33
	v_and_b32_e32 v85, 0xffff0000, v208
	v_lshlrev_b32_e32 v84, 16, v208
	s_waitcnt lgkmcnt(0)
	v_mul_f32_e32 v85, v139, v85
	v_fmac_f32_e32 v85, v138, v84
	v_lshlrev_b32_e32 v84, 16, v209
	v_fmac_f32_e32 v85, v140, v84
	v_and_b32_e32 v84, 0xffff0000, v209
	v_fmac_f32_e32 v85, v141, v84
	v_lshlrev_b32_e32 v84, 16, v210
	v_lshl_add_u64 v[34:35], v[32:33], 0, s[70:71]
	v_fmac_f32_e32 v85, v142, v84
	v_and_b32_e32 v84, 0xffff0000, v210
	v_add_co_u32_e32 v32, vcc, s78, v32
	v_fmac_f32_e32 v85, v143, v84
	v_lshlrev_b32_e32 v84, 16, v211
	v_addc_co_u32_e32 v33, vcc, 0, v33, vcc
	v_fmac_f32_e32 v85, v144, v84
	v_and_b32_e32 v84, 0xffff0000, v211
	global_load_dwordx4 v[208:211], v[32:33], off offset:1536
	s_nop 0
	global_load_dwordx4 v[32:35], v[34:35], off offset:16
	v_fmac_f32_e32 v85, v145, v84
	v_add_f32_e32 v84, v137, v85
	v_lshlrev_b32_e32 v85, 16, v212
	v_mul_f32_e32 v207, v147, v207
	v_fmac_f32_e32 v207, v146, v85
	v_lshlrev_b32_e32 v85, 16, v213
	v_fmac_f32_e32 v207, v148, v85
	v_and_b32_e32 v85, 0xffff0000, v213
	v_fmac_f32_e32 v207, v149, v85
	v_lshlrev_b32_e32 v85, 16, v214
	v_fmac_f32_e32 v207, v150, v85
	v_and_b32_e32 v85, 0xffff0000, v214
	v_and_b32_e32 v213, 0xffff0000, v216
	v_fmac_f32_e32 v207, v151, v85
	v_lshlrev_b32_e32 v85, 16, v215
	v_lshlrev_b32_e32 v212, 16, v216
	v_mul_f32_e32 v213, v139, v213
	v_fmac_f32_e32 v207, v152, v85
	v_and_b32_e32 v85, 0xffff0000, v215
	v_fmac_f32_e32 v213, v138, v212
	v_lshlrev_b32_e32 v212, 16, v217
	v_fmac_f32_e32 v207, v153, v85
	v_fmac_f32_e32 v213, v140, v212
	v_and_b32_e32 v212, 0xffff0000, v217
	v_add_f32_e32 v84, v84, v207
	v_fmac_f32_e32 v213, v141, v212
	v_lshlrev_b32_e32 v212, 16, v218
	v_mul_f32_e64 v85, |v84|, s88
	v_fmac_f32_e32 v213, v142, v212
	v_and_b32_e32 v212, 0xffff0000, v218
	v_exp_f32_e32 v85, v85
	v_fmac_f32_e32 v213, v143, v212
	v_lshlrev_b32_e32 v212, 16, v219
	v_fmac_f32_e32 v213, v144, v212
	v_and_b32_e32 v212, 0xffff0000, v219
	v_fmac_f32_e32 v213, v145, v212
	v_and_b32_e32 v214, 0xffff0000, v220
	v_add_f32_e32 v212, v137, v213
	v_lshlrev_b32_e32 v213, 16, v220
	v_mul_f32_e32 v214, v147, v214
	v_add_f32_e32 v85, 1.0, v85
	v_fmac_f32_e32 v214, v146, v213
	v_lshlrev_b32_e32 v213, 16, v221
	s_nop 0
	v_fmac_f32_e32 v214, v148, v213
	v_and_b32_e32 v213, 0xffff0000, v221
	s_nop 0
	v_fmac_f32_e32 v214, v149, v213
	v_lshlrev_b32_e32 v213, 16, v222
	s_nop 0
	v_fmac_f32_e32 v214, v150, v213
	v_and_b32_e32 v213, 0xffff0000, v222
	v_log_f32_e32 v85, v85
	v_fmac_f32_e32 v214, v151, v213
	v_lshlrev_b32_e32 v213, 16, v223
	v_fmac_f32_e32 v214, v152, v213
	v_and_b32_e32 v213, 0xffff0000, v223
	v_fmac_f32_e32 v214, v153, v213
	v_add_f32_e32 v212, v212, v214
	v_mul_f32_e32 v207, 0x3f317217, v85
	v_mul_f32_e64 v213, |v212|, s88
	v_fma_f32 v207, v85, s90, -v207
	v_exp_f32_e32 v213, v213
	v_fmac_f32_e32 v207, 0x3377d1cf, v85
	v_fmac_f32_e32 v207, 0x3f317217, v85
	s_nop 0
	s_waitcnt vmcnt(3)
	v_and_b32_e32 v214, 0xffff0000, v224
	v_mul_f32_e32 v214, v139, v214
	v_mov_b32_e32 v85, v207
	s_nop 0
	s_nop 0
	v_add_f32_e32 v207, 1.0, v213
	s_nop 0
	s_waitcnt vmcnt(2)
	v_and_b32_e32 v215, 0xffff0000, v228
	v_mul_f32_e32 v215, v147, v215
	s_nop 0
	s_nop 0
	v_lshlrev_b32_e32 v213, 16, v224
	v_fmac_f32_e32 v214, v138, v213
	v_lshlrev_b32_e32 v213, 16, v225
	v_fmac_f32_e32 v214, v140, v213
	v_and_b32_e32 v213, 0xffff0000, v225
	v_fmac_f32_e32 v214, v141, v213
	v_lshlrev_b32_e32 v213, 16, v226
	v_fmac_f32_e32 v214, v142, v213
	v_and_b32_e32 v213, 0xffff0000, v226
	v_fmac_f32_e32 v214, v143, v213
	v_lshlrev_b32_e32 v213, 16, v227
	v_fmac_f32_e32 v214, v144, v213
	v_and_b32_e32 v213, 0xffff0000, v227
	v_fmac_f32_e32 v214, v145, v213
	v_add_f32_e32 v213, v137, v214
	v_lshlrev_b32_e32 v214, 16, v228
	v_fmac_f32_e32 v215, v146, v214
	v_lshlrev_b32_e32 v214, 16, v229
	v_fmac_f32_e32 v215, v148, v214
	v_and_b32_e32 v214, 0xffff0000, v229
	v_fmac_f32_e32 v215, v149, v214
	v_lshlrev_b32_e32 v214, 16, v230
	v_fmac_f32_e32 v215, v150, v214
	v_and_b32_e32 v214, 0xffff0000, v230
	v_fmac_f32_e32 v215, v151, v214
	v_lshlrev_b32_e32 v214, 16, v231
	v_fmac_f32_e32 v215, v152, v214
	v_and_b32_e32 v214, 0xffff0000, v231
	v_log_f32_e32 v207, v207
	v_fmac_f32_e32 v215, v153, v214
	v_add_f32_e32 v213, v213, v215
	v_mul_f32_e64 v214, |v213|, s88
	v_min_f32_e32 v84, 0, v84
	v_exp_f32_e32 v214, v214
	v_sub_f32_e32 v84, v84, v85
	v_min_f32_e32 v85, 0, v212
	v_mul_f32_e32 v212, 0x3f317217, v207
	v_fma_f32 v212, v207, s90, -v212
	v_fmac_f32_e32 v212, 0x3377d1cf, v207
	v_fmac_f32_e32 v212, 0x3f317217, v207
	s_nop 0
	v_add_f32_e32 v214, 1.0, v214
	s_waitcnt vmcnt(1)
	v_lshlrev_b32_e32 v220, 16, v208
	v_mov_b32_e32 v207, v212
	s_nop 0
	s_nop 0
	v_mad_u64_u32 v[216:217], s[0:1], v82, s86, v[36:37]
	s_nop 0
	s_nop 0
	s_nop 0
	v_log_f32_e32 v218, v214
	v_mad_i32_i24 v217, v83, s86, v217
	v_add_co_u32_e64 v82, s[0:1], s78, v216
	s_nop 0
	v_mul_f32_e32 v212, 0x3f317217, v218
	v_and_b32_e32 v208, 0xffff0000, v208
	v_addc_co_u32_e64 v83, s[0:1], 0, v217, s[0:1]
	v_sub_f32_e32 v85, v85, v207
	v_min_f32_e32 v207, 0, v213
	v_fma_f32 v219, v218, s90, -v212
	v_mul_f32_e32 v208, v139, v208
	global_load_dwordx4 v[212:215], v[82:83], off offset:1536
	v_fmac_f32_e32 v208, v138, v220
	v_lshlrev_b32_e32 v82, 16, v209
	v_fmac_f32_e32 v208, v140, v82
	v_and_b32_e32 v82, 0xffff0000, v209
	v_fmac_f32_e32 v208, v141, v82
	v_lshlrev_b32_e32 v82, 16, v210
	v_fmac_f32_e32 v208, v142, v82
	v_and_b32_e32 v82, 0xffff0000, v210
	v_fmac_f32_e32 v208, v143, v82
	v_lshlrev_b32_e32 v82, 16, v211
	v_fmac_f32_e32 v208, v144, v82
	v_and_b32_e32 v82, 0xffff0000, v211
	v_fmac_f32_e32 v208, v145, v82
	v_lshl_add_u64 v[82:83], v[216:217], 0, s[70:71]
	v_add_f32_e32 v220, v137, v208
	global_load_dwordx4 v[208:211], v[82:83], off offset:16
	s_waitcnt vmcnt(2)
	v_lshlrev_b32_e32 v221, 16, v32
	v_and_b32_e32 v32, 0xffff0000, v32
	v_mul_f32_e32 v32, v147, v32
	v_fmac_f32_e32 v32, v146, v221
	v_lshlrev_b32_e32 v82, 16, v33
	v_fmac_f32_e32 v32, v148, v82
	v_and_b32_e32 v33, 0xffff0000, v33
	v_fmac_f32_e32 v32, v149, v33
	v_lshlrev_b32_e32 v33, 16, v34
	v_fmac_f32_e32 v32, v150, v33
	v_and_b32_e32 v33, 0xffff0000, v34
	v_fmac_f32_e32 v32, v151, v33
	v_lshlrev_b32_e32 v33, 16, v35
	v_fmac_f32_e32 v32, v152, v33
	v_and_b32_e32 v33, 0xffff0000, v35
	v_fmac_f32_e32 v32, v153, v33
	v_add_f32_e32 v82, v220, v32
	v_mul_f32_e64 v32, |v82|, s88
	v_exp_f32_e32 v32, v32
	v_fmac_f32_e32 v219, 0x3377d1cf, v218
	v_fmac_f32_e32 v219, 0x3f317217, v218
	s_nop 0
	v_add_f32_e32 v32, 1.0, v32
	s_nop 0
	v_mov_b32_e32 v33, v219
	s_nop 0
	v_mov_b32_e32 v83, v33
	v_mul_f32_e32 v84, 0x3d800000, v84
	s_nop 0
	s_nop 0
	v_log_f32_e32 v220, v32
	v_mad_u64_u32 v[32:33], s[0:1], v78, s86, v[36:37]
	v_mad_i32_i24 v33, v79, s86, v33
	v_add_co_u32_e64 v34, s[0:1], s78, v32
	s_nop 0
	s_nop 0
	v_addc_co_u32_e64 v35, s[0:1], 0, v33, s[0:1]
	global_load_dwordx4 v[216:219], v[34:35], off offset:1536
	v_mul_f32_e32 v35, 0x3f317217, v220
	v_fma_f32 v35, v220, s90, -v35
	v_fmac_f32_e32 v35, 0x3377d1cf, v220
	v_fmac_f32_e32 v35, 0x3f317217, v220
	s_nop 0
	v_lshl_add_u64 v[32:33], v[32:33], 0, s[70:71]
	v_min_f32_e32 v34, 0, v82
	s_nop 0
	global_load_dwordx4 v[220:223], v[32:33], off offset:16
	v_mad_u64_u32 v[32:33], s[0:1], v76, s86, v[36:37]
	s_nop 0
	v_mad_i32_i24 v33, v77, s86, v33
	v_sub_f32_e32 v79, v34, v35
	v_lshl_add_u64 v[34:35], v[32:33], 0, s[70:71]
	v_add_co_u32_e32 v32, vcc, s78, v32
	v_sub_f32_e32 v78, v207, v83
	s_nop 0
	v_addc_co_u32_e32 v33, vcc, 0, v33, vcc
	global_load_dwordx4 v[224:227], v[32:33], off offset:1536
	global_load_dwordx4 v[228:231], v[34:35], off offset:16
	v_mad_u64_u32 v[32:33], s[0:1], v80, s86, v[36:37]
	s_waitcnt vmcnt(5)
	v_and_b32_e32 v77, 0xffff0000, v212
	v_lshlrev_b32_e32 v76, 16, v212
	v_mul_f32_e32 v77, v139, v77
	v_fmac_f32_e32 v77, v138, v76
	v_lshlrev_b32_e32 v76, 16, v213
	v_fmac_f32_e32 v77, v140, v76
	v_and_b32_e32 v76, 0xffff0000, v213
	v_fmac_f32_e32 v77, v141, v76
	v_lshlrev_b32_e32 v76, 16, v214
	v_fmac_f32_e32 v77, v142, v76
	v_and_b32_e32 v76, 0xffff0000, v214
	v_fmac_f32_e32 v77, v143, v76
	v_lshlrev_b32_e32 v76, 16, v215
	v_fmac_f32_e32 v77, v144, v76
	v_and_b32_e32 v76, 0xffff0000, v215
	v_fmac_f32_e32 v77, v145, v76
	s_waitcnt vmcnt(4)
	v_and_b32_e32 v80, 0xffff0000, v208
	v_add_f32_e32 v76, v137, v77
	v_lshlrev_b32_e32 v77, 16, v208
	v_mul_f32_e32 v80, v147, v80
	v_fmac_f32_e32 v80, v146, v77
	v_lshlrev_b32_e32 v77, 16, v209
	v_fmac_f32_e32 v80, v148, v77
	v_and_b32_e32 v77, 0xffff0000, v209
	v_fmac_f32_e32 v80, v149, v77
	v_lshlrev_b32_e32 v77, 16, v210
	v_fmac_f32_e32 v80, v150, v77
	v_and_b32_e32 v77, 0xffff0000, v210
	v_fmac_f32_e32 v80, v151, v77
	v_lshlrev_b32_e32 v77, 16, v211
	v_fmac_f32_e32 v80, v152, v77
	v_and_b32_e32 v77, 0xffff0000, v211
	v_fmac_f32_e32 v80, v153, v77
	v_add_f32_e32 v76, v76, v80
	v_mul_f32_e64 v77, |v76|, s88
	v_exp_f32_e32 v77, v77
	v_mad_i32_i24 v33, v81, s86, v33
	v_lshl_add_u64 v[34:35], v[32:33], 0, s[70:71]
	v_add_co_u32_e32 v32, vcc, s78, v32
	v_add_f32_e32 v77, 1.0, v77
	s_nop 0
	v_addc_co_u32_e32 v33, vcc, 0, v33, vcc
	s_nop 0
	v_min_f32_e32 v76, 0, v76
	s_waitcnt vmcnt(3)
	v_and_b32_e32 v209, 0xffff0000, v216
	s_nop 0
	s_nop 0
	global_load_dwordx4 v[80:83], v[32:33], off offset:1536
	s_nop 0
	global_load_dwordx4 v[32:35], v[34:35], off offset:16
	v_lshlrev_b32_e32 v208, 16, v216
	v_mul_f32_e32 v209, v139, v209
	v_fmac_f32_e32 v209, v138, v208
	v_lshlrev_b32_e32 v208, 16, v217
	v_fmac_f32_e32 v209, v140, v208
	v_and_b32_e32 v208, 0xffff0000, v217
	v_fmac_f32_e32 v209, v141, v208
	v_lshlrev_b32_e32 v208, 16, v218
	v_fmac_f32_e32 v209, v142, v208
	v_and_b32_e32 v208, 0xffff0000, v218
	v_fmac_f32_e32 v209, v143, v208
	v_lshlrev_b32_e32 v208, 16, v219
	v_fmac_f32_e32 v209, v144, v208
	v_and_b32_e32 v208, 0xffff0000, v219
	v_fmac_f32_e32 v209, v145, v208
	s_waitcnt vmcnt(4)
	v_and_b32_e32 v210, 0xffff0000, v220
	v_add_f32_e32 v208, v137, v209
	v_lshlrev_b32_e32 v209, 16, v220
	v_mul_f32_e32 v210, v147, v210
	v_fmac_f32_e32 v210, v146, v209
	v_lshlrev_b32_e32 v209, 16, v221
	v_fmac_f32_e32 v210, v148, v209
	v_and_b32_e32 v209, 0xffff0000, v221
	v_fmac_f32_e32 v210, v149, v209
	v_lshlrev_b32_e32 v209, 16, v222
	v_fmac_f32_e32 v210, v150, v209
	v_and_b32_e32 v209, 0xffff0000, v222
	v_fmac_f32_e32 v210, v151, v209
	v_lshlrev_b32_e32 v209, 16, v223
	v_fmac_f32_e32 v210, v152, v209
	v_and_b32_e32 v209, 0xffff0000, v223
	v_log_f32_e32 v77, v77
	v_fmac_f32_e32 v210, v153, v209
	v_add_f32_e32 v208, v208, v210
	v_mul_f32_e64 v209, |v208|, s88
	v_exp_f32_e32 v209, v209
	v_mul_f32_e32 v207, 0x3f317217, v77
	v_fma_f32 v207, v77, s90, -v207
	v_fmac_f32_e32 v207, 0x3377d1cf, v77
	v_fmac_f32_e32 v207, 0x3f317217, v77
	s_nop 0
	v_add_f32_e32 v209, 1.0, v209
	s_waitcnt vmcnt(2)
	v_and_b32_e32 v211, 0xffff0000, v228
	v_mov_b32_e32 v77, v207
	s_nop 0
	s_nop 0
	s_nop 0
	v_sub_f32_e32 v76, v76, v77
	s_nop 0
	s_nop 0
	v_and_b32_e32 v210, 0xffff0000, v224
	v_min_f32_e32 v77, 0, v208
	v_lshlrev_b32_e32 v208, 16, v224
	v_mul_f32_e32 v210, v139, v210
	v_fmac_f32_e32 v210, v138, v208
	v_lshlrev_b32_e32 v208, 16, v225
	v_fmac_f32_e32 v210, v140, v208
	v_and_b32_e32 v208, 0xffff0000, v225
	v_fmac_f32_e32 v210, v141, v208
	v_lshlrev_b32_e32 v208, 16, v226
	v_fmac_f32_e32 v210, v142, v208
	v_and_b32_e32 v208, 0xffff0000, v226
	v_fmac_f32_e32 v210, v143, v208
	v_lshlrev_b32_e32 v208, 16, v227
	v_fmac_f32_e32 v210, v144, v208
	v_and_b32_e32 v208, 0xffff0000, v227
	v_fmac_f32_e32 v210, v145, v208
	v_add_f32_e32 v208, v137, v210
	v_lshlrev_b32_e32 v210, 16, v228
	v_mul_f32_e32 v211, v147, v211
	v_fmac_f32_e32 v211, v146, v210
	v_lshlrev_b32_e32 v210, 16, v229
	v_fmac_f32_e32 v211, v148, v210
	v_and_b32_e32 v210, 0xffff0000, v229
	v_fmac_f32_e32 v211, v149, v210
	v_lshlrev_b32_e32 v210, 16, v230
	v_fmac_f32_e32 v211, v150, v210
	v_and_b32_e32 v210, 0xffff0000, v230
	v_fmac_f32_e32 v211, v151, v210
	v_lshlrev_b32_e32 v210, 16, v231
	v_fmac_f32_e32 v211, v152, v210
	v_and_b32_e32 v210, 0xffff0000, v231
	v_log_f32_e32 v209, v209
	v_fmac_f32_e32 v211, v153, v210
	v_add_f32_e32 v208, v208, v211
	v_mul_f32_e64 v210, |v208|, s88
	v_exp_f32_e32 v210, v210
	v_mul_f32_e32 v207, 0x3f317217, v209
	v_fma_f32 v207, v209, s90, -v207
	v_fmac_f32_e32 v207, 0x3377d1cf, v209
	v_fmac_f32_e32 v207, 0x3f317217, v209
	s_nop 0
	v_add_f32_e32 v210, 1.0, v210
	s_waitcnt vmcnt(1)
	v_lshlrev_b32_e32 v216, 16, v80
	s_nop 0
	s_nop 0
	s_nop 0
	v_mad_u64_u32 v[212:213], s[0:1], v72, s86, v[36:37]
	s_nop 0
	s_nop 0
	s_nop 0
	v_log_f32_e32 v214, v210
	s_nop 0
	v_mad_i32_i24 v213, v73, s86, v213
	v_add_co_u32_e64 v72, s[0:1], s78, v212
	v_sub_f32_e32 v77, v77, v207
	v_min_f32_e32 v207, 0, v208
	v_mul_f32_e32 v208, 0x3f317217, v214
	v_and_b32_e32 v80, 0xffff0000, v80
	v_addc_co_u32_e64 v73, s[0:1], 0, v213, s[0:1]
	v_fma_f32 v215, v214, s90, -v208
	v_mul_f32_e32 v80, v139, v80
	global_load_dwordx4 v[208:211], v[72:73], off offset:1536
	v_fmac_f32_e32 v80, v138, v216
	v_lshlrev_b32_e32 v72, 16, v81
	v_fmac_f32_e32 v80, v140, v72
	v_and_b32_e32 v72, 0xffff0000, v81
	v_fmac_f32_e32 v80, v141, v72
	v_lshlrev_b32_e32 v72, 16, v82
	v_fmac_f32_e32 v80, v142, v72
	v_and_b32_e32 v72, 0xffff0000, v82
	v_fmac_f32_e32 v80, v143, v72
	v_lshlrev_b32_e32 v72, 16, v83
	v_fmac_f32_e32 v80, v144, v72
	v_and_b32_e32 v72, 0xffff0000, v83
	v_fmac_f32_e32 v80, v145, v72
	v_lshl_add_u64 v[72:73], v[212:213], 0, s[70:71]
	v_add_f32_e32 v216, v137, v80
	global_load_dwordx4 v[80:83], v[72:73], off offset:16
	s_waitcnt vmcnt(2)
	v_lshlrev_b32_e32 v217, 16, v32
	v_and_b32_e32 v32, 0xffff0000, v32
	v_mul_f32_e32 v32, v147, v32
	v_fmac_f32_e32 v32, v146, v217
	v_lshlrev_b32_e32 v72, 16, v33
	v_fmac_f32_e32 v32, v148, v72
	v_and_b32_e32 v33, 0xffff0000, v33
	v_fmac_f32_e32 v32, v149, v33
	v_lshlrev_b32_e32 v33, 16, v34
	v_fmac_f32_e32 v32, v150, v33
	v_and_b32_e32 v33, 0xffff0000, v34
	v_fmac_f32_e32 v32, v151, v33
	v_lshlrev_b32_e32 v33, 16, v35
	v_fmac_f32_e32 v32, v152, v33
	v_and_b32_e32 v33, 0xffff0000, v35
	v_fmac_f32_e32 v32, v153, v33
	v_add_f32_e32 v72, v216, v32
	v_mul_f32_e64 v32, |v72|, s88
	v_exp_f32_e32 v32, v32
	v_fmac_f32_e32 v215, 0x3377d1cf, v214
	v_fmac_f32_e32 v215, 0x3f317217, v214
	s_nop 0
	v_add_f32_e32 v32, 1.0, v32
	s_nop 0
	v_mov_b32_e32 v33, v215
	s_nop 0
	v_mov_b32_e32 v73, v33
	s_nop 0
	s_nop 0
	s_nop 0
	v_log_f32_e32 v216, v32
	v_mad_u64_u32 v[32:33], s[0:1], v70, s86, v[36:37]
	v_mad_i32_i24 v33, v71, s86, v33
	v_add_co_u32_e64 v34, s[0:1], s78, v32
	s_nop 0
	s_nop 0
	v_addc_co_u32_e64 v35, s[0:1], 0, v33, s[0:1]
	global_load_dwordx4 v[212:215], v[34:35], off offset:1536
	v_mul_f32_e32 v35, 0x3f317217, v216
	v_fma_f32 v35, v216, s90, -v35
	v_fmac_f32_e32 v35, 0x3377d1cf, v216
	v_fmac_f32_e32 v35, 0x3f317217, v216
	s_nop 0
	v_lshl_add_u64 v[32:33], v[32:33], 0, s[70:71]
	v_min_f32_e32 v34, 0, v72
	s_nop 0
	global_load_dwordx4 v[216:219], v[32:33], off offset:16
	v_mad_u64_u32 v[32:33], s[0:1], v68, s86, v[36:37]
	s_nop 0
	v_mad_i32_i24 v33, v69, s86, v33
	v_sub_f32_e32 v71, v34, v35
	v_lshl_add_u64 v[34:35], v[32:33], 0, s[70:71]
	v_add_co_u32_e32 v32, vcc, s78, v32
	v_sub_f32_e32 v70, v207, v73
	s_nop 0
	v_addc_co_u32_e32 v33, vcc, 0, v33, vcc
	global_load_dwordx4 v[220:223], v[32:33], off offset:1536
	global_load_dwordx4 v[224:227], v[34:35], off offset:16
	v_mad_u64_u32 v[32:33], s[0:1], v74, s86, v[36:37]
	s_waitcnt vmcnt(5)
	v_and_b32_e32 v69, 0xffff0000, v208
	v_lshlrev_b32_e32 v68, 16, v208
	v_mul_f32_e32 v69, v139, v69
	v_fmac_f32_e32 v69, v138, v68
	v_lshlrev_b32_e32 v68, 16, v209
	v_fmac_f32_e32 v69, v140, v68
	v_and_b32_e32 v68, 0xffff0000, v209
	v_fmac_f32_e32 v69, v141, v68
	v_lshlrev_b32_e32 v68, 16, v210
	v_fmac_f32_e32 v69, v142, v68
	v_and_b32_e32 v68, 0xffff0000, v210
	v_fmac_f32_e32 v69, v143, v68
	v_lshlrev_b32_e32 v68, 16, v211
	v_fmac_f32_e32 v69, v144, v68
	v_and_b32_e32 v68, 0xffff0000, v211
	v_fmac_f32_e32 v69, v145, v68
	s_waitcnt vmcnt(4)
	v_and_b32_e32 v72, 0xffff0000, v80
	v_add_f32_e32 v68, v137, v69
	v_lshlrev_b32_e32 v69, 16, v80
	v_mul_f32_e32 v72, v147, v72
	v_fmac_f32_e32 v72, v146, v69
	v_lshlrev_b32_e32 v69, 16, v81
	v_fmac_f32_e32 v72, v148, v69
	v_and_b32_e32 v69, 0xffff0000, v81
	v_fmac_f32_e32 v72, v149, v69
	v_lshlrev_b32_e32 v69, 16, v82
	v_fmac_f32_e32 v72, v150, v69
	v_and_b32_e32 v69, 0xffff0000, v82
	v_fmac_f32_e32 v72, v151, v69
	v_lshlrev_b32_e32 v69, 16, v83
	v_fmac_f32_e32 v72, v152, v69
	v_and_b32_e32 v69, 0xffff0000, v83
	v_fmac_f32_e32 v72, v153, v69
	v_add_f32_e32 v68, v68, v72
	v_mul_f32_e64 v69, |v68|, s88
	v_exp_f32_e32 v69, v69
	v_mad_i32_i24 v33, v75, s86, v33
	v_lshl_add_u64 v[34:35], v[32:33], 0, s[70:71]
	v_add_co_u32_e32 v32, vcc, s78, v32
	v_add_f32_e32 v69, 1.0, v69
	s_nop 0
	v_addc_co_u32_e32 v33, vcc, 0, v33, vcc
	s_nop 0
	v_min_f32_e32 v68, 0, v68
	s_waitcnt vmcnt(3)
	v_and_b32_e32 v82, 0xffff0000, v212
	s_nop 0
	s_nop 0
	global_load_dwordx4 v[72:75], v[32:33], off offset:1536
	s_nop 0
	global_load_dwordx4 v[32:35], v[34:35], off offset:16
	v_lshlrev_b32_e32 v81, 16, v212
	v_mul_f32_e32 v82, v139, v82
	v_fmac_f32_e32 v82, v138, v81
	v_lshlrev_b32_e32 v81, 16, v213
	v_fmac_f32_e32 v82, v140, v81
	v_and_b32_e32 v81, 0xffff0000, v213
	v_fmac_f32_e32 v82, v141, v81
	v_lshlrev_b32_e32 v81, 16, v214
	v_fmac_f32_e32 v82, v142, v81
	v_and_b32_e32 v81, 0xffff0000, v214
	v_fmac_f32_e32 v82, v143, v81
	v_lshlrev_b32_e32 v81, 16, v215
	v_fmac_f32_e32 v82, v144, v81
	v_and_b32_e32 v81, 0xffff0000, v215
	v_fmac_f32_e32 v82, v145, v81
	s_waitcnt vmcnt(4)
	v_and_b32_e32 v83, 0xffff0000, v216
	v_add_f32_e32 v81, v137, v82
	v_lshlrev_b32_e32 v82, 16, v216
	v_mul_f32_e32 v83, v147, v83
	v_fmac_f32_e32 v83, v146, v82
	v_lshlrev_b32_e32 v82, 16, v217
	v_fmac_f32_e32 v83, v148, v82
	v_and_b32_e32 v82, 0xffff0000, v217
	v_fmac_f32_e32 v83, v149, v82
	v_lshlrev_b32_e32 v82, 16, v218
	v_fmac_f32_e32 v83, v150, v82
	v_and_b32_e32 v82, 0xffff0000, v218
	v_fmac_f32_e32 v83, v151, v82
	v_lshlrev_b32_e32 v82, 16, v219
	v_fmac_f32_e32 v83, v152, v82
	v_and_b32_e32 v82, 0xffff0000, v219
	v_log_f32_e32 v69, v69
	v_fmac_f32_e32 v83, v153, v82
	v_add_f32_e32 v81, v81, v83
	v_mul_f32_e64 v82, |v81|, s88
	v_exp_f32_e32 v82, v82
	v_mul_f32_e32 v80, 0x3f317217, v69
	v_fma_f32 v80, v69, s90, -v80
	v_fmac_f32_e32 v80, 0x3377d1cf, v69
	v_fmac_f32_e32 v80, 0x3f317217, v69
	s_nop 0
	v_add_f32_e32 v82, 1.0, v82
	s_waitcnt vmcnt(2)
	v_and_b32_e32 v207, 0xffff0000, v224
	v_mov_b32_e32 v69, v80
	s_nop 0
	s_nop 0
	s_nop 0
	v_sub_f32_e32 v68, v68, v69
	s_nop 0
	s_nop 0
	v_and_b32_e32 v83, 0xffff0000, v220
	v_min_f32_e32 v69, 0, v81
	v_lshlrev_b32_e32 v81, 16, v220
	v_mul_f32_e32 v83, v139, v83
	v_fmac_f32_e32 v83, v138, v81
	v_lshlrev_b32_e32 v81, 16, v221
	v_fmac_f32_e32 v83, v140, v81
	v_and_b32_e32 v81, 0xffff0000, v221
	v_fmac_f32_e32 v83, v141, v81
	v_lshlrev_b32_e32 v81, 16, v222
	v_fmac_f32_e32 v83, v142, v81
	v_and_b32_e32 v81, 0xffff0000, v222
	v_fmac_f32_e32 v83, v143, v81
	v_lshlrev_b32_e32 v81, 16, v223
	v_fmac_f32_e32 v83, v144, v81
	v_and_b32_e32 v81, 0xffff0000, v223
	v_fmac_f32_e32 v83, v145, v81
	v_add_f32_e32 v81, v137, v83
	v_lshlrev_b32_e32 v83, 16, v224
	v_mul_f32_e32 v207, v147, v207
	v_fmac_f32_e32 v207, v146, v83
	v_lshlrev_b32_e32 v83, 16, v225
	v_fmac_f32_e32 v207, v148, v83
	v_and_b32_e32 v83, 0xffff0000, v225
	v_fmac_f32_e32 v207, v149, v83
	v_lshlrev_b32_e32 v83, 16, v226
	v_fmac_f32_e32 v207, v150, v83
	v_and_b32_e32 v83, 0xffff0000, v226
	v_fmac_f32_e32 v207, v151, v83
	v_lshlrev_b32_e32 v83, 16, v227
	v_fmac_f32_e32 v207, v152, v83
	v_and_b32_e32 v83, 0xffff0000, v227
	v_log_f32_e32 v82, v82
	v_fmac_f32_e32 v207, v153, v83
	v_add_f32_e32 v81, v81, v207
	v_mul_f32_e64 v83, |v81|, s88
	v_exp_f32_e32 v83, v83
	v_mul_f32_e32 v80, 0x3f317217, v82
	v_fma_f32 v80, v82, s90, -v80
	v_fmac_f32_e32 v80, 0x3377d1cf, v82
	v_fmac_f32_e32 v80, 0x3f317217, v82
	s_nop 0
	v_add_f32_e32 v83, 1.0, v83
	v_min_f32_e32 v210, 0, v81
	s_nop 0
	s_nop 0
	s_nop 0
	v_mad_u64_u32 v[208:209], s[0:1], v66, s86, v[36:37]
	s_nop 0
	s_nop 0
	s_nop 0
	v_log_f32_e32 v207, v83
	s_nop 0
	v_mad_i32_i24 v209, v67, s86, v209
	v_add_co_u32_e64 v66, s[0:1], s78, v208
	v_sub_f32_e32 v69, v69, v80
	v_mul_f32_e32 v80, 0x3f317217, v207
	v_addc_co_u32_e64 v67, s[0:1], 0, v209, s[0:1]
	v_fma_f32 v211, v207, s90, -v80
	s_waitcnt vmcnt(1)
	v_lshlrev_b32_e32 v212, 16, v72
	v_and_b32_e32 v72, 0xffff0000, v72
	global_load_dwordx4 v[80:83], v[66:67], off offset:1536
	v_mul_f32_e32 v72, v139, v72
	v_fmac_f32_e32 v72, v138, v212
	v_lshlrev_b32_e32 v66, 16, v73
	v_fmac_f32_e32 v72, v140, v66
	v_and_b32_e32 v66, 0xffff0000, v73
	v_fmac_f32_e32 v72, v141, v66
	v_lshlrev_b32_e32 v66, 16, v74
	v_fmac_f32_e32 v72, v142, v66
	v_and_b32_e32 v66, 0xffff0000, v74
	v_fmac_f32_e32 v72, v143, v66
	v_lshlrev_b32_e32 v66, 16, v75
	v_fmac_f32_e32 v72, v144, v66
	v_and_b32_e32 v66, 0xffff0000, v75
	v_fmac_f32_e32 v72, v145, v66
	v_lshl_add_u64 v[66:67], v[208:209], 0, s[70:71]
	v_add_f32_e32 v212, v137, v72
	global_load_dwordx4 v[72:75], v[66:67], off offset:16
	s_waitcnt vmcnt(2)
	v_lshlrev_b32_e32 v213, 16, v32
	v_and_b32_e32 v32, 0xffff0000, v32
	v_mul_f32_e32 v32, v147, v32
	v_fmac_f32_e32 v32, v146, v213
	v_lshlrev_b32_e32 v66, 16, v33
	v_fmac_f32_e32 v32, v148, v66
	v_and_b32_e32 v33, 0xffff0000, v33
	v_fmac_f32_e32 v32, v149, v33
	v_lshlrev_b32_e32 v33, 16, v34
	v_fmac_f32_e32 v32, v150, v33
	v_and_b32_e32 v33, 0xffff0000, v34
	v_fmac_f32_e32 v32, v151, v33
	v_lshlrev_b32_e32 v33, 16, v35
	v_fmac_f32_e32 v32, v152, v33
	v_and_b32_e32 v33, 0xffff0000, v35
	v_fmac_f32_e32 v32, v153, v33
	v_add_f32_e32 v208, v212, v32
	v_mul_f32_e64 v32, |v208|, s88
	v_exp_f32_e32 v32, v32
	v_fmac_f32_e32 v211, 0x3377d1cf, v207
	v_fmac_f32_e32 v211, 0x3f317217, v207
	s_nop 0
	v_add_f32_e32 v32, 1.0, v32
	s_nop 0
	v_mov_b32_e32 v33, v211
	s_nop 0
	v_mov_b32_e32 v207, v33
	v_mad_u64_u32 v[66:67], s[0:1], v64, s86, v[36:37]
	s_nop 0
	s_nop 0
	v_log_f32_e32 v209, v32
	v_mad_i32_i24 v67, v65, s86, v67
	v_add_co_u32_e64 v32, s[0:1], s78, v66
	v_mul_f32_e32 v65, 0x3f317217, v209
	s_nop 0
	v_addc_co_u32_e64 v33, s[0:1], 0, v67, s[0:1]
	global_load_dwordx4 v[32:35], v[32:33], off offset:1536
	v_fma_f32 v65, v209, s90, -v65
	v_fmac_f32_e32 v65, 0x3377d1cf, v209
	v_fmac_f32_e32 v65, 0x3f317217, v209
	s_nop 0
	v_min_f32_e32 v64, 0, v208
	s_nop 0
	s_nop 0
	s_nop 0
	v_sub_f32_e32 v216, v64, v65
	v_lshl_add_u64 v[64:65], v[66:67], 0, s[70:71]
	global_load_dwordx4 v[64:67], v[64:65], off offset:16
	v_mad_u64_u32 v[208:209], s[0:1], v62, s86, v[36:37]
	v_mad_u64_u32 v[36:37], s[0:1], v38, s86, v[36:37]
	v_mad_i32_i24 v37, v39, s86, v37
	v_mad_i32_i24 v209, v63, s86, v209
	v_lshl_add_u64 v[62:63], v[208:209], 0, s[70:71]
	v_add_co_u32_e32 v208, vcc, s78, v208
	v_sub_f32_e32 v207, v210, v207
	s_nop 0
	v_addc_co_u32_e32 v209, vcc, 0, v209, vcc
	s_waitcnt vmcnt(3)
	v_and_b32_e32 v39, 0xffff0000, v80
	v_lshlrev_b32_e32 v38, 16, v80
	v_mul_f32_e32 v39, v139, v39
	v_fmac_f32_e32 v39, v138, v38
	v_lshlrev_b32_e32 v38, 16, v81
	v_fmac_f32_e32 v39, v140, v38
	v_and_b32_e32 v38, 0xffff0000, v81
	v_fmac_f32_e32 v39, v141, v38
	v_lshlrev_b32_e32 v38, 16, v82
	v_fmac_f32_e32 v39, v142, v38
	v_and_b32_e32 v38, 0xffff0000, v82
	v_fmac_f32_e32 v39, v143, v38
	v_lshlrev_b32_e32 v38, 16, v83
	v_fmac_f32_e32 v39, v144, v38
	v_and_b32_e32 v38, 0xffff0000, v83
	v_fmac_f32_e32 v39, v145, v38
	v_add_f32_e32 v38, v137, v39
	s_waitcnt vmcnt(2)
	v_lshlrev_b32_e32 v39, 16, v72
	v_and_b32_e32 v72, 0xffff0000, v72
	global_load_dwordx4 v[208:211], v[208:209], off offset:1536
	s_nop 0
	global_load_dwordx4 v[212:215], v[62:63], off offset:16
	v_mul_f32_e32 v72, v147, v72
	v_fmac_f32_e32 v72, v146, v39
	v_lshlrev_b32_e32 v39, 16, v73
	v_fmac_f32_e32 v72, v148, v39
	v_and_b32_e32 v39, 0xffff0000, v73
	v_fmac_f32_e32 v72, v149, v39
	v_lshlrev_b32_e32 v39, 16, v74
	v_fmac_f32_e32 v72, v150, v39
	v_and_b32_e32 v39, 0xffff0000, v74
	v_fmac_f32_e32 v72, v151, v39
	v_lshlrev_b32_e32 v39, 16, v75
	v_fmac_f32_e32 v72, v152, v39
	v_and_b32_e32 v39, 0xffff0000, v75
	v_fmac_f32_e32 v72, v153, v39
	v_add_f32_e32 v80, v38, v72
	v_mul_f32_e64 v38, |v80|, s88
	v_exp_f32_e32 v38, v38
	v_lshl_add_u64 v[62:63], v[36:37], 0, s[70:71]
	v_add_co_u32_e32 v36, vcc, s78, v36
	v_add_f32_e32 v38, 1.0, v38
	s_nop 0
	v_addc_co_u32_e32 v37, vcc, 0, v37, vcc
	s_nop 0
	s_nop 1
	s_nop 0
	s_nop 0
	v_log_f32_e32 v81, v38
	global_load_dwordx4 v[36:39], v[36:37], off offset:1536
	s_nop 0
	global_load_dwordx4 v[72:75], v[62:63], off offset:16
	v_min_f32_e32 v62, 0, v80
	v_mul_f32_e32 v63, 0x3f317217, v81
	v_fma_f32 v63, v81, s90, -v63
	v_fmac_f32_e32 v63, 0x3377d1cf, v81
	v_fmac_f32_e32 v63, 0x3f317217, v81
	s_waitcnt vmcnt(5)
	v_lshlrev_b32_e32 v80, 16, v32
	v_and_b32_e32 v32, 0xffff0000, v32
	v_mul_f32_e32 v32, v139, v32
	v_fmac_f32_e32 v32, v138, v80
	v_lshlrev_b32_e32 v80, 16, v33
	v_fmac_f32_e32 v32, v140, v80
	v_and_b32_e32 v33, 0xffff0000, v33
	v_fmac_f32_e32 v32, v141, v33
	v_lshlrev_b32_e32 v33, 16, v34
	v_fmac_f32_e32 v32, v142, v33
	v_and_b32_e32 v33, 0xffff0000, v34
	v_fmac_f32_e32 v32, v143, v33
	v_lshlrev_b32_e32 v33, 16, v35
	v_fmac_f32_e32 v32, v144, v33
	v_and_b32_e32 v33, 0xffff0000, v35
	s_waitcnt vmcnt(4)
	v_and_b32_e32 v34, 0xffff0000, v64
	v_fmac_f32_e32 v32, v145, v33
	v_lshlrev_b32_e32 v33, 16, v64
	v_mul_f32_e32 v34, v147, v34
	v_fmac_f32_e32 v34, v146, v33
	v_lshlrev_b32_e32 v33, 16, v65
	v_fmac_f32_e32 v34, v148, v33
	v_and_b32_e32 v33, 0xffff0000, v65
	v_fmac_f32_e32 v34, v149, v33
	v_lshlrev_b32_e32 v33, 16, v66
	v_fmac_f32_e32 v34, v150, v33
	v_and_b32_e32 v33, 0xffff0000, v66
	v_fmac_f32_e32 v34, v151, v33
	v_lshlrev_b32_e32 v33, 16, v67
	v_fmac_f32_e32 v34, v152, v33
	v_and_b32_e32 v33, 0xffff0000, v67
	v_add_f32_e32 v32, v137, v32
	v_fmac_f32_e32 v34, v153, v33
	v_add_f32_e32 v32, v32, v34
	v_mul_f32_e64 v33, |v32|, s88
	v_exp_f32_e32 v33, v33
	s_nop 0
	s_nop 0
	v_min_f32_e32 v32, 0, v32
	v_add_f32_e32 v33, 1.0, v33
	s_nop 0
	v_mov_b32_e32 v34, v63
	s_nop 0
	s_nop 0
	s_nop 0
	s_waitcnt vmcnt(3)
	v_and_b32_e32 v63, 0xffff0000, v208
	v_sub_f32_e32 v34, v62, v34
	v_lshlrev_b32_e32 v62, 16, v208
	v_mul_f32_e32 v63, v139, v63
	v_fmac_f32_e32 v63, v138, v62
	v_lshlrev_b32_e32 v62, 16, v209
	v_fmac_f32_e32 v63, v140, v62
	v_and_b32_e32 v62, 0xffff0000, v209
	v_fmac_f32_e32 v63, v141, v62
	v_lshlrev_b32_e32 v62, 16, v210
	v_fmac_f32_e32 v63, v142, v62
	v_and_b32_e32 v62, 0xffff0000, v210
	v_fmac_f32_e32 v63, v143, v62
	v_lshlrev_b32_e32 v62, 16, v211
	v_fmac_f32_e32 v63, v144, v62
	v_and_b32_e32 v62, 0xffff0000, v211
	v_log_f32_e32 v33, v33
	v_fmac_f32_e32 v63, v145, v62
	s_waitcnt vmcnt(2)
	v_and_b32_e32 v64, 0xffff0000, v212
	v_add_f32_e32 v62, v137, v63
	v_lshlrev_b32_e32 v63, 16, v212
	v_mul_f32_e32 v64, v147, v64
	v_fmac_f32_e32 v64, v146, v63
	v_lshlrev_b32_e32 v63, 16, v213
	v_fmac_f32_e32 v64, v148, v63
	v_and_b32_e32 v63, 0xffff0000, v213
	v_mul_f32_e32 v35, 0x3f317217, v33
	v_fmac_f32_e32 v64, v149, v63
	v_lshlrev_b32_e32 v63, 16, v214
	v_fma_f32 v35, v33, s90, -v35
	v_fmac_f32_e32 v64, v150, v63
	v_and_b32_e32 v63, 0xffff0000, v214
	v_fmac_f32_e32 v35, 0x3377d1cf, v33
	v_fmac_f32_e32 v64, v151, v63
	v_lshlrev_b32_e32 v63, 16, v215
	v_fmac_f32_e32 v35, 0x3f317217, v33
	v_fmac_f32_e32 v64, v152, v63
	v_and_b32_e32 v63, 0xffff0000, v215
	s_nop 0
	v_fmac_f32_e32 v64, v153, v63
	v_add_f32_e32 v62, v62, v64
	v_mov_b32_e32 v33, v35
	s_nop 0
	s_nop 0
	v_mul_f32_e64 v63, |v62|, s88
	v_sub_f32_e32 v32, v32, v33
	v_min_f32_e32 v33, 0, v62
	s_waitcnt vmcnt(1)
	v_lshlrev_b32_e32 v62, 16, v36
	v_and_b32_e32 v36, 0xffff0000, v36
	v_mul_f32_e32 v36, v139, v36
	v_fmac_f32_e32 v36, v138, v62
	v_lshlrev_b32_e32 v62, 16, v37
	v_fmac_f32_e32 v36, v140, v62
	v_and_b32_e32 v37, 0xffff0000, v37
	v_fmac_f32_e32 v36, v141, v37
	v_lshlrev_b32_e32 v37, 16, v38
	v_fmac_f32_e32 v36, v142, v37
	v_and_b32_e32 v37, 0xffff0000, v38
	v_fmac_f32_e32 v36, v143, v37
	v_lshlrev_b32_e32 v37, 16, v39
	v_fmac_f32_e32 v36, v144, v37
	v_and_b32_e32 v37, 0xffff0000, v39
	s_waitcnt vmcnt(0)
	v_and_b32_e32 v38, 0xffff0000, v72
	v_fmac_f32_e32 v36, v145, v37
	v_lshlrev_b32_e32 v37, 16, v72
	v_mul_f32_e32 v38, v147, v38
	v_fmac_f32_e32 v38, v146, v37
	v_lshlrev_b32_e32 v37, 16, v73
	v_fmac_f32_e32 v38, v148, v37
	v_and_b32_e32 v37, 0xffff0000, v73
	v_fmac_f32_e32 v38, v149, v37
	v_lshlrev_b32_e32 v37, 16, v74
	v_exp_f32_e32 v63, v63
	v_fmac_f32_e32 v38, v150, v37
	v_and_b32_e32 v37, 0xffff0000, v74
	v_fmac_f32_e32 v38, v151, v37
	v_lshlrev_b32_e32 v37, 16, v75
	v_fmac_f32_e32 v38, v152, v37
	v_and_b32_e32 v37, 0xffff0000, v75
	v_add_f32_e32 v36, v137, v36
	v_fmac_f32_e32 v38, v153, v37
	v_add_f32_e32 v63, 1.0, v63
	v_add_f32_e32 v36, v36, v38
	s_nop 0
	v_mul_f32_e64 v37, |v36|, s88
	v_exp_f32_e32 v37, v37
	s_nop 0
	s_nop 0
	v_log_f32_e32 v63, v63
	v_add_f32_e32 v37, 1.0, v37
	s_nop 0
	s_nop 0
	v_mul_f32_e32 v35, 0x3f317217, v63
	v_fma_f32 v35, v63, s90, -v35
	s_nop 0
	s_nop 0
	v_fmac_f32_e32 v35, 0x3377d1cf, v63
	v_log_f32_e32 v37, v37
	v_fmac_f32_e32 v35, 0x3f317217, v63
	s_nop 0
	s_nop 1
	s_nop 0
	s_nop 0
	v_sub_f32_e32 v33, v33, v35
	v_min_f32_e32 v35, 0, v36
	v_mul_f32_e32 v36, 0x3f317217, v37
	v_fma_f32 v36, v37, s90, -v36
	v_fmac_f32_e32 v36, 0x3377d1cf, v37
	v_fmac_f32_e32 v36, 0x3f317217, v37
	s_nop 0
	v_fmamk_f32 v38, v85, 0x3d800000, v84
	s_nop 0
	s_nop 0
	s_nop 0
	s_nop 0
	v_fmamk_f32 v37, v78, 0x3d800000, v38
	v_sub_f32_e32 v35, v35, v36
	v_fmamk_f32 v36, v79, 0x3d800000, v37
	v_fmamk_f32 v74, v76, 0x3d800000, v36
	v_fmamk_f32 v73, v77, 0x3d800000, v74
	v_fmamk_f32 v72, v70, 0x3d800000, v73
	v_fmamk_f32 v71, v71, 0x3d800000, v72
	v_fmamk_f32 v70, v68, 0x3d800000, v71
	v_fmamk_f32 v69, v69, 0x3d800000, v70
	v_fmamk_f32 v68, v207, 0x3d800000, v69
	v_fmamk_f32 v67, v216, 0x3d800000, v68
	v_fmamk_f32 v66, v34, 0x3d800000, v67
	v_fmamk_f32 v65, v32, 0x3d800000, v66
	v_fmamk_f32 v64, v33, 0x3d800000, v65
	v_fmamk_f32 v63, v35, 0x3d800000, v64
	ds_write_b32 v47, v63
	s_waitcnt lgkmcnt(0)
	s_barrier
	ds_read2st64_b32 v[34:35], v55 offset1:2
	ds_read2st64_b32 v[32:33], v55 offset0:4 offset1:6
	s_waitcnt lgkmcnt(1)
	v_add_f32_e32 v34, 0, v34
	v_add_f32_e32 v39, v34, v35
	s_waitcnt lgkmcnt(0)
	v_add_f32_e32 v39, v39, v32
	v_add_f32_e32 v62, v39, v33
	s_and_saveexec_b64 s[0:1], s[6:7]
	s_cbranch_execz .LBB0_1184
	v_mul_f32_e32 v39, 0x3fb8aa3b, v62
	v_exp_f32_e32 v39, v39
	ds_write_b32 v89, v39

.LBB0_2723:
	v_add_u32_e32 v127, s31, v103
	v_add_u32_e32 v32, 0x1ff, v127
	v_add_u32_e32 v146, s31, v104
	v_cndmask_b32_e32 v32, v32, v146, vcc
	v_ashrrev_i32_e32 v33, 31, v32
	v_lshl_add_u64 v[52:53], v[32:33], 0, s[26:27]
	v_add_u32_e32 v32, 0x1fe, v127
	v_add_u32_e32 v33, 1, v146
	v_cndmask_b32_e32 v32, v32, v33, vcc
	v_ashrrev_i32_e32 v33, 31, v32
	v_lshl_add_u64 v[128:129], v[32:33], 0, s[26:27]
	v_add_u32_e32 v32, 0x1fd, v127
	v_add_u32_e32 v33, 2, v146
	v_add_u32_e32 v34, 0x1fc, v127
	v_add_u32_e32 v35, 3, v146
	v_cndmask_b32_e32 v32, v32, v33, vcc
	v_cndmask_b32_e32 v34, v34, v35, vcc
	v_ashrrev_i32_e32 v33, 31, v32
	v_ashrrev_i32_e32 v35, 31, v34
	v_mad_u64_u32 v[50:51], s[0:1], v52, s49, v[48:49]
	v_lshl_add_u64 v[32:33], v[32:33], 0, s[26:27]
	v_lshl_add_u64 v[34:35], v[34:35], 0, s[26:27]
	v_mad_i32_i24 v51, v53, s49, v51
	v_mad_u64_u32 v[54:55], s[0:1], v128, s49, v[48:49]
	v_mad_u64_u32 v[56:57], s[0:1], v32, s49, v[48:49]
	v_mad_u64_u32 v[58:59], s[0:1], v34, s49, v[48:49]
	v_mad_i32_i24 v55, v129, s49, v55
	v_mad_i32_i24 v57, v33, s49, v57
	v_mad_i32_i24 v59, v35, s49, v59
	global_load_ushort v108, v[50:51], off offset:1024
	global_load_ushort v111, v[50:51], off offset:2048
	global_load_ushort v106, v[54:55], off offset:1024
	global_load_ushort v112, v[54:55], off offset:2048
	global_load_ushort v110, v[56:57], off offset:1024
	global_load_ushort v105, v[56:57], off offset:2048
	global_load_ushort v109, v[58:59], off offset:1024
	global_load_ushort v107, v[58:59], off offset:2048
	v_add_u32_e32 v50, 0x1fb, v127
	v_add_u32_e32 v51, 4, v146
	v_cndmask_b32_e32 v50, v50, v51, vcc
	v_add_u32_e32 v54, 0x1fa, v127
	v_add_u32_e32 v55, 5, v146
	v_add_u32_e32 v56, 0x1f9, v127
	v_add_u32_e32 v57, 6, v146
	v_add_u32_e32 v58, 0x1f8, v127
	v_add_u32_e32 v59, 7, v146
	v_ashrrev_i32_e32 v51, 31, v50
	v_cndmask_b32_e32 v54, v54, v55, vcc
	v_cndmask_b32_e32 v56, v56, v57, vcc
	v_cndmask_b32_e32 v58, v58, v59, vcc
	v_lshl_add_u64 v[74:75], v[50:51], 0, s[26:27]
	v_ashrrev_i32_e32 v55, 31, v54
	v_ashrrev_i32_e32 v57, 31, v56
	v_ashrrev_i32_e32 v59, 31, v58
	v_mad_u64_u32 v[50:51], s[0:1], v74, s49, v[48:49]
	v_lshl_add_u64 v[72:73], v[54:55], 0, s[26:27]
	v_lshl_add_u64 v[68:69], v[56:57], 0, s[26:27]
	v_lshl_add_u64 v[70:71], v[58:59], 0, s[26:27]
	v_mad_i32_i24 v51, v75, s49, v51
	v_mad_u64_u32 v[54:55], s[0:1], v72, s49, v[48:49]
	v_mad_u64_u32 v[56:57], s[0:1], v68, s49, v[48:49]
	v_mad_u64_u32 v[58:59], s[0:1], v70, s49, v[48:49]
	v_mad_i32_i24 v55, v73, s49, v55
	v_mad_i32_i24 v57, v69, s49, v57
	v_mad_i32_i24 v59, v71, s49, v59
	global_load_ushort v116, v[50:51], off offset:1024
	global_load_ushort v119, v[50:51], off offset:2048
	global_load_ushort v114, v[54:55], off offset:1024
	global_load_ushort v120, v[54:55], off offset:2048
	global_load_ushort v118, v[56:57], off offset:1024
	global_load_ushort v113, v[56:57], off offset:2048
	global_load_ushort v117, v[58:59], off offset:1024
	global_load_ushort v115, v[58:59], off offset:2048
	v_add_u32_e32 v50, 0x1f7, v127
	v_add_u32_e32 v51, 8, v146
	v_cndmask_b32_e32 v50, v50, v51, vcc
	v_ashrrev_i32_e32 v51, 31, v50
	v_lshl_add_u64 v[64:65], v[50:51], 0, s[26:27]
	v_add_u32_e32 v50, 0x1f6, v127
	v_add_u32_e32 v51, 9, v146
	v_cndmask_b32_e32 v50, v50, v51, vcc
	v_ashrrev_i32_e32 v51, 31, v50
	v_lshl_add_u64 v[62:63], v[50:51], 0, s[26:27]
	v_add_u32_e32 v50, 0x1f5, v127
	v_add_u32_e32 v51, 10, v146
	v_cndmask_b32_e32 v50, v50, v51, vcc
	v_ashrrev_i32_e32 v51, 31, v50
	v_lshl_add_u64 v[60:61], v[50:51], 0, s[26:27]
	v_add_u32_e32 v50, 0x1f4, v127
	v_add_u32_e32 v51, 11, v146
	v_cndmask_b32_e32 v66, v50, v51, vcc
	v_mov_b64_e32 v[50:51], s[34:35]
	v_mad_u64_u32 v[54:55], s[0:1], v64, s49, v[48:49]
	v_mad_u64_u32 v[56:57], s[0:1], v62, s49, v[48:49]
	v_mad_u64_u32 v[58:59], s[0:1], v60, s49, v[48:49]
	v_mad_u64_u32 v[132:133], s[0:1], v52, s49, v[50:51]
	v_mad_i32_i24 v133, v53, s49, v133
	v_add_co_u32_e64 v52, s[0:1], s40, v132
	v_ashrrev_i32_e32 v67, 31, v66
	s_nop 0
	v_addc_co_u32_e64 v53, s[0:1], 0, v133, s[0:1]
	global_load_dwordx4 v[138:141], v[52:53], off offset:1536
	v_lshl_add_u64 v[66:67], v[66:67], 0, s[26:27]
	v_mad_u64_u32 v[52:53], s[0:1], v66, s49, v[48:49]
	v_mad_i32_i24 v55, v65, s49, v55
	v_mad_i32_i24 v53, v67, s49, v53
	v_mad_i32_i24 v57, v63, s49, v57
	v_mad_i32_i24 v59, v61, s49, v59
	global_load_ushort v124, v[54:55], off offset:1024
	global_load_ushort v130, v[54:55], off offset:2048
	global_load_ushort v123, v[56:57], off offset:1024
	global_load_ushort v131, v[56:57], off offset:2048
	global_load_ushort v126, v[58:59], off offset:1024
	global_load_ushort v121, v[58:59], off offset:2048
	global_load_ushort v125, v[52:53], off offset:1024
	global_load_ushort v122, v[52:53], off offset:2048
	v_lshl_add_u64 v[52:53], v[132:133], 0, s[28:29]
	global_load_dwordx4 v[142:145], v[52:53], off offset:16
	v_add_u32_e32 v54, 0x1f3, v127
	v_add_u32_e32 v55, 12, v146
	v_cndmask_b32_e32 v52, v54, v55, vcc
	v_ashrrev_i32_e32 v53, 31, v52
	v_lshl_add_u64 v[58:59], v[52:53], 0, s[26:27]
	v_add_u32_e32 v52, 0x1f2, v127
	v_add_u32_e32 v53, 13, v146
	v_cndmask_b32_e32 v52, v52, v53, vcc
	v_ashrrev_i32_e32 v53, 31, v52
	v_lshl_add_u64 v[56:57], v[52:53], 0, s[26:27]
	v_add_u32_e32 v52, 0x1f1, v127
	v_add_u32_e32 v53, 14, v146
	v_cndmask_b32_e32 v52, v52, v53, vcc
	v_ashrrev_i32_e32 v53, 31, v52
	v_lshl_add_u64 v[54:55], v[52:53], 0, s[26:27]
	v_mad_u64_u32 v[134:135], s[0:1], v58, s49, v[48:49]
	v_mad_u64_u32 v[136:137], s[0:1], v56, s49, v[48:49]
	v_mad_u64_u32 v[150:151], s[0:1], v54, s49, v[48:49]
	v_mad_u64_u32 v[152:153], s[0:1], v128, s49, v[50:51]
	v_mad_i32_i24 v153, v129, s49, v153
	v_add_co_u32_e64 v128, s[0:1], s40, v152
	v_add_u32_e32 v53, 15, v146
	s_nop 0
	v_addc_co_u32_e64 v129, s[0:1], 0, v153, s[0:1]
	global_load_dwordx4 v[146:149], v[128:129], off offset:1536
	v_add_u32_e32 v52, 0x1f0, v127
	v_cndmask_b32_e32 v52, v52, v53, vcc
	v_ashrrev_i32_e32 v53, 31, v52
	v_lshl_add_u64 v[52:53], v[52:53], 0, s[26:27]
	v_mad_i32_i24 v135, v59, s49, v135
	v_mad_i32_i24 v151, v55, s49, v151
	v_mad_u64_u32 v[154:155], s[0:1], v52, s49, v[48:49]
	v_mad_i32_i24 v137, v57, s49, v137
	v_mad_i32_i24 v155, v53, s49, v155
	global_load_ushort v132, v[134:135], off offset:1024
	s_nop 0
	global_load_ushort v135, v[134:135], off offset:2048
	s_nop 0
	global_load_ushort v129, v[136:137], off offset:1024
	s_nop 0
	global_load_ushort v136, v[136:137], off offset:2048
	s_nop 0
	global_load_ushort v134, v[150:151], off offset:1024
	global_load_ushort v127, v[150:151], off offset:2048
	global_load_ushort v133, v[154:155], off offset:1024
	global_load_ushort v128, v[154:155], off offset:2048
	v_lshl_add_u64 v[150:151], v[152:153], 0, s[28:29]
	global_load_dwordx4 v[150:153], v[150:151], off offset:16
	v_mad_u64_u32 v[154:155], s[0:1], v32, s49, v[50:51]
	v_mad_i32_i24 v155, v33, s49, v155
	v_lshl_add_u64 v[32:33], v[154:155], 0, s[28:29]
	v_add_co_u32_e64 v154, s[0:1], s40, v154
	s_waitcnt vmcnt(0)
	v_lshlrev_b32_e32 v137, 16, v138
	v_addc_co_u32_e64 v155, s[0:1], 0, v155, s[0:1]
	global_load_dwordx4 v[154:157], v[154:155], off offset:1536
	s_nop 0
	global_load_dwordx4 v[158:161], v[32:33], off offset:16
	v_and_b32_e32 v138, 0xffff0000, v138
	s_waitcnt lgkmcnt(0)
	v_mul_f32_e32 v138, v88, v138
	v_fmac_f32_e32 v138, v87, v137
	v_lshlrev_b32_e32 v137, 16, v139
	v_fmac_f32_e32 v138, v89, v137
	v_and_b32_e32 v137, 0xffff0000, v139
	v_fmac_f32_e32 v138, v90, v137
	v_lshlrev_b32_e32 v137, 16, v140
	v_fmac_f32_e32 v138, v91, v137
	v_and_b32_e32 v137, 0xffff0000, v140
	v_fmac_f32_e32 v138, v92, v137
	v_lshlrev_b32_e32 v137, 16, v141
	v_mad_u64_u32 v[32:33], s[0:1], v34, s49, v[50:51]
	v_fmac_f32_e32 v138, v93, v137
	v_and_b32_e32 v137, 0xffff0000, v141
	v_mad_i32_i24 v33, v35, s49, v33
	v_fmac_f32_e32 v138, v94, v137
	v_and_b32_e32 v139, 0xffff0000, v142
	v_lshl_add_u64 v[34:35], v[32:33], 0, s[28:29]
	v_add_f32_e32 v137, v86, v138
	v_lshlrev_b32_e32 v138, 16, v142
	v_mul_f32_e32 v139, v96, v139
	v_add_co_u32_e64 v32, s[0:1], s40, v32
	v_fmac_f32_e32 v139, v95, v138
	v_lshlrev_b32_e32 v138, 16, v143
	v_addc_co_u32_e64 v33, s[0:1], 0, v33, s[0:1]
	v_fmac_f32_e32 v139, v97, v138
	v_and_b32_e32 v138, 0xffff0000, v143
	global_load_dwordx4 v[140:143], v[32:33], off offset:1536
	s_nop 0
	global_load_dwordx4 v[32:35], v[34:35], off offset:16
	v_fmac_f32_e32 v139, v98, v138
	v_lshlrev_b32_e32 v138, 16, v144
	v_fmac_f32_e32 v139, v99, v138
	v_and_b32_e32 v138, 0xffff0000, v144
	v_fmac_f32_e32 v139, v100, v138
	v_lshlrev_b32_e32 v138, 16, v145
	v_fmac_f32_e32 v139, v101, v138
	v_and_b32_e32 v138, 0xffff0000, v145
	v_and_b32_e32 v145, 0xffff0000, v146
	v_lshlrev_b32_e32 v144, 16, v146
	v_mul_f32_e32 v145, v88, v145
	v_fmac_f32_e32 v145, v87, v144
	v_lshlrev_b32_e32 v144, 16, v147
	v_fmac_f32_e32 v139, v102, v138
	v_fmac_f32_e32 v145, v89, v144
	v_and_b32_e32 v144, 0xffff0000, v147
	v_add_f32_e32 v137, v137, v139
	v_fmac_f32_e32 v145, v90, v144
	v_lshlrev_b32_e32 v144, 16, v148
	v_mul_f32_e64 v138, |v137|, s51
	v_fmac_f32_e32 v145, v91, v144
	v_and_b32_e32 v144, 0xffff0000, v148
	v_exp_f32_e32 v138, v138
	v_fmac_f32_e32 v145, v92, v144
	v_lshlrev_b32_e32 v144, 16, v149
	v_fmac_f32_e32 v145, v93, v144
	v_and_b32_e32 v144, 0xffff0000, v149
	v_fmac_f32_e32 v145, v94, v144
	v_and_b32_e32 v146, 0xffff0000, v150
	v_add_f32_e32 v144, v86, v145
	v_lshlrev_b32_e32 v145, 16, v150
	v_mul_f32_e32 v146, v96, v146
	v_add_f32_e32 v138, 1.0, v138
	v_fmac_f32_e32 v146, v95, v145
	v_lshlrev_b32_e32 v145, 16, v151
	s_nop 0
	v_fmac_f32_e32 v146, v97, v145
	v_and_b32_e32 v145, 0xffff0000, v151
	s_nop 0
	v_fmac_f32_e32 v146, v98, v145
	v_lshlrev_b32_e32 v145, 16, v152
	s_nop 0
	v_fmac_f32_e32 v146, v99, v145
	v_and_b32_e32 v145, 0xffff0000, v152
	v_log_f32_e32 v138, v138
	v_fmac_f32_e32 v146, v100, v145
	v_lshlrev_b32_e32 v145, 16, v153
	v_fmac_f32_e32 v146, v101, v145
	v_and_b32_e32 v145, 0xffff0000, v153
	v_fmac_f32_e32 v146, v102, v145
	v_add_f32_e32 v144, v144, v146
	v_mul_f32_e32 v139, 0x3f317217, v138
	v_mul_f32_e64 v145, |v144|, s51
	v_fma_f32 v139, v138, s53, -v139
	v_exp_f32_e32 v145, v145
	v_fmac_f32_e32 v139, 0x3377d1cf, v138
	v_fmac_f32_e32 v139, 0x3f317217, v138
	s_nop 0
	s_waitcnt vmcnt(3)
	v_and_b32_e32 v146, 0xffff0000, v154
	v_mul_f32_e32 v146, v88, v146
	v_mov_b32_e32 v138, v139
	s_nop 0
	s_nop 0
	v_add_f32_e32 v139, 1.0, v145
	s_nop 0
	s_waitcnt vmcnt(2)
	v_and_b32_e32 v147, 0xffff0000, v158
	v_mul_f32_e32 v147, v96, v147
	s_nop 0
	s_nop 0
	v_lshlrev_b32_e32 v145, 16, v154
	v_fmac_f32_e32 v146, v87, v145
	v_lshlrev_b32_e32 v145, 16, v155
	v_fmac_f32_e32 v146, v89, v145
	v_and_b32_e32 v145, 0xffff0000, v155
	v_fmac_f32_e32 v146, v90, v145
	v_lshlrev_b32_e32 v145, 16, v156
	v_fmac_f32_e32 v146, v91, v145
	v_and_b32_e32 v145, 0xffff0000, v156
	v_fmac_f32_e32 v146, v92, v145
	v_lshlrev_b32_e32 v145, 16, v157
	v_fmac_f32_e32 v146, v93, v145
	v_and_b32_e32 v145, 0xffff0000, v157
	v_fmac_f32_e32 v146, v94, v145
	v_add_f32_e32 v145, v86, v146
	v_lshlrev_b32_e32 v146, 16, v158
	v_fmac_f32_e32 v147, v95, v146
	v_lshlrev_b32_e32 v146, 16, v159
	v_fmac_f32_e32 v147, v97, v146
	v_and_b32_e32 v146, 0xffff0000, v159
	v_fmac_f32_e32 v147, v98, v146
	v_lshlrev_b32_e32 v146, 16, v160
	v_fmac_f32_e32 v147, v99, v146
	v_and_b32_e32 v146, 0xffff0000, v160
	v_fmac_f32_e32 v147, v100, v146
	v_lshlrev_b32_e32 v146, 16, v161
	v_fmac_f32_e32 v147, v101, v146
	v_and_b32_e32 v146, 0xffff0000, v161
	v_log_f32_e32 v139, v139
	v_fmac_f32_e32 v147, v102, v146
	v_add_f32_e32 v145, v145, v147
	v_mul_f32_e64 v146, |v145|, s51
	v_min_f32_e32 v137, 0, v137
	v_exp_f32_e32 v146, v146
	v_sub_f32_e32 v137, v137, v138
	v_min_f32_e32 v138, 0, v144
	v_mul_f32_e32 v144, 0x3f317217, v139
	v_fma_f32 v144, v139, s53, -v144
	v_fmac_f32_e32 v144, 0x3377d1cf, v139
	v_fmac_f32_e32 v144, 0x3f317217, v139
	s_nop 0
	v_add_f32_e32 v146, 1.0, v146
	s_waitcnt vmcnt(1)
	v_lshlrev_b32_e32 v152, 16, v140
	v_mov_b32_e32 v139, v144
	s_nop 0
	s_nop 0
	v_mad_u64_u32 v[148:149], s[20:21], v74, s49, v[50:51]
	s_nop 0
	s_nop 0
	s_nop 0
	v_log_f32_e32 v150, v146
	v_mad_i32_i24 v149, v75, s49, v149
	v_add_co_u32_e64 v74, s[20:21], s40, v148
	s_nop 0
	v_mul_f32_e32 v144, 0x3f317217, v150
	v_and_b32_e32 v140, 0xffff0000, v140
	v_addc_co_u32_e64 v75, s[20:21], 0, v149, s[20:21]
	v_sub_f32_e32 v138, v138, v139
	v_min_f32_e32 v139, 0, v145
	v_fma_f32 v151, v150, s53, -v144
	v_mul_f32_e32 v140, v88, v140
	global_load_dwordx4 v[144:147], v[74:75], off offset:1536
	v_fmac_f32_e32 v140, v87, v152
	v_lshlrev_b32_e32 v74, 16, v141
	v_fmac_f32_e32 v140, v89, v74
	v_and_b32_e32 v74, 0xffff0000, v141
	v_fmac_f32_e32 v140, v90, v74
	v_lshlrev_b32_e32 v74, 16, v142
	v_fmac_f32_e32 v140, v91, v74
	v_and_b32_e32 v74, 0xffff0000, v142
	v_fmac_f32_e32 v140, v92, v74
	v_lshlrev_b32_e32 v74, 16, v143
	v_fmac_f32_e32 v140, v93, v74
	v_and_b32_e32 v74, 0xffff0000, v143
	v_fmac_f32_e32 v140, v94, v74
	v_lshl_add_u64 v[74:75], v[148:149], 0, s[28:29]
	v_add_f32_e32 v152, v86, v140
	global_load_dwordx4 v[140:143], v[74:75], off offset:16
	s_waitcnt vmcnt(2)
	v_lshlrev_b32_e32 v153, 16, v32
	v_and_b32_e32 v32, 0xffff0000, v32
	v_mul_f32_e32 v32, v96, v32
	v_fmac_f32_e32 v32, v95, v153
	v_lshlrev_b32_e32 v74, 16, v33
	v_fmac_f32_e32 v32, v97, v74
	v_and_b32_e32 v33, 0xffff0000, v33
	v_fmac_f32_e32 v32, v98, v33
	v_lshlrev_b32_e32 v33, 16, v34
	v_fmac_f32_e32 v32, v99, v33
	v_and_b32_e32 v33, 0xffff0000, v34
	v_fmac_f32_e32 v32, v100, v33
	v_lshlrev_b32_e32 v33, 16, v35
	v_fmac_f32_e32 v32, v101, v33
	v_and_b32_e32 v33, 0xffff0000, v35
	v_fmac_f32_e32 v32, v102, v33
	v_add_f32_e32 v74, v152, v32
	v_mul_f32_e64 v32, |v74|, s51
	v_exp_f32_e32 v32, v32
	v_fmac_f32_e32 v151, 0x3377d1cf, v150
	v_fmac_f32_e32 v151, 0x3f317217, v150
	s_nop 0
	v_add_f32_e32 v32, 1.0, v32
	s_nop 0
	v_mov_b32_e32 v33, v151
	s_nop 0
	v_mov_b32_e32 v75, v33
	v_mul_f32_e32 v137, 0x3d800000, v137
	s_nop 0
	s_nop 0
	v_log_f32_e32 v152, v32
	v_mad_u64_u32 v[32:33], s[20:21], v72, s49, v[50:51]
	v_mad_i32_i24 v33, v73, s49, v33
	v_add_co_u32_e64 v34, s[20:21], s40, v32
	s_nop 0
	s_nop 0
	v_addc_co_u32_e64 v35, s[20:21], 0, v33, s[20:21]
	global_load_dwordx4 v[148:151], v[34:35], off offset:1536
	v_mul_f32_e32 v35, 0x3f317217, v152
	v_fma_f32 v35, v152, s53, -v35
	v_fmac_f32_e32 v35, 0x3377d1cf, v152
	v_fmac_f32_e32 v35, 0x3f317217, v152
	s_nop 0
	v_lshl_add_u64 v[32:33], v[32:33], 0, s[28:29]
	v_min_f32_e32 v34, 0, v74
	s_nop 0
	global_load_dwordx4 v[152:155], v[32:33], off offset:16
	v_mad_u64_u32 v[32:33], s[0:1], v68, s49, v[50:51]
	s_nop 0
	v_mad_i32_i24 v33, v69, s49, v33
	v_sub_f32_e32 v73, v34, v35
	v_lshl_add_u64 v[34:35], v[32:33], 0, s[28:29]
	v_add_co_u32_e64 v32, s[0:1], s40, v32
	v_sub_f32_e32 v72, v139, v75
	s_nop 0
	v_addc_co_u32_e64 v33, s[0:1], 0, v33, s[0:1]
	global_load_dwordx4 v[156:159], v[32:33], off offset:1536
	global_load_dwordx4 v[160:163], v[34:35], off offset:16
	v_mad_u64_u32 v[32:33], s[0:1], v70, s49, v[50:51]
	s_waitcnt vmcnt(5)
	v_and_b32_e32 v69, 0xffff0000, v144
	v_lshlrev_b32_e32 v68, 16, v144
	v_mul_f32_e32 v69, v88, v69
	v_fmac_f32_e32 v69, v87, v68
	v_lshlrev_b32_e32 v68, 16, v145
	v_fmac_f32_e32 v69, v89, v68
	v_and_b32_e32 v68, 0xffff0000, v145
	v_fmac_f32_e32 v69, v90, v68
	v_lshlrev_b32_e32 v68, 16, v146
	v_fmac_f32_e32 v69, v91, v68
	v_and_b32_e32 v68, 0xffff0000, v146
	v_fmac_f32_e32 v69, v92, v68
	v_lshlrev_b32_e32 v68, 16, v147
	v_fmac_f32_e32 v69, v93, v68
	v_and_b32_e32 v68, 0xffff0000, v147
	v_fmac_f32_e32 v69, v94, v68
	s_waitcnt vmcnt(4)
	v_and_b32_e32 v70, 0xffff0000, v140
	v_add_f32_e32 v68, v86, v69
	v_lshlrev_b32_e32 v69, 16, v140
	v_mul_f32_e32 v70, v96, v70
	v_fmac_f32_e32 v70, v95, v69
	v_lshlrev_b32_e32 v69, 16, v141
	v_fmac_f32_e32 v70, v97, v69
	v_and_b32_e32 v69, 0xffff0000, v141
	v_mad_i32_i24 v33, v71, s49, v33
	v_fmac_f32_e32 v70, v98, v69
	v_lshlrev_b32_e32 v69, 16, v142
	v_lshl_add_u64 v[34:35], v[32:33], 0, s[28:29]
	v_fmac_f32_e32 v70, v99, v69
	v_and_b32_e32 v69, 0xffff0000, v142
	v_add_co_u32_e64 v32, s[0:1], s40, v32
	v_fmac_f32_e32 v70, v100, v69
	v_lshlrev_b32_e32 v69, 16, v143
	v_addc_co_u32_e64 v33, s[0:1], 0, v33, s[0:1]
	v_fmac_f32_e32 v70, v101, v69
	v_and_b32_e32 v69, 0xffff0000, v143
	global_load_dwordx4 v[140:143], v[32:33], off offset:1536
	s_nop 0
	global_load_dwordx4 v[32:35], v[34:35], off offset:16
	v_fmac_f32_e32 v70, v102, v69
	v_add_f32_e32 v68, v68, v70
	v_mul_f32_e64 v69, |v68|, s51
	v_exp_f32_e32 v69, v69
	v_min_f32_e32 v68, 0, v68
	v_add_f32_e32 v69, 1.0, v69
	s_nop 0
	s_waitcnt vmcnt(5)
	v_and_b32_e32 v74, 0xffff0000, v148
	v_lshlrev_b32_e32 v71, 16, v148
	v_mul_f32_e32 v74, v88, v74
	v_fmac_f32_e32 v74, v87, v71
	v_lshlrev_b32_e32 v71, 16, v149
	v_fmac_f32_e32 v74, v89, v71
	v_and_b32_e32 v71, 0xffff0000, v149
	v_fmac_f32_e32 v74, v90, v71
	v_lshlrev_b32_e32 v71, 16, v150
	v_fmac_f32_e32 v74, v91, v71
	v_and_b32_e32 v71, 0xffff0000, v150
	v_fmac_f32_e32 v74, v92, v71
	v_lshlrev_b32_e32 v71, 16, v151
	v_fmac_f32_e32 v74, v93, v71
	v_and_b32_e32 v71, 0xffff0000, v151
	v_fmac_f32_e32 v74, v94, v71
	s_waitcnt vmcnt(4)
	v_and_b32_e32 v75, 0xffff0000, v152
	v_add_f32_e32 v71, v86, v74
	v_lshlrev_b32_e32 v74, 16, v152
	v_mul_f32_e32 v75, v96, v75
	v_fmac_f32_e32 v75, v95, v74
	v_lshlrev_b32_e32 v74, 16, v153
	v_fmac_f32_e32 v75, v97, v74
	v_and_b32_e32 v74, 0xffff0000, v153
	v_fmac_f32_e32 v75, v98, v74
	v_lshlrev_b32_e32 v74, 16, v154
	v_fmac_f32_e32 v75, v99, v74
	v_and_b32_e32 v74, 0xffff0000, v154
	s_nop 0
	v_fmac_f32_e32 v75, v100, v74
	v_lshlrev_b32_e32 v74, 16, v155
	s_nop 0
	v_fmac_f32_e32 v75, v101, v74
	v_and_b32_e32 v74, 0xffff0000, v155
	v_log_f32_e32 v69, v69
	v_fmac_f32_e32 v75, v102, v74
	v_add_f32_e32 v71, v71, v75
	v_mul_f32_e64 v74, |v71|, s51
	v_exp_f32_e32 v74, v74
	v_mul_f32_e32 v70, 0x3f317217, v69
	v_fma_f32 v70, v69, s53, -v70
	v_fmac_f32_e32 v70, 0x3377d1cf, v69
	v_fmac_f32_e32 v70, 0x3f317217, v69
	s_nop 0
	v_add_f32_e32 v74, 1.0, v74
	s_waitcnt vmcnt(2)
	v_and_b32_e32 v139, 0xffff0000, v160
	v_mov_b32_e32 v69, v70
	s_nop 0
	s_nop 0
	s_nop 0
	v_sub_f32_e32 v68, v68, v69
	s_nop 0
	s_nop 0
	v_and_b32_e32 v75, 0xffff0000, v156
	v_min_f32_e32 v69, 0, v71
	v_lshlrev_b32_e32 v71, 16, v156
	v_mul_f32_e32 v75, v88, v75
	v_fmac_f32_e32 v75, v87, v71
	v_lshlrev_b32_e32 v71, 16, v157
	v_fmac_f32_e32 v75, v89, v71
	v_and_b32_e32 v71, 0xffff0000, v157
	v_fmac_f32_e32 v75, v90, v71
	v_lshlrev_b32_e32 v71, 16, v158
	v_fmac_f32_e32 v75, v91, v71
	v_and_b32_e32 v71, 0xffff0000, v158
	v_fmac_f32_e32 v75, v92, v71
	v_lshlrev_b32_e32 v71, 16, v159
	v_fmac_f32_e32 v75, v93, v71
	v_and_b32_e32 v71, 0xffff0000, v159
	v_fmac_f32_e32 v75, v94, v71
	v_add_f32_e32 v71, v86, v75
	v_lshlrev_b32_e32 v75, 16, v160
	v_mul_f32_e32 v139, v96, v139
	v_fmac_f32_e32 v139, v95, v75
	v_lshlrev_b32_e32 v75, 16, v161
	v_fmac_f32_e32 v139, v97, v75
	v_and_b32_e32 v75, 0xffff0000, v161
	v_fmac_f32_e32 v139, v98, v75
	v_lshlrev_b32_e32 v75, 16, v162
	v_fmac_f32_e32 v139, v99, v75
	v_and_b32_e32 v75, 0xffff0000, v162
	v_fmac_f32_e32 v139, v100, v75
	v_lshlrev_b32_e32 v75, 16, v163
	v_fmac_f32_e32 v139, v101, v75
	v_and_b32_e32 v75, 0xffff0000, v163
	v_log_f32_e32 v74, v74
	v_fmac_f32_e32 v139, v102, v75
	v_add_f32_e32 v71, v71, v139
	v_mul_f32_e64 v75, |v71|, s51
	v_exp_f32_e32 v75, v75
	v_mul_f32_e32 v70, 0x3f317217, v74
	v_fma_f32 v70, v74, s53, -v70
	v_fmac_f32_e32 v70, 0x3377d1cf, v74
	v_fmac_f32_e32 v70, 0x3f317217, v74
	s_nop 0
	v_add_f32_e32 v75, 1.0, v75
	s_waitcnt vmcnt(1)
	v_lshlrev_b32_e32 v148, 16, v140
	s_nop 0
	s_nop 0
	s_nop 0
	s_nop 0
	v_sub_f32_e32 v69, v69, v70
	s_nop 0
	s_nop 0
	v_log_f32_e32 v75, v75
	v_min_f32_e32 v74, 0, v71
	s_waitcnt vmcnt(0)
	v_lshlrev_b32_e32 v149, 16, v32
	v_and_b32_e32 v32, 0xffff0000, v32
	v_mul_f32_e32 v70, 0x3f317217, v75
	v_fma_f32 v139, v75, s53, -v70
	v_and_b32_e32 v70, 0xffff0000, v140
	v_mul_f32_e32 v140, v88, v70
	v_mad_u64_u32 v[70:71], s[20:21], v64, s49, v[50:51]
	v_mad_i32_i24 v71, v65, s49, v71
	v_add_co_u32_e64 v64, s[20:21], s40, v70
	v_fmac_f32_e32 v140, v87, v148
	s_nop 0
	v_addc_co_u32_e64 v65, s[20:21], 0, v71, s[20:21]
	global_load_dwordx4 v[144:147], v[64:65], off offset:1536
	v_lshlrev_b32_e32 v64, 16, v141
	v_fmac_f32_e32 v140, v89, v64
	v_and_b32_e32 v64, 0xffff0000, v141
	v_fmac_f32_e32 v140, v90, v64
	v_lshlrev_b32_e32 v64, 16, v142
	v_fmac_f32_e32 v140, v91, v64
	v_and_b32_e32 v64, 0xffff0000, v142
	v_fmac_f32_e32 v140, v92, v64
	v_lshlrev_b32_e32 v64, 16, v143
	v_fmac_f32_e32 v140, v93, v64
	v_and_b32_e32 v64, 0xffff0000, v143
	v_fmac_f32_e32 v140, v94, v64
	v_lshl_add_u64 v[64:65], v[70:71], 0, s[28:29]
	v_add_f32_e32 v148, v86, v140
	global_load_dwordx4 v[140:143], v[64:65], off offset:16
	v_mul_f32_e32 v32, v96, v32
	v_fmac_f32_e32 v32, v95, v149
	v_lshlrev_b32_e32 v64, 16, v33
	v_fmac_f32_e32 v32, v97, v64
	v_and_b32_e32 v33, 0xffff0000, v33
	v_fmac_f32_e32 v32, v98, v33
	v_lshlrev_b32_e32 v33, 16, v34
	v_fmac_f32_e32 v32, v99, v33
	v_and_b32_e32 v33, 0xffff0000, v34
	v_fmac_f32_e32 v32, v100, v33
	v_lshlrev_b32_e32 v33, 16, v35
	v_fmac_f32_e32 v32, v101, v33
	v_and_b32_e32 v33, 0xffff0000, v35
	v_fmac_f32_e32 v32, v102, v33
	v_add_f32_e32 v64, v148, v32
	v_mul_f32_e64 v32, |v64|, s51
	v_exp_f32_e32 v32, v32
	v_fmac_f32_e32 v139, 0x3377d1cf, v75
	v_fmac_f32_e32 v139, 0x3f317217, v75
	s_nop 0
	v_add_f32_e32 v32, 1.0, v32
	s_nop 0
	v_mov_b32_e32 v33, v139
	s_nop 0
	v_mov_b32_e32 v65, v33
	s_nop 0
	s_nop 0
	s_nop 0
	v_log_f32_e32 v70, v32
	v_mad_u64_u32 v[32:33], s[20:21], v62, s49, v[50:51]
	v_mad_i32_i24 v33, v63, s49, v33
	v_add_co_u32_e64 v34, s[20:21], s40, v32
	s_nop 0
	s_nop 0
	v_addc_co_u32_e64 v35, s[20:21], 0, v33, s[20:21]
	global_load_dwordx4 v[148:151], v[34:35], off offset:1536
	v_lshl_add_u64 v[32:33], v[32:33], 0, s[28:29]
	global_load_dwordx4 v[152:155], v[32:33], off offset:16
	v_mul_f32_e32 v35, 0x3f317217, v70
	v_fma_f32 v35, v70, s53, -v35
	v_fmac_f32_e32 v35, 0x3377d1cf, v70
	v_fmac_f32_e32 v35, 0x3f317217, v70
	s_nop 0
	v_mad_u64_u32 v[32:33], s[0:1], v60, s49, v[50:51]
	s_nop 0
	s_nop 0
	v_min_f32_e32 v34, 0, v64
	s_nop 0
	v_mad_i32_i24 v33, v61, s49, v33
	v_sub_f32_e32 v63, v34, v35
	v_lshl_add_u64 v[34:35], v[32:33], 0, s[28:29]
	v_add_co_u32_e64 v32, s[0:1], s40, v32
	v_sub_f32_e32 v62, v74, v65
	s_nop 0
	v_addc_co_u32_e64 v33, s[0:1], 0, v33, s[0:1]
	global_load_dwordx4 v[156:159], v[32:33], off offset:1536
	global_load_dwordx4 v[160:163], v[34:35], off offset:16
	v_mad_u64_u32 v[32:33], s[0:1], v66, s49, v[50:51]
	v_mad_i32_i24 v33, v67, s49, v33
	v_lshl_add_u64 v[34:35], v[32:33], 0, s[28:29]
	v_add_co_u32_e64 v32, s[0:1], s40, v32
	s_waitcnt vmcnt(5)
	v_and_b32_e32 v61, 0xffff0000, v144
	v_lshlrev_b32_e32 v60, 16, v144
	v_mul_f32_e32 v61, v88, v61
	v_fmac_f32_e32 v61, v87, v60
	v_lshlrev_b32_e32 v60, 16, v145
	v_fmac_f32_e32 v61, v89, v60
	v_and_b32_e32 v60, 0xffff0000, v145
	v_fmac_f32_e32 v61, v90, v60
	v_lshlrev_b32_e32 v60, 16, v146
	v_fmac_f32_e32 v61, v91, v60
	v_and_b32_e32 v60, 0xffff0000, v146
	v_fmac_f32_e32 v61, v92, v60
	v_lshlrev_b32_e32 v60, 16, v147
	v_fmac_f32_e32 v61, v93, v60
	v_and_b32_e32 v60, 0xffff0000, v147
	v_fmac_f32_e32 v61, v94, v60
	s_waitcnt vmcnt(4)
	v_and_b32_e32 v64, 0xffff0000, v140
	v_add_f32_e32 v60, v86, v61
	v_lshlrev_b32_e32 v61, 16, v140
	v_mul_f32_e32 v64, v96, v64
	v_fmac_f32_e32 v64, v95, v61
	v_lshlrev_b32_e32 v61, 16, v141
	v_fmac_f32_e32 v64, v97, v61
	v_and_b32_e32 v61, 0xffff0000, v141
	v_fmac_f32_e32 v64, v98, v61
	v_lshlrev_b32_e32 v61, 16, v142
	v_fmac_f32_e32 v64, v99, v61
	v_and_b32_e32 v61, 0xffff0000, v142
	v_fmac_f32_e32 v64, v100, v61
	v_lshlrev_b32_e32 v61, 16, v143
	v_fmac_f32_e32 v64, v101, v61
	v_and_b32_e32 v61, 0xffff0000, v143
	v_fmac_f32_e32 v64, v102, v61
	v_add_f32_e32 v60, v60, v64
	v_mul_f32_e64 v61, |v60|, s51
	v_exp_f32_e32 v61, v61
	v_addc_co_u32_e64 v33, s[0:1], 0, v33, s[0:1]
	v_min_f32_e32 v60, 0, v60
	v_add_f32_e32 v61, 1.0, v61
	s_nop 0
	s_waitcnt vmcnt(3)
	v_and_b32_e32 v74, 0xffff0000, v148
	s_nop 0
	s_nop 0
	global_load_dwordx4 v[64:67], v[32:33], off offset:1536
	s_nop 0
	global_load_dwordx4 v[32:35], v[34:35], off offset:16
	v_lshlrev_b32_e32 v71, 16, v148
	v_mul_f32_e32 v74, v88, v74
	v_fmac_f32_e32 v74, v87, v71
	v_lshlrev_b32_e32 v71, 16, v149
	v_fmac_f32_e32 v74, v89, v71
	v_and_b32_e32 v71, 0xffff0000, v149
	v_fmac_f32_e32 v74, v90, v71
	v_lshlrev_b32_e32 v71, 16, v150
	v_fmac_f32_e32 v74, v91, v71
	v_and_b32_e32 v71, 0xffff0000, v150
	v_fmac_f32_e32 v74, v92, v71
	v_lshlrev_b32_e32 v71, 16, v151
	v_fmac_f32_e32 v74, v93, v71
	v_and_b32_e32 v71, 0xffff0000, v151
	v_fmac_f32_e32 v74, v94, v71
	s_waitcnt vmcnt(4)
	v_and_b32_e32 v75, 0xffff0000, v152
	v_add_f32_e32 v71, v86, v74
	v_lshlrev_b32_e32 v74, 16, v152
	v_mul_f32_e32 v75, v96, v75
	v_fmac_f32_e32 v75, v95, v74
	v_lshlrev_b32_e32 v74, 16, v153
	v_fmac_f32_e32 v75, v97, v74
	v_and_b32_e32 v74, 0xffff0000, v153
	v_fmac_f32_e32 v75, v98, v74
	v_lshlrev_b32_e32 v74, 16, v154
	v_fmac_f32_e32 v75, v99, v74
	v_and_b32_e32 v74, 0xffff0000, v154
	v_fmac_f32_e32 v75, v100, v74
	v_lshlrev_b32_e32 v74, 16, v155
	v_fmac_f32_e32 v75, v101, v74
	v_and_b32_e32 v74, 0xffff0000, v155
	v_log_f32_e32 v61, v61
	v_fmac_f32_e32 v75, v102, v74
	v_add_f32_e32 v71, v71, v75
	v_mul_f32_e64 v74, |v71|, s51
	v_exp_f32_e32 v74, v74
	v_mul_f32_e32 v70, 0x3f317217, v61
	v_fma_f32 v70, v61, s53, -v70
	v_fmac_f32_e32 v70, 0x3377d1cf, v61
	v_fmac_f32_e32 v70, 0x3f317217, v61
	s_nop 0
	v_add_f32_e32 v74, 1.0, v74
	s_waitcnt vmcnt(2)
	v_and_b32_e32 v139, 0xffff0000, v160
	v_mov_b32_e32 v61, v70
	s_nop 0
	s_nop 0
	s_nop 0
	v_sub_f32_e32 v60, v60, v61
	s_nop 0
	s_nop 0
	v_and_b32_e32 v75, 0xffff0000, v156
	v_min_f32_e32 v61, 0, v71
	v_lshlrev_b32_e32 v71, 16, v156
	v_mul_f32_e32 v75, v88, v75
	v_fmac_f32_e32 v75, v87, v71
	v_lshlrev_b32_e32 v71, 16, v157
	v_fmac_f32_e32 v75, v89, v71
	v_and_b32_e32 v71, 0xffff0000, v157
	v_fmac_f32_e32 v75, v90, v71
	v_lshlrev_b32_e32 v71, 16, v158
	v_fmac_f32_e32 v75, v91, v71
	v_and_b32_e32 v71, 0xffff0000, v158
	v_fmac_f32_e32 v75, v92, v71
	v_lshlrev_b32_e32 v71, 16, v159
	v_fmac_f32_e32 v75, v93, v71
	v_and_b32_e32 v71, 0xffff0000, v159
	v_fmac_f32_e32 v75, v94, v71
	v_add_f32_e32 v71, v86, v75
	v_lshlrev_b32_e32 v75, 16, v160
	v_mul_f32_e32 v139, v96, v139
	v_fmac_f32_e32 v139, v95, v75
	v_lshlrev_b32_e32 v75, 16, v161
	v_fmac_f32_e32 v139, v97, v75
	v_and_b32_e32 v75, 0xffff0000, v161
	v_fmac_f32_e32 v139, v98, v75
	v_lshlrev_b32_e32 v75, 16, v162
	v_fmac_f32_e32 v139, v99, v75
	v_and_b32_e32 v75, 0xffff0000, v162
	v_fmac_f32_e32 v139, v100, v75
	v_lshlrev_b32_e32 v75, 16, v163
	v_fmac_f32_e32 v139, v101, v75
	v_and_b32_e32 v75, 0xffff0000, v163
	v_log_f32_e32 v74, v74
	v_fmac_f32_e32 v139, v102, v75
	v_add_f32_e32 v71, v71, v139
	v_mul_f32_e64 v75, |v71|, s51
	v_exp_f32_e32 v75, v75
	v_mul_f32_e32 v70, 0x3f317217, v74
	v_fma_f32 v70, v74, s53, -v70
	v_fmac_f32_e32 v70, 0x3377d1cf, v74
	v_fmac_f32_e32 v70, 0x3f317217, v74
	s_nop 0
	v_add_f32_e32 v75, 1.0, v75
	s_waitcnt vmcnt(1)
	v_lshlrev_b32_e32 v144, 16, v64
	s_nop 0
	s_nop 0
	s_nop 0
	s_nop 0
	v_sub_f32_e32 v74, v61, v70
	s_nop 0
	s_nop 0
	v_log_f32_e32 v75, v75
	v_min_f32_e32 v61, 0, v71
	v_and_b32_e32 v64, 0xffff0000, v64
	v_mul_f32_e32 v64, v88, v64
	v_mul_f32_e32 v70, 0x3f317217, v75
	v_fma_f32 v139, v75, s53, -v70
	v_mad_u64_u32 v[70:71], s[20:21], v58, s49, v[50:51]
	v_mad_i32_i24 v71, v59, s49, v71
	v_add_co_u32_e64 v58, s[20:21], s40, v70
	v_fmac_f32_e32 v64, v87, v144
	s_nop 0
	v_addc_co_u32_e64 v59, s[20:21], 0, v71, s[20:21]
	global_load_dwordx4 v[140:143], v[58:59], off offset:1536
	v_lshlrev_b32_e32 v58, 16, v65
	v_fmac_f32_e32 v64, v89, v58
	v_and_b32_e32 v58, 0xffff0000, v65
	v_fmac_f32_e32 v64, v90, v58
	v_lshlrev_b32_e32 v58, 16, v66
	v_fmac_f32_e32 v64, v91, v58
	v_and_b32_e32 v58, 0xffff0000, v66
	v_fmac_f32_e32 v64, v92, v58
	v_lshlrev_b32_e32 v58, 16, v67
	v_fmac_f32_e32 v64, v93, v58
	v_and_b32_e32 v58, 0xffff0000, v67
	v_fmac_f32_e32 v64, v94, v58
	v_lshl_add_u64 v[58:59], v[70:71], 0, s[28:29]
	v_add_f32_e32 v144, v86, v64
	global_load_dwordx4 v[64:67], v[58:59], off offset:16
	s_waitcnt vmcnt(2)
	v_lshlrev_b32_e32 v145, 16, v32
	v_and_b32_e32 v32, 0xffff0000, v32
	v_mul_f32_e32 v32, v96, v32
	v_fmac_f32_e32 v32, v95, v145
	v_lshlrev_b32_e32 v58, 16, v33
	v_fmac_f32_e32 v32, v97, v58
	v_and_b32_e32 v33, 0xffff0000, v33
	v_fmac_f32_e32 v32, v98, v33
	v_lshlrev_b32_e32 v33, 16, v34
	v_fmac_f32_e32 v32, v99, v33
	v_and_b32_e32 v33, 0xffff0000, v34
	v_fmac_f32_e32 v32, v100, v33
	v_lshlrev_b32_e32 v33, 16, v35
	v_fmac_f32_e32 v32, v101, v33
	v_and_b32_e32 v33, 0xffff0000, v35
	v_fmac_f32_e32 v32, v102, v33
	v_add_f32_e32 v70, v144, v32
	v_mul_f32_e64 v32, |v70|, s51
	v_exp_f32_e32 v32, v32
	v_fmac_f32_e32 v139, 0x3377d1cf, v75
	v_fmac_f32_e32 v139, 0x3f317217, v75
	s_nop 0
	v_add_f32_e32 v32, 1.0, v32
	s_nop 0
	v_mov_b32_e32 v33, v139
	s_nop 0
	v_mov_b32_e32 v71, v33
	v_mad_u64_u32 v[58:59], s[20:21], v56, s49, v[50:51]
	s_nop 0
	s_nop 0
	v_log_f32_e32 v75, v32
	v_mad_i32_i24 v59, v57, s49, v59
	v_add_co_u32_e64 v32, s[20:21], s40, v58
	v_mul_f32_e32 v57, 0x3f317217, v75
	s_nop 0
	v_addc_co_u32_e64 v33, s[20:21], 0, v59, s[20:21]
	global_load_dwordx4 v[32:35], v[32:33], off offset:1536
	v_fma_f32 v57, v75, s53, -v57
	v_fmac_f32_e32 v57, 0x3377d1cf, v75
	v_fmac_f32_e32 v57, 0x3f317217, v75
	s_nop 0
	v_sub_f32_e32 v139, v61, v71
	s_nop 0
	s_nop 0
	v_min_f32_e32 v56, 0, v70
	s_nop 0
	v_sub_f32_e32 v75, v56, v57
	v_lshl_add_u64 v[56:57], v[58:59], 0, s[28:29]
	global_load_dwordx4 v[56:59], v[56:57], off offset:16
	v_mad_u64_u32 v[70:71], s[0:1], v54, s49, v[50:51]
	v_mad_i32_i24 v71, v55, s49, v71
	v_lshl_add_u64 v[54:55], v[70:71], 0, s[28:29]
	v_add_co_u32_e64 v70, s[0:1], s40, v70
	s_waitcnt vmcnt(2)
	v_and_b32_e32 v61, 0xffff0000, v64
	v_addc_co_u32_e64 v71, s[0:1], 0, v71, s[0:1]
	v_mad_u64_u32 v[50:51], s[0:1], v52, s49, v[50:51]
	v_mad_i32_i24 v51, v53, s49, v51
	v_and_b32_e32 v53, 0xffff0000, v140
	v_lshlrev_b32_e32 v52, 16, v140
	v_mul_f32_e32 v53, v88, v53
	v_fmac_f32_e32 v53, v87, v52
	v_lshlrev_b32_e32 v52, 16, v141
	v_fmac_f32_e32 v53, v89, v52
	v_and_b32_e32 v52, 0xffff0000, v141
	v_fmac_f32_e32 v53, v90, v52
	v_lshlrev_b32_e32 v52, 16, v142
	v_fmac_f32_e32 v53, v91, v52
	v_and_b32_e32 v52, 0xffff0000, v142
	v_fmac_f32_e32 v53, v92, v52
	v_lshlrev_b32_e32 v52, 16, v143
	v_fmac_f32_e32 v53, v93, v52
	v_and_b32_e32 v52, 0xffff0000, v143
	v_fmac_f32_e32 v53, v94, v52
	global_load_dwordx4 v[144:147], v[70:71], off offset:1536
	global_load_dwordx4 v[148:151], v[54:55], off offset:16
	v_add_f32_e32 v52, v86, v53
	v_lshlrev_b32_e32 v53, 16, v64
	v_mul_f32_e32 v61, v96, v61
	v_fmac_f32_e32 v61, v95, v53
	v_lshlrev_b32_e32 v53, 16, v65
	v_fmac_f32_e32 v61, v97, v53
	v_and_b32_e32 v53, 0xffff0000, v65
	v_fmac_f32_e32 v61, v98, v53
	v_lshlrev_b32_e32 v53, 16, v66
	v_fmac_f32_e32 v61, v99, v53
	v_and_b32_e32 v53, 0xffff0000, v66
	v_fmac_f32_e32 v61, v100, v53
	v_lshlrev_b32_e32 v53, 16, v67
	v_fmac_f32_e32 v61, v101, v53
	v_and_b32_e32 v53, 0xffff0000, v67
	v_fmac_f32_e32 v61, v102, v53
	v_add_f32_e32 v61, v52, v61
	v_mul_f32_e64 v52, |v61|, s51
	v_exp_f32_e32 v52, v52
	v_lshl_add_u64 v[54:55], v[50:51], 0, s[28:29]
	v_add_co_u32_e64 v50, s[0:1], s40, v50
	v_add_f32_e32 v52, 1.0, v52
	s_nop 0
	v_addc_co_u32_e64 v51, s[0:1], 0, v51, s[0:1]
	s_nop 0
	s_nop 1
	s_nop 0
	s_nop 0
	v_log_f32_e32 v70, v52
	global_load_dwordx4 v[50:53], v[50:51], off offset:1536
	s_nop 0
	global_load_dwordx4 v[64:67], v[54:55], off offset:16
	v_min_f32_e32 v54, 0, v61
	s_waitcnt vmcnt(5)
	v_lshlrev_b32_e32 v61, 16, v32
	v_and_b32_e32 v32, 0xffff0000, v32
	v_mul_f32_e32 v32, v88, v32
	v_fmac_f32_e32 v32, v87, v61
	v_lshlrev_b32_e32 v61, 16, v33
	v_fmac_f32_e32 v32, v89, v61
	v_and_b32_e32 v33, 0xffff0000, v33
	v_fmac_f32_e32 v32, v90, v33
	v_lshlrev_b32_e32 v33, 16, v34
	v_fmac_f32_e32 v32, v91, v33
	v_and_b32_e32 v33, 0xffff0000, v34
	v_fmac_f32_e32 v32, v92, v33
	v_lshlrev_b32_e32 v33, 16, v35
	v_fmac_f32_e32 v32, v93, v33
	v_and_b32_e32 v33, 0xffff0000, v35
	s_waitcnt vmcnt(4)
	v_and_b32_e32 v34, 0xffff0000, v56
	v_fmac_f32_e32 v32, v94, v33
	v_lshlrev_b32_e32 v33, 16, v56
	v_mul_f32_e32 v34, v96, v34
	v_fmac_f32_e32 v34, v95, v33
	v_lshlrev_b32_e32 v33, 16, v57
	v_fmac_f32_e32 v34, v97, v33
	v_and_b32_e32 v33, 0xffff0000, v57
	v_fmac_f32_e32 v34, v98, v33
	v_lshlrev_b32_e32 v33, 16, v58
	v_fmac_f32_e32 v34, v99, v33
	v_and_b32_e32 v33, 0xffff0000, v58
	v_fmac_f32_e32 v34, v100, v33
	v_lshlrev_b32_e32 v33, 16, v59
	v_fmac_f32_e32 v34, v101, v33
	v_and_b32_e32 v33, 0xffff0000, v59
	v_add_f32_e32 v32, v86, v32
	v_fmac_f32_e32 v34, v102, v33
	v_add_f32_e32 v32, v32, v34
	v_mul_f32_e64 v33, |v32|, s51
	v_exp_f32_e32 v33, v33
	v_mul_f32_e32 v55, 0x3f317217, v70
	v_fma_f32 v55, v70, s53, -v55
	v_fmac_f32_e32 v55, 0x3377d1cf, v70
	v_add_f32_e32 v33, 1.0, v33
	v_fmac_f32_e32 v55, 0x3f317217, v70
	s_nop 0
	s_nop 0
	s_nop 0
	v_mov_b32_e32 v34, v55
	s_nop 0
	s_nop 0
	s_nop 0
	s_waitcnt vmcnt(3)
	v_and_b32_e32 v55, 0xffff0000, v144
	v_sub_f32_e32 v34, v54, v34
	v_lshlrev_b32_e32 v54, 16, v144
	v_mul_f32_e32 v55, v88, v55
	v_fmac_f32_e32 v55, v87, v54
	v_lshlrev_b32_e32 v54, 16, v145
	v_fmac_f32_e32 v55, v89, v54
	v_and_b32_e32 v54, 0xffff0000, v145
	v_fmac_f32_e32 v55, v90, v54
	v_lshlrev_b32_e32 v54, 16, v146
	v_fmac_f32_e32 v55, v91, v54
	v_and_b32_e32 v54, 0xffff0000, v146
	v_fmac_f32_e32 v55, v92, v54
	v_lshlrev_b32_e32 v54, 16, v147
	v_fmac_f32_e32 v55, v93, v54
	v_and_b32_e32 v54, 0xffff0000, v147
	v_log_f32_e32 v33, v33
	v_fmac_f32_e32 v55, v94, v54
	s_waitcnt vmcnt(2)
	v_and_b32_e32 v56, 0xffff0000, v148
	v_add_f32_e32 v54, v86, v55
	v_lshlrev_b32_e32 v55, 16, v148
	v_mul_f32_e32 v56, v96, v56
	v_fmac_f32_e32 v56, v95, v55
	v_lshlrev_b32_e32 v55, 16, v149
	v_fmac_f32_e32 v56, v97, v55
	v_and_b32_e32 v55, 0xffff0000, v149
	v_mul_f32_e32 v35, 0x3f317217, v33
	v_fmac_f32_e32 v56, v98, v55
	v_lshlrev_b32_e32 v55, 16, v150
	v_fma_f32 v35, v33, s53, -v35
	v_fmac_f32_e32 v56, v99, v55
	v_and_b32_e32 v55, 0xffff0000, v150
	v_fmac_f32_e32 v35, 0x3377d1cf, v33
	v_fmac_f32_e32 v56, v100, v55
	v_lshlrev_b32_e32 v55, 16, v151
	v_fmac_f32_e32 v35, 0x3f317217, v33
	v_fmac_f32_e32 v56, v101, v55
	v_and_b32_e32 v55, 0xffff0000, v151
	s_nop 0
	v_fmac_f32_e32 v56, v102, v55
	v_min_f32_e32 v32, 0, v32
	v_mov_b32_e32 v33, v35
	s_nop 0
	v_add_f32_e32 v54, v54, v56
	s_nop 0
	v_mul_f32_e64 v55, |v54|, s51
	v_sub_f32_e32 v32, v32, v33
	v_min_f32_e32 v33, 0, v54
	s_waitcnt vmcnt(1)
	v_lshlrev_b32_e32 v54, 16, v50
	v_and_b32_e32 v50, 0xffff0000, v50
	v_mul_f32_e32 v50, v88, v50
	v_fmac_f32_e32 v50, v87, v54
	v_lshlrev_b32_e32 v54, 16, v51
	v_fmac_f32_e32 v50, v89, v54
	v_and_b32_e32 v51, 0xffff0000, v51
	v_fmac_f32_e32 v50, v90, v51
	v_lshlrev_b32_e32 v51, 16, v52
	v_fmac_f32_e32 v50, v91, v51
	v_and_b32_e32 v51, 0xffff0000, v52
	v_fmac_f32_e32 v50, v92, v51
	v_lshlrev_b32_e32 v51, 16, v53
	v_fmac_f32_e32 v50, v93, v51
	v_and_b32_e32 v51, 0xffff0000, v53
	s_waitcnt vmcnt(0)
	v_and_b32_e32 v52, 0xffff0000, v64
	v_fmac_f32_e32 v50, v94, v51
	v_lshlrev_b32_e32 v51, 16, v64
	v_mul_f32_e32 v52, v96, v52
	v_fmac_f32_e32 v52, v95, v51
	v_lshlrev_b32_e32 v51, 16, v65
	v_fmac_f32_e32 v52, v97, v51
	v_and_b32_e32 v51, 0xffff0000, v65
	v_fmac_f32_e32 v52, v98, v51
	v_lshlrev_b32_e32 v51, 16, v66
	v_exp_f32_e32 v55, v55
	v_fmac_f32_e32 v52, v99, v51
	v_and_b32_e32 v51, 0xffff0000, v66
	v_fmac_f32_e32 v52, v100, v51
	v_lshlrev_b32_e32 v51, 16, v67
	v_fmac_f32_e32 v52, v101, v51
	v_and_b32_e32 v51, 0xffff0000, v67
	v_add_f32_e32 v50, v86, v50
	v_fmac_f32_e32 v52, v102, v51
	v_add_f32_e32 v55, 1.0, v55
	v_add_f32_e32 v50, v50, v52
	s_nop 0
	v_mul_f32_e64 v51, |v50|, s51
	v_exp_f32_e32 v51, v51
	s_nop 0
	s_nop 0
	v_log_f32_e32 v55, v55
	v_add_f32_e32 v51, 1.0, v51
	s_nop 0
	s_nop 0
	v_fmamk_f32 v67, v138, 0x3d800000, v137
	v_mul_f32_e32 v35, 0x3f317217, v55
	s_nop 0
	v_fmamk_f32 v66, v72, 0x3d800000, v67
	v_fma_f32 v35, v55, s53, -v35
	s_nop 0
	v_fmamk_f32 v65, v73, 0x3d800000, v66
	v_fmac_f32_e32 v35, 0x3377d1cf, v55
	v_log_f32_e32 v51, v51
	v_fmamk_f32 v64, v68, 0x3d800000, v65
	v_fmac_f32_e32 v35, 0x3f317217, v55
	s_nop 0
	v_fmamk_f32 v61, v69, 0x3d800000, v64
	v_fmamk_f32 v59, v62, 0x3d800000, v61
	s_nop 0
	s_nop 0
	v_fmamk_f32 v58, v63, 0x3d800000, v59
	v_sub_f32_e32 v33, v33, v35
	v_min_f32_e32 v35, 0, v50
	v_mul_f32_e32 v50, 0x3f317217, v51
	v_fmamk_f32 v57, v60, 0x3d800000, v58
	v_fma_f32 v50, v51, s53, -v50
	v_fmamk_f32 v56, v74, 0x3d800000, v57
	v_fmac_f32_e32 v50, 0x3377d1cf, v51
	v_fmamk_f32 v55, v139, 0x3d800000, v56
	v_fmac_f32_e32 v50, 0x3f317217, v51
	s_nop 0
	v_fmamk_f32 v54, v75, 0x3d800000, v55
	v_fmamk_f32 v53, v34, 0x3d800000, v54
	s_nop 0
	s_nop 0
	s_nop 0
	v_fmamk_f32 v52, v32, 0x3d800000, v53
	v_sub_f32_e32 v35, v35, v50
	v_fmamk_f32 v51, v33, 0x3d800000, v52
	v_fmamk_f32 v50, v35, 0x3d800000, v51
	ds_write_b32 v77, v50
	s_waitcnt lgkmcnt(0)
	s_barrier
	ds_read2st64_b32 v[34:35], v78 offset1:2
	ds_read2st64_b32 v[32:33], v78 offset0:4 offset1:6
	s_waitcnt lgkmcnt(1)
	v_add_f32_e32 v60, 0, v34
	v_add_f32_e32 v34, v60, v35
	s_waitcnt lgkmcnt(0)
	v_add_f32_e32 v34, v34, v32
	v_add_f32_e32 v34, v34, v33
	s_and_saveexec_b64 s[0:1], s[8:9]
	s_cbranch_execz .LBB0_2722
	v_mul_f32_e32 v62, 0x3fb8aa3b, v34
	v_exp_f32_e32 v62, v62
	v_add_f32_e32 v40, v40, v34
	ds_write_b32 v81, v62
	s_branch .LBB0_2722

.LBB0_2792:
	v_add_u32_e32 v163, s81, v42
	v_add_u32_e32 v32, 0x1ff, v163
	v_add_u32_e32 v165, s81, v154
	v_cndmask_b32_e64 v32, v32, v165, s[40:41]
	v_ashrrev_i32_e32 v33, 31, v32
	v_lshl_add_u64 v[38:39], v[32:33], 0, s[48:49]
	v_add_u32_e32 v32, 0x1fe, v163
	v_add_u32_e32 v33, 1, v165
	v_cndmask_b32_e64 v32, v32, v33, s[40:41]
	v_ashrrev_i32_e32 v33, 31, v32
	v_lshl_add_u64 v[34:35], v[32:33], 0, s[48:49]
	v_add_u32_e32 v32, 0x1fd, v163
	v_add_u32_e32 v33, 2, v165
	v_cndmask_b32_e64 v32, v32, v33, s[40:41]
	v_ashrrev_i32_e32 v33, 31, v32
	v_mad_u64_u32 v[36:37], s[0:1], v38, s63, v[58:59]
	v_lshl_add_u64 v[32:33], v[32:33], 0, s[48:49]
	v_mad_i32_i24 v37, v39, s63, v37
	v_mad_u64_u32 v[62:63], s[0:1], v34, s63, v[58:59]
	v_mad_u64_u32 v[64:65], s[0:1], v32, s63, v[58:59]
	v_mad_i32_i24 v63, v35, s63, v63
	v_mad_i32_i24 v65, v33, s63, v65
	global_load_ushort v204, v[36:37], off
	global_load_ushort v188, v[36:37], off offset:1024
	global_load_ushort v197, v[36:37], off offset:2048
	global_load_ushort v201, v[62:63], off
	global_load_ushort v185, v[62:63], off offset:1024
	global_load_ushort v198, v[62:63], off offset:2048
	global_load_ushort v190, v[64:65], off offset:1024
	global_load_ushort v174, v[64:65], off offset:2048
	v_add_u32_e32 v36, 0x1fc, v163
	v_add_u32_e32 v37, 3, v165
	v_cndmask_b32_e64 v36, v36, v37, s[40:41]
	v_add_u32_e32 v62, 0x1fb, v163
	v_add_u32_e32 v63, 4, v165
	v_add_u32_e32 v66, 0x1fa, v163
	v_add_u32_e32 v67, 5, v165
	v_ashrrev_i32_e32 v37, 31, v36
	v_cndmask_b32_e64 v62, v62, v63, s[40:41]
	v_cndmask_b32_e64 v66, v66, v67, s[40:41]
	v_lshl_add_u64 v[84:85], v[36:37], 0, s[48:49]
	v_ashrrev_i32_e32 v63, 31, v62
	v_ashrrev_i32_e32 v67, 31, v66
	v_mad_u64_u32 v[36:37], s[0:1], v84, s63, v[58:59]
	v_lshl_add_u64 v[82:83], v[62:63], 0, s[48:49]
	v_lshl_add_u64 v[78:79], v[66:67], 0, s[48:49]
	v_mad_i32_i24 v37, v85, s63, v37
	v_mad_u64_u32 v[62:63], s[0:1], v82, s63, v[58:59]
	v_mad_u64_u32 v[66:67], s[0:1], v78, s63, v[58:59]
	v_mad_i32_i24 v63, v83, s63, v63
	v_mad_i32_i24 v67, v79, s63, v67
	global_load_ushort v206, v[64:65], off
	global_load_ushort v203, v[36:37], off
	global_load_ushort v200, v[36:37], off offset:1024
	global_load_ushort v193, v[36:37], off offset:2048
	global_load_ushort v192, v[62:63], off
	global_load_ushort v164, v[62:63], off offset:1024
	global_load_ushort v178, v[62:63], off offset:2048
	global_load_ushort v184, v[66:67], off offset:2048
	v_add_u32_e32 v36, 0x1f9, v163
	v_add_u32_e32 v37, 6, v165
	v_cndmask_b32_e64 v36, v36, v37, s[40:41]
	v_add_u32_e32 v62, 0x1f8, v163
	v_add_u32_e32 v63, 7, v165
	v_ashrrev_i32_e32 v37, 31, v36
	v_cndmask_b32_e64 v62, v62, v63, s[40:41]
	v_lshl_add_u64 v[76:77], v[36:37], 0, s[48:49]
	v_ashrrev_i32_e32 v63, 31, v62
	v_mad_u64_u32 v[36:37], s[0:1], v76, s63, v[58:59]
	v_lshl_add_u64 v[80:81], v[62:63], 0, s[48:49]
	v_mad_i32_i24 v37, v77, s63, v37
	v_mad_u64_u32 v[62:63], s[0:1], v80, s63, v[58:59]
	v_mad_i32_i24 v63, v81, s63, v63
	global_load_ushort v196, v[66:67], off
	global_load_ushort v176, v[66:67], off offset:1024
	global_load_ushort v191, v[36:37], off
	global_load_ushort v180, v[36:37], off offset:1024
	global_load_ushort v162, v[36:37], off offset:2048
	global_load_ushort v187, v[62:63], off
	global_load_ushort v179, v[62:63], off offset:1024
	global_load_ushort v167, v[62:63], off offset:2048
	v_add_u32_e32 v36, 0x1f7, v163
	v_add_u32_e32 v37, 8, v165
	v_cndmask_b32_e64 v36, v36, v37, s[40:41]
	v_add_u32_e32 v62, 0x1f6, v163
	v_add_u32_e32 v63, 9, v165
	v_add_u32_e32 v64, 0x1f5, v163
	v_add_u32_e32 v65, 10, v165
	v_ashrrev_i32_e32 v37, 31, v36
	v_cndmask_b32_e64 v62, v62, v63, s[40:41]
	v_cndmask_b32_e64 v64, v64, v65, s[40:41]
	v_lshl_add_u64 v[72:73], v[36:37], 0, s[48:49]
	v_ashrrev_i32_e32 v63, 31, v62
	v_ashrrev_i32_e32 v65, 31, v64
	v_mad_u64_u32 v[36:37], s[0:1], v72, s63, v[58:59]
	v_lshl_add_u64 v[70:71], v[62:63], 0, s[48:49]
	v_lshl_add_u64 v[68:69], v[64:65], 0, s[48:49]
	v_mad_i32_i24 v37, v73, s63, v37
	v_mad_u64_u32 v[62:63], s[0:1], v70, s63, v[58:59]
	v_mad_u64_u32 v[168:169], s[0:1], v68, s63, v[58:59]
	v_mad_i32_i24 v63, v71, s63, v63
	v_mad_i32_i24 v169, v69, s63, v169
	global_load_ushort v182, v[36:37], off
	global_load_ushort v159, v[36:37], off offset:1024
	global_load_ushort v166, v[36:37], off offset:2048
	global_load_ushort v177, v[62:63], off
	global_load_ushort v158, v[62:63], off offset:1024
	global_load_ushort v171, v[62:63], off offset:2048
	global_load_ushort v160, v[168:169], off offset:1024
	global_load_ushort v157, v[168:169], off offset:2048
	v_add_u32_e32 v36, 0x1f4, v163
	v_add_u32_e32 v37, 11, v165
	v_cndmask_b32_e64 v62, v36, v37, s[40:41]
	v_mov_b64_e32 v[36:37], s[52:53]
	v_mad_u64_u32 v[64:65], s[0:1], v38, s63, v[36:37]
	v_mad_i32_i24 v65, v39, s63, v65
	v_add_co_u32_e32 v38, vcc, s55, v64
	v_ashrrev_i32_e32 v63, 31, v62
	s_nop 0
	v_addc_co_u32_e32 v39, vcc, 0, v65, vcc
	global_load_dwordx4 v[208:211], v[38:39], off offset:1536
	v_lshl_add_u64 v[74:75], v[62:63], 0, s[48:49]
	v_add_u32_e32 v62, 0x1f3, v163
	v_add_u32_e32 v63, 12, v165
	v_add_u32_e32 v161, 0x1f2, v163
	v_add_u32_e32 v170, 13, v165
	v_lshl_add_u64 v[64:65], v[64:65], 0, s[50:51]
	v_cndmask_b32_e64 v62, v62, v63, s[40:41]
	global_load_dwordx4 v[212:215], v[64:65], off offset:16
	v_cndmask_b32_e64 v64, v161, v170, s[40:41]
	v_ashrrev_i32_e32 v63, 31, v62
	v_ashrrev_i32_e32 v65, 31, v64
	v_mad_u64_u32 v[38:39], s[0:1], v74, s63, v[58:59]
	v_lshl_add_u64 v[66:67], v[62:63], 0, s[48:49]
	v_lshl_add_u64 v[64:65], v[64:65], 0, s[48:49]
	v_mad_i32_i24 v39, v75, s63, v39
	v_mad_u64_u32 v[62:63], s[0:1], v66, s63, v[58:59]
	v_mad_u64_u32 v[220:221], s[0:1], v64, s63, v[58:59]
	v_mad_u64_u32 v[224:225], s[0:1], v34, s63, v[36:37]
	v_mad_i32_i24 v63, v67, s63, v63
	v_mad_i32_i24 v221, v65, s63, v221
	global_load_ushort v205, v[168:169], off
	global_load_ushort v202, v[38:39], off
	global_load_ushort v199, v[38:39], off offset:1024
	global_load_ushort v186, v[38:39], off offset:2048
	global_load_ushort v183, v[62:63], off
	global_load_ushort v161, v[62:63], off offset:1024
	global_load_ushort v168, v[62:63], off offset:2048
	global_load_ushort v172, v[220:221], off offset:2048
	v_add_u32_e32 v38, 0x1f1, v163
	v_add_u32_e32 v39, 14, v165
	v_mad_i32_i24 v225, v35, s63, v225
	v_add_co_u32_e32 v34, vcc, s55, v224
	v_cndmask_b32_e64 v38, v38, v39, s[40:41]
	s_nop 0
	v_addc_co_u32_e32 v35, vcc, 0, v225, vcc
	v_ashrrev_i32_e32 v39, 31, v38
	global_load_dwordx4 v[216:219], v[34:35], off offset:1536
	v_lshl_add_u64 v[62:63], v[38:39], 0, s[48:49]
	v_add_u32_e32 v38, 0x1f0, v163
	v_add_u32_e32 v39, 15, v165
	v_cndmask_b32_e64 v38, v38, v39, s[40:41]
	v_ashrrev_i32_e32 v39, 31, v38
	v_lshl_add_u64 v[38:39], v[38:39], 0, s[48:49]
	v_mad_u64_u32 v[34:35], s[0:1], v38, s63, v[58:59]
	v_mad_u64_u32 v[222:223], s[0:1], v62, s63, v[58:59]
	v_mad_i32_i24 v35, v39, s63, v35
	v_mad_i32_i24 v223, v63, s63, v223
	global_load_ushort v189, v[220:221], off
	global_load_ushort v163, v[220:221], off offset:1024
	global_load_ushort v181, v[222:223], off
	global_load_ushort v169, v[222:223], off offset:1024
	global_load_ushort v170, v[222:223], off offset:2048
	global_load_ushort v175, v[34:35], off
	global_load_ushort v165, v[34:35], off offset:1024
	global_load_ushort v173, v[34:35], off offset:2048
	v_lshl_add_u64 v[34:35], v[224:225], 0, s[50:51]
	global_load_dwordx4 v[220:223], v[34:35], off offset:16
	v_mad_u64_u32 v[34:35], s[0:1], v32, s63, v[36:37]
	v_mad_i32_i24 v35, v33, s63, v35
	v_lshl_add_u64 v[32:33], v[34:35], 0, s[50:51]
	v_add_co_u32_e32 v34, vcc, s55, v34
	s_waitcnt vmcnt(0)
	v_and_b32_e32 v207, 0xffff0000, v212
	v_addc_co_u32_e32 v35, vcc, 0, v35, vcc
	global_load_dwordx4 v[224:227], v[34:35], off offset:1536
	global_load_dwordx4 v[228:231], v[32:33], off offset:16
	v_mad_u64_u32 v[32:33], s[0:1], v84, s63, v[36:37]
	v_mad_i32_i24 v33, v85, s63, v33
	v_and_b32_e32 v85, 0xffff0000, v208
	v_lshlrev_b32_e32 v84, 16, v208
	s_waitcnt lgkmcnt(0)
	v_mul_f32_e32 v85, v139, v85
	v_fmac_f32_e32 v85, v138, v84
	v_lshlrev_b32_e32 v84, 16, v209
	v_fmac_f32_e32 v85, v140, v84
	v_and_b32_e32 v84, 0xffff0000, v209
	v_fmac_f32_e32 v85, v141, v84
	v_lshlrev_b32_e32 v84, 16, v210
	v_lshl_add_u64 v[34:35], v[32:33], 0, s[50:51]
	v_fmac_f32_e32 v85, v142, v84
	v_and_b32_e32 v84, 0xffff0000, v210
	v_add_co_u32_e32 v32, vcc, s55, v32
	v_fmac_f32_e32 v85, v143, v84
	v_lshlrev_b32_e32 v84, 16, v211
	v_addc_co_u32_e32 v33, vcc, 0, v33, vcc
	v_fmac_f32_e32 v85, v144, v84
	v_and_b32_e32 v84, 0xffff0000, v211
	global_load_dwordx4 v[208:211], v[32:33], off offset:1536
	s_nop 0
	global_load_dwordx4 v[32:35], v[34:35], off offset:16
	v_fmac_f32_e32 v85, v145, v84
	v_add_f32_e32 v84, v137, v85
	v_lshlrev_b32_e32 v85, 16, v212
	v_mul_f32_e32 v207, v147, v207
	v_fmac_f32_e32 v207, v146, v85
	v_lshlrev_b32_e32 v85, 16, v213
	v_fmac_f32_e32 v207, v148, v85
	v_and_b32_e32 v85, 0xffff0000, v213
	v_fmac_f32_e32 v207, v149, v85
	v_lshlrev_b32_e32 v85, 16, v214
	v_fmac_f32_e32 v207, v150, v85
	v_and_b32_e32 v85, 0xffff0000, v214
	v_and_b32_e32 v213, 0xffff0000, v216
	v_fmac_f32_e32 v207, v151, v85
	v_lshlrev_b32_e32 v85, 16, v215
	v_lshlrev_b32_e32 v212, 16, v216
	v_mul_f32_e32 v213, v139, v213
	v_fmac_f32_e32 v207, v152, v85
	v_and_b32_e32 v85, 0xffff0000, v215
	v_fmac_f32_e32 v213, v138, v212
	v_lshlrev_b32_e32 v212, 16, v217
	v_fmac_f32_e32 v207, v153, v85
	v_fmac_f32_e32 v213, v140, v212
	v_and_b32_e32 v212, 0xffff0000, v217
	v_add_f32_e32 v84, v84, v207
	v_fmac_f32_e32 v213, v141, v212
	v_lshlrev_b32_e32 v212, 16, v218
	v_mul_f32_e64 v85, |v84|, s71
	v_fmac_f32_e32 v213, v142, v212
	v_and_b32_e32 v212, 0xffff0000, v218
	v_exp_f32_e32 v85, v85
	v_fmac_f32_e32 v213, v143, v212
	v_lshlrev_b32_e32 v212, 16, v219
	v_fmac_f32_e32 v213, v144, v212
	v_and_b32_e32 v212, 0xffff0000, v219
	v_fmac_f32_e32 v213, v145, v212
	v_and_b32_e32 v214, 0xffff0000, v220
	v_add_f32_e32 v212, v137, v213
	v_lshlrev_b32_e32 v213, 16, v220
	v_mul_f32_e32 v214, v147, v214
	v_add_f32_e32 v85, 1.0, v85
	v_fmac_f32_e32 v214, v146, v213
	v_lshlrev_b32_e32 v213, 16, v221
	s_nop 0
	v_fmac_f32_e32 v214, v148, v213
	v_and_b32_e32 v213, 0xffff0000, v221
	s_nop 0
	v_fmac_f32_e32 v214, v149, v213
	v_lshlrev_b32_e32 v213, 16, v222
	s_nop 0
	v_fmac_f32_e32 v214, v150, v213
	v_and_b32_e32 v213, 0xffff0000, v222
	v_log_f32_e32 v85, v85
	v_fmac_f32_e32 v214, v151, v213
	v_lshlrev_b32_e32 v213, 16, v223
	v_fmac_f32_e32 v214, v152, v213
	v_and_b32_e32 v213, 0xffff0000, v223
	v_fmac_f32_e32 v214, v153, v213
	v_add_f32_e32 v212, v212, v214
	v_mul_f32_e32 v207, 0x3f317217, v85
	v_mul_f32_e64 v213, |v212|, s71
	v_fma_f32 v207, v85, s73, -v207
	v_exp_f32_e32 v213, v213
	v_fmac_f32_e32 v207, 0x3377d1cf, v85
	v_fmac_f32_e32 v207, 0x3f317217, v85
	s_nop 0
	s_waitcnt vmcnt(3)
	v_and_b32_e32 v214, 0xffff0000, v224
	v_mul_f32_e32 v214, v139, v214
	v_mov_b32_e32 v85, v207
	s_nop 0
	s_nop 0
	v_add_f32_e32 v207, 1.0, v213
	s_nop 0
	s_waitcnt vmcnt(2)
	v_and_b32_e32 v215, 0xffff0000, v228
	v_mul_f32_e32 v215, v147, v215
	s_nop 0
	s_nop 0
	v_lshlrev_b32_e32 v213, 16, v224
	v_fmac_f32_e32 v214, v138, v213
	v_lshlrev_b32_e32 v213, 16, v225
	v_fmac_f32_e32 v214, v140, v213
	v_and_b32_e32 v213, 0xffff0000, v225
	v_fmac_f32_e32 v214, v141, v213
	v_lshlrev_b32_e32 v213, 16, v226
	v_fmac_f32_e32 v214, v142, v213
	v_and_b32_e32 v213, 0xffff0000, v226
	v_fmac_f32_e32 v214, v143, v213
	v_lshlrev_b32_e32 v213, 16, v227
	v_fmac_f32_e32 v214, v144, v213
	v_and_b32_e32 v213, 0xffff0000, v227
	v_fmac_f32_e32 v214, v145, v213
	v_add_f32_e32 v213, v137, v214
	v_lshlrev_b32_e32 v214, 16, v228
	v_fmac_f32_e32 v215, v146, v214
	v_lshlrev_b32_e32 v214, 16, v229
	v_fmac_f32_e32 v215, v148, v214
	v_and_b32_e32 v214, 0xffff0000, v229
	v_fmac_f32_e32 v215, v149, v214
	v_lshlrev_b32_e32 v214, 16, v230
	v_fmac_f32_e32 v215, v150, v214
	v_and_b32_e32 v214, 0xffff0000, v230
	v_fmac_f32_e32 v215, v151, v214
	v_lshlrev_b32_e32 v214, 16, v231
	v_fmac_f32_e32 v215, v152, v214
	v_and_b32_e32 v214, 0xffff0000, v231
	v_log_f32_e32 v207, v207
	v_fmac_f32_e32 v215, v153, v214
	v_add_f32_e32 v213, v213, v215
	v_mul_f32_e64 v214, |v213|, s71
	v_min_f32_e32 v84, 0, v84
	v_exp_f32_e32 v214, v214
	v_sub_f32_e32 v84, v84, v85
	v_min_f32_e32 v85, 0, v212
	v_mul_f32_e32 v212, 0x3f317217, v207
	v_fma_f32 v212, v207, s73, -v212
	v_fmac_f32_e32 v212, 0x3377d1cf, v207
	v_fmac_f32_e32 v212, 0x3f317217, v207
	s_nop 0
	v_add_f32_e32 v214, 1.0, v214
	s_waitcnt vmcnt(1)
	v_lshlrev_b32_e32 v220, 16, v208
	v_mov_b32_e32 v207, v212
	s_nop 0
	s_nop 0
	v_mad_u64_u32 v[216:217], s[0:1], v82, s63, v[36:37]
	s_nop 0
	s_nop 0
	s_nop 0
	v_log_f32_e32 v218, v214
	v_mad_i32_i24 v217, v83, s63, v217
	v_add_co_u32_e64 v82, s[0:1], s55, v216
	s_nop 0
	v_mul_f32_e32 v212, 0x3f317217, v218
	v_and_b32_e32 v208, 0xffff0000, v208
	v_addc_co_u32_e64 v83, s[0:1], 0, v217, s[0:1]
	v_sub_f32_e32 v85, v85, v207
	v_min_f32_e32 v207, 0, v213
	v_fma_f32 v219, v218, s73, -v212
	v_mul_f32_e32 v208, v139, v208
	global_load_dwordx4 v[212:215], v[82:83], off offset:1536
	v_fmac_f32_e32 v208, v138, v220
	v_lshlrev_b32_e32 v82, 16, v209
	v_fmac_f32_e32 v208, v140, v82
	v_and_b32_e32 v82, 0xffff0000, v209
	v_fmac_f32_e32 v208, v141, v82
	v_lshlrev_b32_e32 v82, 16, v210
	v_fmac_f32_e32 v208, v142, v82
	v_and_b32_e32 v82, 0xffff0000, v210
	v_fmac_f32_e32 v208, v143, v82
	v_lshlrev_b32_e32 v82, 16, v211
	v_fmac_f32_e32 v208, v144, v82
	v_and_b32_e32 v82, 0xffff0000, v211
	v_fmac_f32_e32 v208, v145, v82
	v_lshl_add_u64 v[82:83], v[216:217], 0, s[50:51]
	v_add_f32_e32 v220, v137, v208
	global_load_dwordx4 v[208:211], v[82:83], off offset:16
	s_waitcnt vmcnt(2)
	v_lshlrev_b32_e32 v221, 16, v32
	v_and_b32_e32 v32, 0xffff0000, v32
	v_mul_f32_e32 v32, v147, v32
	v_fmac_f32_e32 v32, v146, v221
	v_lshlrev_b32_e32 v82, 16, v33
	v_fmac_f32_e32 v32, v148, v82
	v_and_b32_e32 v33, 0xffff0000, v33
	v_fmac_f32_e32 v32, v149, v33
	v_lshlrev_b32_e32 v33, 16, v34
	v_fmac_f32_e32 v32, v150, v33
	v_and_b32_e32 v33, 0xffff0000, v34
	v_fmac_f32_e32 v32, v151, v33
	v_lshlrev_b32_e32 v33, 16, v35
	v_fmac_f32_e32 v32, v152, v33
	v_and_b32_e32 v33, 0xffff0000, v35
	v_fmac_f32_e32 v32, v153, v33
	v_add_f32_e32 v82, v220, v32
	v_mul_f32_e64 v32, |v82|, s71
	v_exp_f32_e32 v32, v32
	v_fmac_f32_e32 v219, 0x3377d1cf, v218
	v_fmac_f32_e32 v219, 0x3f317217, v218
	s_nop 0
	v_add_f32_e32 v32, 1.0, v32
	s_nop 0
	v_mov_b32_e32 v33, v219
	s_nop 0
	v_mov_b32_e32 v83, v33
	v_mul_f32_e32 v84, 0x3d800000, v84
	s_nop 0
	s_nop 0
	v_log_f32_e32 v220, v32
	v_mad_u64_u32 v[32:33], s[0:1], v78, s63, v[36:37]
	v_mad_i32_i24 v33, v79, s63, v33
	v_add_co_u32_e64 v34, s[0:1], s55, v32
	s_nop 0
	s_nop 0
	v_addc_co_u32_e64 v35, s[0:1], 0, v33, s[0:1]
	global_load_dwordx4 v[216:219], v[34:35], off offset:1536
	v_mul_f32_e32 v35, 0x3f317217, v220
	v_fma_f32 v35, v220, s73, -v35
	v_fmac_f32_e32 v35, 0x3377d1cf, v220
	v_fmac_f32_e32 v35, 0x3f317217, v220
	s_nop 0
	v_lshl_add_u64 v[32:33], v[32:33], 0, s[50:51]
	v_min_f32_e32 v34, 0, v82
	s_nop 0
	global_load_dwordx4 v[220:223], v[32:33], off offset:16
	v_mad_u64_u32 v[32:33], s[0:1], v76, s63, v[36:37]
	s_nop 0
	v_mad_i32_i24 v33, v77, s63, v33
	v_sub_f32_e32 v79, v34, v35
	v_lshl_add_u64 v[34:35], v[32:33], 0, s[50:51]
	v_add_co_u32_e32 v32, vcc, s55, v32
	v_sub_f32_e32 v78, v207, v83
	s_nop 0
	v_addc_co_u32_e32 v33, vcc, 0, v33, vcc
	global_load_dwordx4 v[224:227], v[32:33], off offset:1536
	global_load_dwordx4 v[228:231], v[34:35], off offset:16
	v_mad_u64_u32 v[32:33], s[0:1], v80, s63, v[36:37]
	s_waitcnt vmcnt(5)
	v_and_b32_e32 v77, 0xffff0000, v212
	v_lshlrev_b32_e32 v76, 16, v212
	v_mul_f32_e32 v77, v139, v77
	v_fmac_f32_e32 v77, v138, v76
	v_lshlrev_b32_e32 v76, 16, v213
	v_fmac_f32_e32 v77, v140, v76
	v_and_b32_e32 v76, 0xffff0000, v213
	v_fmac_f32_e32 v77, v141, v76
	v_lshlrev_b32_e32 v76, 16, v214
	v_fmac_f32_e32 v77, v142, v76
	v_and_b32_e32 v76, 0xffff0000, v214
	v_fmac_f32_e32 v77, v143, v76
	v_lshlrev_b32_e32 v76, 16, v215
	v_fmac_f32_e32 v77, v144, v76
	v_and_b32_e32 v76, 0xffff0000, v215
	v_fmac_f32_e32 v77, v145, v76
	s_waitcnt vmcnt(4)
	v_and_b32_e32 v80, 0xffff0000, v208
	v_add_f32_e32 v76, v137, v77
	v_lshlrev_b32_e32 v77, 16, v208
	v_mul_f32_e32 v80, v147, v80
	v_fmac_f32_e32 v80, v146, v77
	v_lshlrev_b32_e32 v77, 16, v209
	v_fmac_f32_e32 v80, v148, v77
	v_and_b32_e32 v77, 0xffff0000, v209
	v_fmac_f32_e32 v80, v149, v77
	v_lshlrev_b32_e32 v77, 16, v210
	v_fmac_f32_e32 v80, v150, v77
	v_and_b32_e32 v77, 0xffff0000, v210
	v_fmac_f32_e32 v80, v151, v77
	v_lshlrev_b32_e32 v77, 16, v211
	v_fmac_f32_e32 v80, v152, v77
	v_and_b32_e32 v77, 0xffff0000, v211
	v_fmac_f32_e32 v80, v153, v77
	v_add_f32_e32 v76, v76, v80
	v_mul_f32_e64 v77, |v76|, s71
	v_exp_f32_e32 v77, v77
	v_mad_i32_i24 v33, v81, s63, v33
	v_lshl_add_u64 v[34:35], v[32:33], 0, s[50:51]
	v_add_co_u32_e32 v32, vcc, s55, v32
	v_add_f32_e32 v77, 1.0, v77
	s_nop 0
	v_addc_co_u32_e32 v33, vcc, 0, v33, vcc
	s_nop 0
	v_min_f32_e32 v76, 0, v76
	s_waitcnt vmcnt(3)
	v_and_b32_e32 v209, 0xffff0000, v216
	s_nop 0
	s_nop 0
	global_load_dwordx4 v[80:83], v[32:33], off offset:1536
	s_nop 0
	global_load_dwordx4 v[32:35], v[34:35], off offset:16
	v_lshlrev_b32_e32 v208, 16, v216
	v_mul_f32_e32 v209, v139, v209
	v_fmac_f32_e32 v209, v138, v208
	v_lshlrev_b32_e32 v208, 16, v217
	v_fmac_f32_e32 v209, v140, v208
	v_and_b32_e32 v208, 0xffff0000, v217
	v_fmac_f32_e32 v209, v141, v208
	v_lshlrev_b32_e32 v208, 16, v218
	v_fmac_f32_e32 v209, v142, v208
	v_and_b32_e32 v208, 0xffff0000, v218
	v_fmac_f32_e32 v209, v143, v208
	v_lshlrev_b32_e32 v208, 16, v219
	v_fmac_f32_e32 v209, v144, v208
	v_and_b32_e32 v208, 0xffff0000, v219
	v_fmac_f32_e32 v209, v145, v208
	s_waitcnt vmcnt(4)
	v_and_b32_e32 v210, 0xffff0000, v220
	v_add_f32_e32 v208, v137, v209
	v_lshlrev_b32_e32 v209, 16, v220
	v_mul_f32_e32 v210, v147, v210
	v_fmac_f32_e32 v210, v146, v209
	v_lshlrev_b32_e32 v209, 16, v221
	v_fmac_f32_e32 v210, v148, v209
	v_and_b32_e32 v209, 0xffff0000, v221
	v_fmac_f32_e32 v210, v149, v209
	v_lshlrev_b32_e32 v209, 16, v222
	v_fmac_f32_e32 v210, v150, v209
	v_and_b32_e32 v209, 0xffff0000, v222
	v_fmac_f32_e32 v210, v151, v209
	v_lshlrev_b32_e32 v209, 16, v223
	v_fmac_f32_e32 v210, v152, v209
	v_and_b32_e32 v209, 0xffff0000, v223
	v_log_f32_e32 v77, v77
	v_fmac_f32_e32 v210, v153, v209
	v_add_f32_e32 v208, v208, v210
	v_mul_f32_e64 v209, |v208|, s71
	v_exp_f32_e32 v209, v209
	v_mul_f32_e32 v207, 0x3f317217, v77
	v_fma_f32 v207, v77, s73, -v207
	v_fmac_f32_e32 v207, 0x3377d1cf, v77
	v_fmac_f32_e32 v207, 0x3f317217, v77
	s_nop 0
	v_add_f32_e32 v209, 1.0, v209
	s_waitcnt vmcnt(2)
	v_and_b32_e32 v211, 0xffff0000, v228
	v_mov_b32_e32 v77, v207
	s_nop 0
	s_nop 0
	s_nop 0
	v_sub_f32_e32 v76, v76, v77
	s_nop 0
	s_nop 0
	v_and_b32_e32 v210, 0xffff0000, v224
	v_min_f32_e32 v77, 0, v208
	v_lshlrev_b32_e32 v208, 16, v224
	v_mul_f32_e32 v210, v139, v210
	v_fmac_f32_e32 v210, v138, v208
	v_lshlrev_b32_e32 v208, 16, v225
	v_fmac_f32_e32 v210, v140, v208
	v_and_b32_e32 v208, 0xffff0000, v225
	v_fmac_f32_e32 v210, v141, v208
	v_lshlrev_b32_e32 v208, 16, v226
	v_fmac_f32_e32 v210, v142, v208
	v_and_b32_e32 v208, 0xffff0000, v226
	v_fmac_f32_e32 v210, v143, v208
	v_lshlrev_b32_e32 v208, 16, v227
	v_fmac_f32_e32 v210, v144, v208
	v_and_b32_e32 v208, 0xffff0000, v227
	v_fmac_f32_e32 v210, v145, v208
	v_add_f32_e32 v208, v137, v210
	v_lshlrev_b32_e32 v210, 16, v228
	v_mul_f32_e32 v211, v147, v211
	v_fmac_f32_e32 v211, v146, v210
	v_lshlrev_b32_e32 v210, 16, v229
	v_fmac_f32_e32 v211, v148, v210
	v_and_b32_e32 v210, 0xffff0000, v229
	v_fmac_f32_e32 v211, v149, v210
	v_lshlrev_b32_e32 v210, 16, v230
	v_fmac_f32_e32 v211, v150, v210
	v_and_b32_e32 v210, 0xffff0000, v230
	v_fmac_f32_e32 v211, v151, v210
	v_lshlrev_b32_e32 v210, 16, v231
	v_fmac_f32_e32 v211, v152, v210
	v_and_b32_e32 v210, 0xffff0000, v231
	v_log_f32_e32 v209, v209
	v_fmac_f32_e32 v211, v153, v210
	v_add_f32_e32 v208, v208, v211
	v_mul_f32_e64 v210, |v208|, s71
	v_exp_f32_e32 v210, v210
	v_mul_f32_e32 v207, 0x3f317217, v209
	v_fma_f32 v207, v209, s73, -v207
	v_fmac_f32_e32 v207, 0x3377d1cf, v209
	v_fmac_f32_e32 v207, 0x3f317217, v209
	s_nop 0
	v_add_f32_e32 v210, 1.0, v210
	s_waitcnt vmcnt(1)
	v_lshlrev_b32_e32 v216, 16, v80
	s_nop 0
	s_nop 0
	s_nop 0
	v_mad_u64_u32 v[212:213], s[0:1], v72, s63, v[36:37]
	s_nop 0
	s_nop 0
	s_nop 0
	v_log_f32_e32 v214, v210
	s_nop 0
	v_mad_i32_i24 v213, v73, s63, v213
	v_add_co_u32_e64 v72, s[0:1], s55, v212
	v_sub_f32_e32 v77, v77, v207
	v_min_f32_e32 v207, 0, v208
	v_mul_f32_e32 v208, 0x3f317217, v214
	v_and_b32_e32 v80, 0xffff0000, v80
	v_addc_co_u32_e64 v73, s[0:1], 0, v213, s[0:1]
	v_fma_f32 v215, v214, s73, -v208
	v_mul_f32_e32 v80, v139, v80
	global_load_dwordx4 v[208:211], v[72:73], off offset:1536
	v_fmac_f32_e32 v80, v138, v216
	v_lshlrev_b32_e32 v72, 16, v81
	v_fmac_f32_e32 v80, v140, v72
	v_and_b32_e32 v72, 0xffff0000, v81
	v_fmac_f32_e32 v80, v141, v72
	v_lshlrev_b32_e32 v72, 16, v82
	v_fmac_f32_e32 v80, v142, v72
	v_and_b32_e32 v72, 0xffff0000, v82
	v_fmac_f32_e32 v80, v143, v72
	v_lshlrev_b32_e32 v72, 16, v83
	v_fmac_f32_e32 v80, v144, v72
	v_and_b32_e32 v72, 0xffff0000, v83
	v_fmac_f32_e32 v80, v145, v72
	v_lshl_add_u64 v[72:73], v[212:213], 0, s[50:51]
	v_add_f32_e32 v216, v137, v80
	global_load_dwordx4 v[80:83], v[72:73], off offset:16
	s_waitcnt vmcnt(2)
	v_lshlrev_b32_e32 v217, 16, v32
	v_and_b32_e32 v32, 0xffff0000, v32
	v_mul_f32_e32 v32, v147, v32
	v_fmac_f32_e32 v32, v146, v217
	v_lshlrev_b32_e32 v72, 16, v33
	v_fmac_f32_e32 v32, v148, v72
	v_and_b32_e32 v33, 0xffff0000, v33
	v_fmac_f32_e32 v32, v149, v33
	v_lshlrev_b32_e32 v33, 16, v34
	v_fmac_f32_e32 v32, v150, v33
	v_and_b32_e32 v33, 0xffff0000, v34
	v_fmac_f32_e32 v32, v151, v33
	v_lshlrev_b32_e32 v33, 16, v35
	v_fmac_f32_e32 v32, v152, v33
	v_and_b32_e32 v33, 0xffff0000, v35
	v_fmac_f32_e32 v32, v153, v33
	v_add_f32_e32 v72, v216, v32
	v_mul_f32_e64 v32, |v72|, s71
	v_exp_f32_e32 v32, v32
	v_fmac_f32_e32 v215, 0x3377d1cf, v214
	v_fmac_f32_e32 v215, 0x3f317217, v214
	s_nop 0
	v_add_f32_e32 v32, 1.0, v32
	s_nop 0
	v_mov_b32_e32 v33, v215
	s_nop 0
	v_mov_b32_e32 v73, v33
	s_nop 0
	s_nop 0
	s_nop 0
	v_log_f32_e32 v216, v32
	v_mad_u64_u32 v[32:33], s[0:1], v70, s63, v[36:37]
	v_mad_i32_i24 v33, v71, s63, v33
	v_add_co_u32_e64 v34, s[0:1], s55, v32
	s_nop 0
	s_nop 0
	v_addc_co_u32_e64 v35, s[0:1], 0, v33, s[0:1]
	global_load_dwordx4 v[212:215], v[34:35], off offset:1536
	v_mul_f32_e32 v35, 0x3f317217, v216
	v_fma_f32 v35, v216, s73, -v35
	v_fmac_f32_e32 v35, 0x3377d1cf, v216
	v_fmac_f32_e32 v35, 0x3f317217, v216
	s_nop 0
	v_lshl_add_u64 v[32:33], v[32:33], 0, s[50:51]
	v_min_f32_e32 v34, 0, v72
	s_nop 0
	global_load_dwordx4 v[216:219], v[32:33], off offset:16
	v_mad_u64_u32 v[32:33], s[0:1], v68, s63, v[36:37]
	s_nop 0
	v_mad_i32_i24 v33, v69, s63, v33
	v_sub_f32_e32 v71, v34, v35
	v_lshl_add_u64 v[34:35], v[32:33], 0, s[50:51]
	v_add_co_u32_e32 v32, vcc, s55, v32
	v_sub_f32_e32 v70, v207, v73
	s_nop 0
	v_addc_co_u32_e32 v33, vcc, 0, v33, vcc
	global_load_dwordx4 v[220:223], v[32:33], off offset:1536
	global_load_dwordx4 v[224:227], v[34:35], off offset:16
	v_mad_u64_u32 v[32:33], s[0:1], v74, s63, v[36:37]
	s_waitcnt vmcnt(5)
	v_and_b32_e32 v69, 0xffff0000, v208
	v_lshlrev_b32_e32 v68, 16, v208
	v_mul_f32_e32 v69, v139, v69
	v_fmac_f32_e32 v69, v138, v68
	v_lshlrev_b32_e32 v68, 16, v209
	v_fmac_f32_e32 v69, v140, v68
	v_and_b32_e32 v68, 0xffff0000, v209
	v_fmac_f32_e32 v69, v141, v68
	v_lshlrev_b32_e32 v68, 16, v210
	v_fmac_f32_e32 v69, v142, v68
	v_and_b32_e32 v68, 0xffff0000, v210
	v_fmac_f32_e32 v69, v143, v68
	v_lshlrev_b32_e32 v68, 16, v211
	v_fmac_f32_e32 v69, v144, v68
	v_and_b32_e32 v68, 0xffff0000, v211
	v_fmac_f32_e32 v69, v145, v68
	s_waitcnt vmcnt(4)
	v_and_b32_e32 v72, 0xffff0000, v80
	v_add_f32_e32 v68, v137, v69
	v_lshlrev_b32_e32 v69, 16, v80
	v_mul_f32_e32 v72, v147, v72
	v_fmac_f32_e32 v72, v146, v69
	v_lshlrev_b32_e32 v69, 16, v81
	v_fmac_f32_e32 v72, v148, v69
	v_and_b32_e32 v69, 0xffff0000, v81
	v_fmac_f32_e32 v72, v149, v69
	v_lshlrev_b32_e32 v69, 16, v82
	v_fmac_f32_e32 v72, v150, v69
	v_and_b32_e32 v69, 0xffff0000, v82
	v_fmac_f32_e32 v72, v151, v69
	v_lshlrev_b32_e32 v69, 16, v83
	v_fmac_f32_e32 v72, v152, v69
	v_and_b32_e32 v69, 0xffff0000, v83
	v_fmac_f32_e32 v72, v153, v69
	v_add_f32_e32 v68, v68, v72
	v_mul_f32_e64 v69, |v68|, s71
	v_exp_f32_e32 v69, v69
	v_mad_i32_i24 v33, v75, s63, v33
	v_lshl_add_u64 v[34:35], v[32:33], 0, s[50:51]
	v_add_co_u32_e32 v32, vcc, s55, v32
	v_add_f32_e32 v69, 1.0, v69
	s_nop 0
	v_addc_co_u32_e32 v33, vcc, 0, v33, vcc
	s_nop 0
	v_min_f32_e32 v68, 0, v68
	s_waitcnt vmcnt(3)
	v_and_b32_e32 v82, 0xffff0000, v212
	s_nop 0
	s_nop 0
	global_load_dwordx4 v[72:75], v[32:33], off offset:1536
	s_nop 0
	global_load_dwordx4 v[32:35], v[34:35], off offset:16
	v_lshlrev_b32_e32 v81, 16, v212
	v_mul_f32_e32 v82, v139, v82
	v_fmac_f32_e32 v82, v138, v81
	v_lshlrev_b32_e32 v81, 16, v213
	v_fmac_f32_e32 v82, v140, v81
	v_and_b32_e32 v81, 0xffff0000, v213
	v_fmac_f32_e32 v82, v141, v81
	v_lshlrev_b32_e32 v81, 16, v214
	v_fmac_f32_e32 v82, v142, v81
	v_and_b32_e32 v81, 0xffff0000, v214
	v_fmac_f32_e32 v82, v143, v81
	v_lshlrev_b32_e32 v81, 16, v215
	v_fmac_f32_e32 v82, v144, v81
	v_and_b32_e32 v81, 0xffff0000, v215
	v_fmac_f32_e32 v82, v145, v81
	s_waitcnt vmcnt(4)
	v_and_b32_e32 v83, 0xffff0000, v216
	v_add_f32_e32 v81, v137, v82
	v_lshlrev_b32_e32 v82, 16, v216
	v_mul_f32_e32 v83, v147, v83
	v_fmac_f32_e32 v83, v146, v82
	v_lshlrev_b32_e32 v82, 16, v217
	v_fmac_f32_e32 v83, v148, v82
	v_and_b32_e32 v82, 0xffff0000, v217
	v_fmac_f32_e32 v83, v149, v82
	v_lshlrev_b32_e32 v82, 16, v218
	v_fmac_f32_e32 v83, v150, v82
	v_and_b32_e32 v82, 0xffff0000, v218
	v_fmac_f32_e32 v83, v151, v82
	v_lshlrev_b32_e32 v82, 16, v219
	v_fmac_f32_e32 v83, v152, v82
	v_and_b32_e32 v82, 0xffff0000, v219
	v_log_f32_e32 v69, v69
	v_fmac_f32_e32 v83, v153, v82
	v_add_f32_e32 v81, v81, v83
	v_mul_f32_e64 v82, |v81|, s71
	v_exp_f32_e32 v82, v82
	v_mul_f32_e32 v80, 0x3f317217, v69
	v_fma_f32 v80, v69, s73, -v80
	v_fmac_f32_e32 v80, 0x3377d1cf, v69
	v_fmac_f32_e32 v80, 0x3f317217, v69
	s_nop 0
	v_add_f32_e32 v82, 1.0, v82
	s_waitcnt vmcnt(2)
	v_and_b32_e32 v207, 0xffff0000, v224
	v_mov_b32_e32 v69, v80
	s_nop 0
	s_nop 0
	s_nop 0
	v_sub_f32_e32 v68, v68, v69
	s_nop 0
	s_nop 0
	v_and_b32_e32 v83, 0xffff0000, v220
	v_min_f32_e32 v69, 0, v81
	v_lshlrev_b32_e32 v81, 16, v220
	v_mul_f32_e32 v83, v139, v83
	v_fmac_f32_e32 v83, v138, v81
	v_lshlrev_b32_e32 v81, 16, v221
	v_fmac_f32_e32 v83, v140, v81
	v_and_b32_e32 v81, 0xffff0000, v221
	v_fmac_f32_e32 v83, v141, v81
	v_lshlrev_b32_e32 v81, 16, v222
	v_fmac_f32_e32 v83, v142, v81
	v_and_b32_e32 v81, 0xffff0000, v222
	v_fmac_f32_e32 v83, v143, v81
	v_lshlrev_b32_e32 v81, 16, v223
	v_fmac_f32_e32 v83, v144, v81
	v_and_b32_e32 v81, 0xffff0000, v223
	v_fmac_f32_e32 v83, v145, v81
	v_add_f32_e32 v81, v137, v83
	v_lshlrev_b32_e32 v83, 16, v224
	v_mul_f32_e32 v207, v147, v207
	v_fmac_f32_e32 v207, v146, v83
	v_lshlrev_b32_e32 v83, 16, v225
	v_fmac_f32_e32 v207, v148, v83
	v_and_b32_e32 v83, 0xffff0000, v225
	v_fmac_f32_e32 v207, v149, v83
	v_lshlrev_b32_e32 v83, 16, v226
	v_fmac_f32_e32 v207, v150, v83
	v_and_b32_e32 v83, 0xffff0000, v226
	v_fmac_f32_e32 v207, v151, v83
	v_lshlrev_b32_e32 v83, 16, v227
	v_fmac_f32_e32 v207, v152, v83
	v_and_b32_e32 v83, 0xffff0000, v227
	v_log_f32_e32 v82, v82
	v_fmac_f32_e32 v207, v153, v83
	v_add_f32_e32 v81, v81, v207
	v_mul_f32_e64 v83, |v81|, s71
	v_exp_f32_e32 v83, v83
	v_mul_f32_e32 v80, 0x3f317217, v82
	v_fma_f32 v80, v82, s73, -v80
	v_fmac_f32_e32 v80, 0x3377d1cf, v82
	v_fmac_f32_e32 v80, 0x3f317217, v82
	s_nop 0
	v_add_f32_e32 v83, 1.0, v83
	v_min_f32_e32 v210, 0, v81
	s_nop 0
	s_nop 0
	s_nop 0
	v_mad_u64_u32 v[208:209], s[0:1], v66, s63, v[36:37]
	s_nop 0
	s_nop 0
	s_nop 0
	v_log_f32_e32 v207, v83
	s_nop 0
	v_mad_i32_i24 v209, v67, s63, v209
	v_add_co_u32_e64 v66, s[0:1], s55, v208
	v_sub_f32_e32 v69, v69, v80
	v_mul_f32_e32 v80, 0x3f317217, v207
	v_addc_co_u32_e64 v67, s[0:1], 0, v209, s[0:1]
	v_fma_f32 v211, v207, s73, -v80
	s_waitcnt vmcnt(1)
	v_lshlrev_b32_e32 v212, 16, v72
	v_and_b32_e32 v72, 0xffff0000, v72
	global_load_dwordx4 v[80:83], v[66:67], off offset:1536
	v_mul_f32_e32 v72, v139, v72
	v_fmac_f32_e32 v72, v138, v212
	v_lshlrev_b32_e32 v66, 16, v73
	v_fmac_f32_e32 v72, v140, v66
	v_and_b32_e32 v66, 0xffff0000, v73
	v_fmac_f32_e32 v72, v141, v66
	v_lshlrev_b32_e32 v66, 16, v74
	v_fmac_f32_e32 v72, v142, v66
	v_and_b32_e32 v66, 0xffff0000, v74
	v_fmac_f32_e32 v72, v143, v66
	v_lshlrev_b32_e32 v66, 16, v75
	v_fmac_f32_e32 v72, v144, v66
	v_and_b32_e32 v66, 0xffff0000, v75
	v_fmac_f32_e32 v72, v145, v66
	v_lshl_add_u64 v[66:67], v[208:209], 0, s[50:51]
	v_add_f32_e32 v212, v137, v72
	global_load_dwordx4 v[72:75], v[66:67], off offset:16
	s_waitcnt vmcnt(2)
	v_lshlrev_b32_e32 v213, 16, v32
	v_and_b32_e32 v32, 0xffff0000, v32
	v_mul_f32_e32 v32, v147, v32
	v_fmac_f32_e32 v32, v146, v213
	v_lshlrev_b32_e32 v66, 16, v33
	v_fmac_f32_e32 v32, v148, v66
	v_and_b32_e32 v33, 0xffff0000, v33
	v_fmac_f32_e32 v32, v149, v33
	v_lshlrev_b32_e32 v33, 16, v34
	v_fmac_f32_e32 v32, v150, v33
	v_and_b32_e32 v33, 0xffff0000, v34
	v_fmac_f32_e32 v32, v151, v33
	v_lshlrev_b32_e32 v33, 16, v35
	v_fmac_f32_e32 v32, v152, v33
	v_and_b32_e32 v33, 0xffff0000, v35
	v_fmac_f32_e32 v32, v153, v33
	v_add_f32_e32 v208, v212, v32
	v_mul_f32_e64 v32, |v208|, s71
	v_exp_f32_e32 v32, v32
	v_fmac_f32_e32 v211, 0x3377d1cf, v207
	v_fmac_f32_e32 v211, 0x3f317217, v207
	s_nop 0
	v_add_f32_e32 v32, 1.0, v32
	s_nop 0
	v_mov_b32_e32 v33, v211
	s_nop 0
	v_mov_b32_e32 v207, v33
	v_mad_u64_u32 v[66:67], s[0:1], v64, s63, v[36:37]
	s_nop 0
	s_nop 0
	v_log_f32_e32 v209, v32
	v_mad_i32_i24 v67, v65, s63, v67
	v_add_co_u32_e64 v32, s[0:1], s55, v66
	v_mul_f32_e32 v65, 0x3f317217, v209
	s_nop 0
	v_addc_co_u32_e64 v33, s[0:1], 0, v67, s[0:1]
	global_load_dwordx4 v[32:35], v[32:33], off offset:1536
	v_fma_f32 v65, v209, s73, -v65
	v_fmac_f32_e32 v65, 0x3377d1cf, v209
	v_fmac_f32_e32 v65, 0x3f317217, v209
	s_nop 0
	v_min_f32_e32 v64, 0, v208
	s_nop 0
	s_nop 0
	s_nop 0
	v_sub_f32_e32 v216, v64, v65
	v_lshl_add_u64 v[64:65], v[66:67], 0, s[50:51]
	global_load_dwordx4 v[64:67], v[64:65], off offset:16
	v_mad_u64_u32 v[208:209], s[0:1], v62, s63, v[36:37]
	v_mad_u64_u32 v[36:37], s[0:1], v38, s63, v[36:37]
	v_mad_i32_i24 v37, v39, s63, v37
	v_mad_i32_i24 v209, v63, s63, v209
	v_lshl_add_u64 v[62:63], v[208:209], 0, s[50:51]
	v_add_co_u32_e32 v208, vcc, s55, v208
	v_sub_f32_e32 v207, v210, v207
	s_nop 0
	v_addc_co_u32_e32 v209, vcc, 0, v209, vcc
	s_waitcnt vmcnt(3)
	v_and_b32_e32 v39, 0xffff0000, v80
	v_lshlrev_b32_e32 v38, 16, v80
	v_mul_f32_e32 v39, v139, v39
	v_fmac_f32_e32 v39, v138, v38
	v_lshlrev_b32_e32 v38, 16, v81
	v_fmac_f32_e32 v39, v140, v38
	v_and_b32_e32 v38, 0xffff0000, v81
	v_fmac_f32_e32 v39, v141, v38
	v_lshlrev_b32_e32 v38, 16, v82
	v_fmac_f32_e32 v39, v142, v38
	v_and_b32_e32 v38, 0xffff0000, v82
	v_fmac_f32_e32 v39, v143, v38
	v_lshlrev_b32_e32 v38, 16, v83
	v_fmac_f32_e32 v39, v144, v38
	v_and_b32_e32 v38, 0xffff0000, v83
	v_fmac_f32_e32 v39, v145, v38
	v_add_f32_e32 v38, v137, v39
	s_waitcnt vmcnt(2)
	v_lshlrev_b32_e32 v39, 16, v72
	v_and_b32_e32 v72, 0xffff0000, v72
	global_load_dwordx4 v[208:211], v[208:209], off offset:1536
	s_nop 0
	global_load_dwordx4 v[212:215], v[62:63], off offset:16
	v_mul_f32_e32 v72, v147, v72
	v_fmac_f32_e32 v72, v146, v39
	v_lshlrev_b32_e32 v39, 16, v73
	v_fmac_f32_e32 v72, v148, v39
	v_and_b32_e32 v39, 0xffff0000, v73
	v_fmac_f32_e32 v72, v149, v39
	v_lshlrev_b32_e32 v39, 16, v74
	v_fmac_f32_e32 v72, v150, v39
	v_and_b32_e32 v39, 0xffff0000, v74
	v_fmac_f32_e32 v72, v151, v39
	v_lshlrev_b32_e32 v39, 16, v75
	v_fmac_f32_e32 v72, v152, v39
	v_and_b32_e32 v39, 0xffff0000, v75
	v_fmac_f32_e32 v72, v153, v39
	v_add_f32_e32 v80, v38, v72
	v_mul_f32_e64 v38, |v80|, s71
	v_exp_f32_e32 v38, v38
	v_lshl_add_u64 v[62:63], v[36:37], 0, s[50:51]
	v_add_co_u32_e32 v36, vcc, s55, v36
	v_add_f32_e32 v38, 1.0, v38
	s_nop 0
	v_addc_co_u32_e32 v37, vcc, 0, v37, vcc
	s_nop 0
	s_nop 1
	s_nop 0
	s_nop 0
	v_log_f32_e32 v81, v38
	global_load_dwordx4 v[36:39], v[36:37], off offset:1536
	s_nop 0
	global_load_dwordx4 v[72:75], v[62:63], off offset:16
	v_min_f32_e32 v62, 0, v80
	v_mul_f32_e32 v63, 0x3f317217, v81
	v_fma_f32 v63, v81, s73, -v63
	v_fmac_f32_e32 v63, 0x3377d1cf, v81
	v_fmac_f32_e32 v63, 0x3f317217, v81
	s_waitcnt vmcnt(5)
	v_lshlrev_b32_e32 v80, 16, v32
	v_and_b32_e32 v32, 0xffff0000, v32
	v_mul_f32_e32 v32, v139, v32
	v_fmac_f32_e32 v32, v138, v80
	v_lshlrev_b32_e32 v80, 16, v33
	v_fmac_f32_e32 v32, v140, v80
	v_and_b32_e32 v33, 0xffff0000, v33
	v_fmac_f32_e32 v32, v141, v33
	v_lshlrev_b32_e32 v33, 16, v34
	v_fmac_f32_e32 v32, v142, v33
	v_and_b32_e32 v33, 0xffff0000, v34
	v_fmac_f32_e32 v32, v143, v33
	v_lshlrev_b32_e32 v33, 16, v35
	v_fmac_f32_e32 v32, v144, v33
	v_and_b32_e32 v33, 0xffff0000, v35
	s_waitcnt vmcnt(4)
	v_and_b32_e32 v34, 0xffff0000, v64
	v_fmac_f32_e32 v32, v145, v33
	v_lshlrev_b32_e32 v33, 16, v64
	v_mul_f32_e32 v34, v147, v34
	v_fmac_f32_e32 v34, v146, v33
	v_lshlrev_b32_e32 v33, 16, v65
	v_fmac_f32_e32 v34, v148, v33
	v_and_b32_e32 v33, 0xffff0000, v65
	v_fmac_f32_e32 v34, v149, v33
	v_lshlrev_b32_e32 v33, 16, v66
	v_fmac_f32_e32 v34, v150, v33
	v_and_b32_e32 v33, 0xffff0000, v66
	v_fmac_f32_e32 v34, v151, v33
	v_lshlrev_b32_e32 v33, 16, v67
	v_fmac_f32_e32 v34, v152, v33
	v_and_b32_e32 v33, 0xffff0000, v67
	v_add_f32_e32 v32, v137, v32
	v_fmac_f32_e32 v34, v153, v33
	v_add_f32_e32 v32, v32, v34
	v_mul_f32_e64 v33, |v32|, s71
	v_exp_f32_e32 v33, v33
	s_nop 0
	s_nop 0
	v_min_f32_e32 v32, 0, v32
	v_add_f32_e32 v33, 1.0, v33
	s_nop 0
	v_mov_b32_e32 v34, v63
	s_nop 0
	s_nop 0
	s_nop 0
	s_waitcnt vmcnt(3)
	v_and_b32_e32 v63, 0xffff0000, v208
	v_sub_f32_e32 v34, v62, v34
	v_lshlrev_b32_e32 v62, 16, v208
	v_mul_f32_e32 v63, v139, v63
	v_fmac_f32_e32 v63, v138, v62
	v_lshlrev_b32_e32 v62, 16, v209
	v_fmac_f32_e32 v63, v140, v62
	v_and_b32_e32 v62, 0xffff0000, v209
	v_fmac_f32_e32 v63, v141, v62
	v_lshlrev_b32_e32 v62, 16, v210
	v_fmac_f32_e32 v63, v142, v62
	v_and_b32_e32 v62, 0xffff0000, v210
	v_fmac_f32_e32 v63, v143, v62
	v_lshlrev_b32_e32 v62, 16, v211
	v_fmac_f32_e32 v63, v144, v62
	v_and_b32_e32 v62, 0xffff0000, v211
	v_log_f32_e32 v33, v33
	v_fmac_f32_e32 v63, v145, v62
	s_waitcnt vmcnt(2)
	v_and_b32_e32 v64, 0xffff0000, v212
	v_add_f32_e32 v62, v137, v63
	v_lshlrev_b32_e32 v63, 16, v212
	v_mul_f32_e32 v64, v147, v64
	v_fmac_f32_e32 v64, v146, v63
	v_lshlrev_b32_e32 v63, 16, v213
	v_fmac_f32_e32 v64, v148, v63
	v_and_b32_e32 v63, 0xffff0000, v213
	v_mul_f32_e32 v35, 0x3f317217, v33
	v_fmac_f32_e32 v64, v149, v63
	v_lshlrev_b32_e32 v63, 16, v214
	v_fma_f32 v35, v33, s73, -v35
	v_fmac_f32_e32 v64, v150, v63
	v_and_b32_e32 v63, 0xffff0000, v214
	v_fmac_f32_e32 v35, 0x3377d1cf, v33
	v_fmac_f32_e32 v64, v151, v63
	v_lshlrev_b32_e32 v63, 16, v215
	v_fmac_f32_e32 v35, 0x3f317217, v33
	v_fmac_f32_e32 v64, v152, v63
	v_and_b32_e32 v63, 0xffff0000, v215
	s_nop 0
	v_fmac_f32_e32 v64, v153, v63
	v_add_f32_e32 v62, v62, v64
	v_mov_b32_e32 v33, v35
	s_nop 0
	s_nop 0
	v_mul_f32_e64 v63, |v62|, s71
	v_sub_f32_e32 v32, v32, v33
	v_min_f32_e32 v33, 0, v62
	s_waitcnt vmcnt(1)
	v_lshlrev_b32_e32 v62, 16, v36
	v_and_b32_e32 v36, 0xffff0000, v36
	v_mul_f32_e32 v36, v139, v36
	v_fmac_f32_e32 v36, v138, v62
	v_lshlrev_b32_e32 v62, 16, v37
	v_fmac_f32_e32 v36, v140, v62
	v_and_b32_e32 v37, 0xffff0000, v37
	v_fmac_f32_e32 v36, v141, v37
	v_lshlrev_b32_e32 v37, 16, v38
	v_fmac_f32_e32 v36, v142, v37
	v_and_b32_e32 v37, 0xffff0000, v38
	v_fmac_f32_e32 v36, v143, v37
	v_lshlrev_b32_e32 v37, 16, v39
	v_fmac_f32_e32 v36, v144, v37
	v_and_b32_e32 v37, 0xffff0000, v39
	s_waitcnt vmcnt(0)
	v_and_b32_e32 v38, 0xffff0000, v72
	v_fmac_f32_e32 v36, v145, v37
	v_lshlrev_b32_e32 v37, 16, v72
	v_mul_f32_e32 v38, v147, v38
	v_fmac_f32_e32 v38, v146, v37
	v_lshlrev_b32_e32 v37, 16, v73
	v_fmac_f32_e32 v38, v148, v37
	v_and_b32_e32 v37, 0xffff0000, v73
	v_fmac_f32_e32 v38, v149, v37
	v_lshlrev_b32_e32 v37, 16, v74
	v_exp_f32_e32 v63, v63
	v_fmac_f32_e32 v38, v150, v37
	v_and_b32_e32 v37, 0xffff0000, v74
	v_fmac_f32_e32 v38, v151, v37
	v_lshlrev_b32_e32 v37, 16, v75
	v_fmac_f32_e32 v38, v152, v37
	v_and_b32_e32 v37, 0xffff0000, v75
	v_add_f32_e32 v36, v137, v36
	v_fmac_f32_e32 v38, v153, v37
	v_add_f32_e32 v63, 1.0, v63
	v_add_f32_e32 v36, v36, v38
	s_nop 0
	v_mul_f32_e64 v37, |v36|, s71
	v_exp_f32_e32 v37, v37
	s_nop 0
	s_nop 0
	v_log_f32_e32 v63, v63
	v_add_f32_e32 v37, 1.0, v37
	s_nop 0
	s_nop 0
	v_mul_f32_e32 v35, 0x3f317217, v63
	v_fma_f32 v35, v63, s73, -v35
	s_nop 0
	s_nop 0
	v_fmac_f32_e32 v35, 0x3377d1cf, v63
	v_log_f32_e32 v37, v37
	v_fmac_f32_e32 v35, 0x3f317217, v63
	s_nop 0
	s_nop 1
	s_nop 0
	s_nop 0
	v_sub_f32_e32 v33, v33, v35
	v_min_f32_e32 v35, 0, v36
	v_mul_f32_e32 v36, 0x3f317217, v37
	v_fma_f32 v36, v37, s73, -v36
	v_fmac_f32_e32 v36, 0x3377d1cf, v37
	v_fmac_f32_e32 v36, 0x3f317217, v37
	s_nop 0
	v_fmamk_f32 v38, v85, 0x3d800000, v84
	s_nop 0
	s_nop 0
	s_nop 0
	s_nop 0
	v_fmamk_f32 v37, v78, 0x3d800000, v38
	v_sub_f32_e32 v35, v35, v36
	v_fmamk_f32 v36, v79, 0x3d800000, v37
	v_fmamk_f32 v74, v76, 0x3d800000, v36
	v_fmamk_f32 v73, v77, 0x3d800000, v74
	v_fmamk_f32 v72, v70, 0x3d800000, v73
	v_fmamk_f32 v71, v71, 0x3d800000, v72
	v_fmamk_f32 v70, v68, 0x3d800000, v71
	v_fmamk_f32 v69, v69, 0x3d800000, v70
	v_fmamk_f32 v68, v207, 0x3d800000, v69
	v_fmamk_f32 v67, v216, 0x3d800000, v68
	v_fmamk_f32 v66, v34, 0x3d800000, v67
	v_fmamk_f32 v65, v32, 0x3d800000, v66
	v_fmamk_f32 v64, v33, 0x3d800000, v65
	v_fmamk_f32 v63, v35, 0x3d800000, v64
	ds_write_b32 v47, v63
	s_waitcnt lgkmcnt(0)
	s_barrier
	ds_read2st64_b32 v[34:35], v55 offset1:2
	ds_read2st64_b32 v[32:33], v55 offset0:4 offset1:6
	s_waitcnt lgkmcnt(1)
	v_add_f32_e32 v34, 0, v34
	v_add_f32_e32 v39, v34, v35
	s_waitcnt lgkmcnt(0)
	v_add_f32_e32 v39, v39, v32
	v_add_f32_e32 v62, v39, v33
	s_and_saveexec_b64 s[0:1], s[8:9]
	s_cbranch_execz .LBB0_2794
	v_mul_f32_e32 v39, 0x3fb8aa3b, v62
	v_exp_f32_e32 v39, v39
	ds_write_b32 v89, v39
